# static s_setprio 1 for waves 4-7 for the whole kernel, all per-phase GEMM s_setprio flips deleted
# speedup vs baseline: 1.0106x; 1.0057x over previous
; #define LAS __attribute__((address_space(3)))
; __global__ void __launch_bounds__(NWAVES * 64, 2) mk_fwd(Args args) {
;     extern __shared__ __attribute__((aligned(16))) unsigned char lds[];
;     LAS unsigned char* L = (LAS unsigned char*)lds;
;     const int tid = threadIdx.x, lane = tid & 63, wave = __builtin_amdgcn_readfirstlane(tid >> 6);
;     const int G = gridDim.x, bx = blockIdx.x;
;     const int vcu = (G % 8 == 0) ? (bx % 8) * (G / 8) + bx / 8 : bx;
;     const int gw = vcu * NWAVES + wave, NGW = G * NWAVES;
;     unsigned char* ws = args.ws;
_Z6mk_fwd4Args:
	s_load_dwordx2 s[34:35], s[0:1], 0xb0
	s_load_dwordx4 s[28:31], s[0:1], 0xa0
	s_load_dwordx8 s[4:11], s[0:1], 0x80
	s_load_dword s67, s[0:1], 0xc8
	s_add_u32 s86, s0, 0xc8
	v_and_b32_e32 v1, 0x3ff, v0
	s_addc_u32 s87, s1, 0
	s_waitcnt lgkmcnt(0)
	v_writelane_b32 v250, s4, 0
	s_and_b32 s3, s67, 7
	v_readfirstlane_b32 s20, v1
	s_nop 3
	s_cmpk_ge_u32 s20, 0x100
	s_cbranch_scc0 .Lk_prio_skip
	s_setprio 1
.Lk_prio_skip:
	v_writelane_b32 v250, s5, 1
	v_writelane_b32 v250, s6, 2
	v_writelane_b32 v250, s7, 3
	v_writelane_b32 v250, s8, 4
	v_writelane_b32 v250, s9, 5
	v_writelane_b32 v250, s10, 6
	s_cmp_lg_u32 s3, 0
	s_mov_b32 s3, s2
	v_writelane_b32 v250, s11, 7
	s_cbranch_scc0 .LBB0_114
	s_load_dwordx4 s[60:63], s[0:1], 0xb8
	v_cmp_gt_u32_e32 vcc, 2, v1
	s_and_saveexec_b64 s[4:5], vcc

; #define PG8_STAGE(bufoff, gbase, voff) do { _Pragma("unroll") for (int _i = 0; _i < 2; ++_i) \
;         __builtin_amdgcn_global_load_lds((const unsigned*)((const char*)(gbase) + (voff)[_i]), (PG8_LAS unsigned*)(lds + (bufoff) + ldsw + _i * 8192), 16, 0, 0); } while (0)
; #define PG8_LDA(dst, b, h) do { _Pragma("unroll") for (int m = 0; m < 4; ++m) _Pragma("unroll") for (int k = 0; k < 2; ++k) dst[m][k] = *(const PG8_LAS bf16x8*)(lds + PG8_SA(b, h) + aoff + m * 2048 + k * 1024); } while (0)
; #define PG8_LDB(dst, b, h) do { _Pragma("unroll") for (int n = 0; n < 2; ++n) _Pragma("unroll") for (int k = 0; k < 2; ++k) dst[n][k] = *(const PG8_LAS bf16x8*)(lds + PG8_SB(b, h) + boff + n * 2048 + k * 1024); } while (0)
; #define PG8_MMA(ai, bj, At, Bt) do { __builtin_amdgcn_s_setprio(1); _Pragma("unroll") for (int m = 0; m < 4; ++m) _Pragma("unroll") for (int n = 0; n < 2; ++n) _Pragma("unroll") for (int k = 0; k < 2; ++k) \
;         acc[ai][bj][m][n] = __builtin_amdgcn_mfma_f32_16x16x32_bf16(Bt[n][k], At[m][k], acc[ai][bj][m][n], 0, 0, 0); __builtin_amdgcn_s_setprio(0); } while (0)
; #define PG8_BAR __builtin_amdgcn_s_barrier()
; template <class Epi, class Sched, bool ALIGN_EPI = false, bool SP2 = false, bool MID = false>
; __device__ __forceinline__ void gemm_phase(PG8_LAS unsigned char* lds, const Gemm g, const Sched& S, const Epi& E) {
;     ...
;             PG8_LDB(B0, 0, 0); PG8_LDB(B1, 0, 1); PG8_SCHED; PG8_LDA(At, 0, 0); PG8_STAGE(PG8_SA(1, 1), a1 + hstep, voffA);
;             PG8_WAIT_V(8); PG8_WAIT_L(0); PG8_BAR; PG8_MMA(0, 0, At, B0); PG8_MMA(0, 1, At, B1); PG8_BAR; PG8_SCHED;
;             PG8_LDA(At, 0, 1); PG8_STAGE(PG8_SB(0, 0), b2, voffB); PG8_STAGE(PG8_SB(0, 1), b2 + hstep, voffB); PG8_STAGE(PG8_SA(0, 0), a2, voffA);
;             PG8_WAIT_V(8); PG8_WAIT_L(0); PG8_BAR; PG8_MMA(1, 0, At, B0); PG8_MMA(1, 1, At, B1); PG8_BAR; PG8_SCHED;
;             PG8_LDB(B0, 1, 0); PG8_LDB(B1, 1, 1); PG8_SCHED; PG8_LDA(At, 1, 0); PG8_STAGE(PG8_SA(0, 1), a2 + hstep, voffA);
;             PG8_WAIT_V(8); PG8_WAIT_L(0); PG8_BAR; PG8_MMA(0, 0, At, B0); PG8_MMA(0, 1, At, B1); PG8_BAR; PG8_SCHED;
;             PG8_LDA(At, 1, 1); PG8_STAGE(PG8_SB(1, 0), b3, voffB); PG8_STAGE(PG8_SB(1, 1), b3 + hstep, voffB); PG8_STAGE(PG8_SA(1, 0), a3, voffA);
;             PG8_WAIT_V(8); PG8_WAIT_L(0); PG8_BAR; PG8_MMA(1, 0, At, B0); PG8_MMA(1, 1, At, B1); PG8_BAR; PG8_SCHED;
.LBB0_206:
	ds_read_b128 v[130:133], v176
	ds_read_b128 v[134:137], v176 offset:1024
	ds_read_b128 v[138:141], v176 offset:2048
	ds_read_b128 v[164:167], v176 offset:3072
	ds_read_b128 v[168:171], v177
	ds_read_b128 v[180:183], v177 offset:1024
	ds_read_b128 v[184:187], v177 offset:2048
	ds_read_b128 v[188:191], v177 offset:3072
	s_add_u32 s52, s4, 0xfff80080
	s_addc_u32 s53, s5, -1
	s_cmp_eq_u32 s51, 28
	s_cselect_b32 s75, s14, s53
	s_cselect_b32 s74, s15, s52
	s_cselect_b32 s73, s24, s27
	s_cselect_b32 s72, s25, s26
	v_lshl_add_u64 v[142:143], s[4:5], 0, v[156:157]
	s_add_i32 m0, s71, 0xc000
	ds_read_b128 v[192:195], v178
	ds_read_b128 v[200:203], v178 offset:1024
	ds_read_b128 v[204:207], v178 offset:2048
	ds_read_b128 v[208:211], v178 offset:3072
	ds_read_b128 v[212:215], v178 offset:4096
	ds_read_b128 v[216:219], v178 offset:5120
	ds_read_b128 v[220:223], v178 offset:6144
	ds_read_b128 v[224:227], v178 offset:7168
	global_load_lds_dwordx4 v[142:143], off
	v_lshl_add_u64 v[142:143], s[4:5], 0, v[158:159]
	s_add_i32 m0, s71, 0xe000
	s_nop 0
	global_load_lds_dwordx4 v[142:143], off
	s_waitcnt vmcnt(8)
	s_waitcnt lgkmcnt(0)
	s_barrier
	s_waitcnt lgkmcnt(0)
	v_mfma_f32_16x16x32_bf16 v[126:129], v[130:133], v[192:195], v[126:129]
	v_mfma_f32_16x16x32_bf16 v[122:125], v[138:141], v[192:195], v[122:125]
	v_mfma_f32_16x16x32_bf16 v[110:113], v[130:133], v[204:207], v[110:113]
	v_mfma_f32_16x16x32_bf16 v[106:109], v[138:141], v[204:207], v[106:109]
	v_mfma_f32_16x16x32_bf16 v[94:97], v[130:133], v[212:215], v[94:97]
	v_mfma_f32_16x16x32_bf16 v[90:93], v[138:141], v[212:215], v[90:93]
	v_mfma_f32_16x16x32_bf16 v[78:81], v[130:133], v[220:223], v[78:81]
	v_mfma_f32_16x16x32_bf16 v[74:77], v[138:141], v[220:223], v[74:77]
	v_mfma_f32_16x16x32_bf16 v[126:129], v[134:137], v[200:203], v[126:129]
	v_mfma_f32_16x16x32_bf16 v[122:125], v[164:167], v[200:203], v[122:125]
	v_mfma_f32_16x16x32_bf16 v[110:113], v[134:137], v[208:211], v[110:113]
	v_mfma_f32_16x16x32_bf16 v[106:109], v[164:167], v[208:211], v[106:109]
	v_mfma_f32_16x16x32_bf16 v[94:97], v[134:137], v[216:219], v[94:97]
	v_mfma_f32_16x16x32_bf16 v[90:93], v[164:167], v[216:219], v[90:93]
	v_mfma_f32_16x16x32_bf16 v[78:81], v[134:137], v[224:227], v[78:81]
	v_mfma_f32_16x16x32_bf16 v[74:77], v[164:167], v[224:227], v[74:77]
	v_mfma_f32_16x16x32_bf16 v[118:121], v[168:171], v[192:195], v[118:121]
	v_mfma_f32_16x16x32_bf16 v[114:117], v[184:187], v[192:195], v[114:117]
	v_mfma_f32_16x16x32_bf16 v[102:105], v[168:171], v[204:207], v[102:105]
	v_mfma_f32_16x16x32_bf16 v[98:101], v[184:187], v[204:207], v[98:101]
	v_mfma_f32_16x16x32_bf16 v[86:89], v[168:171], v[212:215], v[86:89]
	v_mfma_f32_16x16x32_bf16 v[82:85], v[184:187], v[212:215], v[82:85]
	v_mfma_f32_16x16x32_bf16 v[70:73], v[168:171], v[220:223], v[70:73]
	v_mfma_f32_16x16x32_bf16 v[66:69], v[184:187], v[220:223], v[66:69]
	v_mfma_f32_16x16x32_bf16 v[118:121], v[180:183], v[200:203], v[118:121]
	v_mfma_f32_16x16x32_bf16 v[114:117], v[188:191], v[200:203], v[114:117]
	v_mfma_f32_16x16x32_bf16 v[102:105], v[180:183], v[208:211], v[102:105]
	v_mfma_f32_16x16x32_bf16 v[98:101], v[188:191], v[208:211], v[98:101]
	v_mfma_f32_16x16x32_bf16 v[86:89], v[180:183], v[216:219], v[86:89]
	v_mfma_f32_16x16x32_bf16 v[82:85], v[188:191], v[216:219], v[82:85]
	v_mfma_f32_16x16x32_bf16 v[70:73], v[180:183], v[224:227], v[70:73]
	v_mfma_f32_16x16x32_bf16 v[66:69], v[188:191], v[224:227], v[66:69]
	s_barrier
	s_add_i32 s52, s62, s87
	v_lshl_add_u64 v[142:143], s[72:73], 0, v[144:145]
	s_mov_b32 m0, s52
	ds_read_b128 v[192:195], v178 offset:16384
	ds_read_b128 v[200:203], v178 offset:17408
	ds_read_b128 v[204:207], v178 offset:18432
	ds_read_b128 v[208:211], v178 offset:19456
	ds_read_b128 v[212:215], v178 offset:20480
	ds_read_b128 v[216:219], v178 offset:21504
	ds_read_b128 v[220:223], v178 offset:22528
	ds_read_b128 v[224:227], v178 offset:23552
	global_load_lds_dwordx4 v[142:143], off
	s_add_i32 m0, s52, 0x2000
	s_add_u32 s52, s72, 0x80000
	v_lshl_add_u64 v[172:173], s[72:73], 0, v[146:147]
	s_addc_u32 s53, s73, 0
	s_add_i32 s55, s12, s87
	global_load_lds_dwordx4 v[172:173], off
	v_lshl_add_u64 v[196:197], s[52:53], 0, v[144:145]
	s_mov_b32 m0, s55
	v_lshl_add_u64 v[228:229], s[74:75], 0, v[146:147]
	global_load_lds_dwordx4 v[196:197], off
	v_lshl_add_u64 v[196:197], s[52:53], 0, v[146:147]
	s_add_i32 m0, s55, 0x2000
	s_nop 0
	global_load_lds_dwordx4 v[196:197], off
	v_lshl_add_u64 v[196:197], s[74:75], 0, v[144:145]
	s_mov_b32 m0, s71
	s_nop 0
	global_load_lds_dwordx4 v[196:197], off
	s_mov_b32 m0, s88
	s_nop 0
	global_load_lds_dwordx4 v[228:229], off
	s_waitcnt vmcnt(8)
	s_waitcnt lgkmcnt(0)
	s_barrier
; #define PG8_STAGE(bufoff, gbase, voff) do { _Pragma("unroll") for (int _i = 0; _i < 2; ++_i) \
;         __builtin_amdgcn_global_load_lds((const unsigned*)((const char*)(gbase) + (voff)[_i]), (PG8_LAS unsigned*)(lds + (bufoff) + ldsw + _i * 8192), 16, 0, 0); } while (0)
; #define PG8_LDA(dst, b, h) do { _Pragma("unroll") for (int m = 0; m < 4; ++m) _Pragma("unroll") for (int k = 0; k < 2; ++k) dst[m][k] = *(const PG8_LAS bf16x8*)(lds + PG8_SA(b, h) + aoff + m * 2048 + k * 1024); } while (0)
; #define PG8_LDB(dst, b, h) do { _Pragma("unroll") for (int n = 0; n < 2; ++n) _Pragma("unroll") for (int k = 0; k < 2; ++k) dst[n][k] = *(const PG8_LAS bf16x8*)(lds + PG8_SB(b, h) + boff + n * 2048 + k * 1024); } while (0)
; #define PG8_MMA(ai, bj, At, Bt) do { __builtin_amdgcn_s_setprio(1); _Pragma("unroll") for (int m = 0; m < 4; ++m) _Pragma("unroll") for (int n = 0; n < 2; ++n) _Pragma("unroll") for (int k = 0; k < 2; ++k) \
;         acc[ai][bj][m][n] = __builtin_amdgcn_mfma_f32_16x16x32_bf16(Bt[n][k], At[m][k], acc[ai][bj][m][n], 0, 0, 0); __builtin_amdgcn_s_setprio(0); } while (0)
; #define PG8_BAR __builtin_amdgcn_s_barrier()
; template <class Epi, class Sched, bool ALIGN_EPI = false, bool SP2 = false, bool MID = false>
; __device__ __forceinline__ void gemm_phase(PG8_LAS unsigned char* lds, const Gemm g, const Sched& S, const Epi& E) {
;     ...
;             PG8_LDB(B0, 0, 0); PG8_LDB(B1, 0, 1); PG8_SCHED; PG8_LDA(At, 0, 0); PG8_STAGE(PG8_SA(1, 1), a1 + hstep, voffA);
;             PG8_WAIT_V(8); PG8_WAIT_L(0); PG8_BAR; PG8_MMA(0, 0, At, B0); PG8_MMA(0, 1, At, B1); PG8_BAR; PG8_SCHED;
;             PG8_LDA(At, 0, 1); PG8_STAGE(PG8_SB(0, 0), b2, voffB); PG8_STAGE(PG8_SB(0, 1), b2 + hstep, voffB); PG8_STAGE(PG8_SA(0, 0), a2, voffA);
;             PG8_WAIT_V(8); PG8_WAIT_L(0); PG8_BAR; PG8_MMA(1, 0, At, B0); PG8_MMA(1, 1, At, B1); PG8_BAR; PG8_SCHED;
;             PG8_LDB(B0, 1, 0); PG8_LDB(B1, 1, 1); PG8_SCHED; PG8_LDA(At, 1, 0); PG8_STAGE(PG8_SA(0, 1), a2 + hstep, voffA);
;             PG8_WAIT_V(8); PG8_WAIT_L(0); PG8_BAR; PG8_MMA(0, 0, At, B0); PG8_MMA(0, 1, At, B1); PG8_BAR; PG8_SCHED;
;             PG8_LDA(At, 1, 1); PG8_STAGE(PG8_SB(1, 0), b3, voffB); PG8_STAGE(PG8_SB(1, 1), b3 + hstep, voffB); PG8_STAGE(PG8_SA(1, 0), a3, voffA);
;             PG8_WAIT_V(8); PG8_WAIT_L(0); PG8_BAR; PG8_MMA(1, 0, At, B0); PG8_MMA(1, 1, At, B1); PG8_BAR; PG8_SCHED;
	s_waitcnt lgkmcnt(0)
	v_mfma_f32_16x16x32_bf16 v[62:65], v[130:133], v[192:195], v[62:65]
	v_mfma_f32_16x16x32_bf16 v[58:61], v[138:141], v[192:195], v[58:61]
	v_mfma_f32_16x16x32_bf16 v[46:49], v[130:133], v[204:207], v[46:49]
	v_mfma_f32_16x16x32_bf16 v[42:45], v[138:141], v[204:207], v[42:45]
	v_mfma_f32_16x16x32_bf16 v[30:33], v[130:133], v[212:215], v[30:33]
	v_mfma_f32_16x16x32_bf16 v[26:29], v[138:141], v[212:215], v[26:29]
	v_mfma_f32_16x16x32_bf16 v[14:17], v[130:133], v[220:223], v[14:17]
	v_mfma_f32_16x16x32_bf16 v[10:13], v[138:141], v[220:223], v[10:13]
	v_mfma_f32_16x16x32_bf16 v[62:65], v[134:137], v[200:203], v[62:65]
	v_mfma_f32_16x16x32_bf16 v[58:61], v[164:167], v[200:203], v[58:61]
	v_mfma_f32_16x16x32_bf16 v[46:49], v[134:137], v[208:211], v[46:49]
	v_mfma_f32_16x16x32_bf16 v[42:45], v[164:167], v[208:211], v[42:45]
	v_mfma_f32_16x16x32_bf16 v[30:33], v[134:137], v[216:219], v[30:33]
	v_mfma_f32_16x16x32_bf16 v[26:29], v[164:167], v[216:219], v[26:29]
	v_mfma_f32_16x16x32_bf16 v[14:17], v[134:137], v[224:227], v[14:17]
	v_mfma_f32_16x16x32_bf16 v[10:13], v[164:167], v[224:227], v[10:13]
	v_mfma_f32_16x16x32_bf16 v[54:57], v[168:171], v[192:195], v[54:57]
	v_mfma_f32_16x16x32_bf16 v[50:53], v[184:187], v[192:195], v[50:53]
	v_mfma_f32_16x16x32_bf16 v[38:41], v[168:171], v[204:207], v[38:41]
	v_mfma_f32_16x16x32_bf16 v[34:37], v[184:187], v[204:207], v[34:37]
	v_mfma_f32_16x16x32_bf16 v[22:25], v[168:171], v[212:215], v[22:25]
	v_mfma_f32_16x16x32_bf16 v[18:21], v[184:187], v[212:215], v[18:21]
	v_mfma_f32_16x16x32_bf16 v[6:9], v[168:171], v[220:223], v[6:9]
	v_mfma_f32_16x16x32_bf16 v[2:5], v[184:187], v[220:223], v[2:5]
	v_mfma_f32_16x16x32_bf16 v[54:57], v[180:183], v[200:203], v[54:57]
	v_mfma_f32_16x16x32_bf16 v[50:53], v[188:191], v[200:203], v[50:53]
	v_mfma_f32_16x16x32_bf16 v[38:41], v[180:183], v[208:211], v[38:41]
	v_mfma_f32_16x16x32_bf16 v[34:37], v[188:191], v[208:211], v[34:37]
	v_mfma_f32_16x16x32_bf16 v[22:25], v[180:183], v[216:219], v[22:25]
	v_mfma_f32_16x16x32_bf16 v[18:21], v[188:191], v[216:219], v[18:21]
	v_mfma_f32_16x16x32_bf16 v[6:9], v[180:183], v[224:227], v[6:9]
	v_mfma_f32_16x16x32_bf16 v[2:5], v[188:191], v[224:227], v[2:5]
	s_barrier
	s_add_i32 s55, 0, 0x18000
	v_add_u32_e32 v148, s55, v174
	s_add_i32 s76, 0, 0x1c000
	ds_read_b128 v[130:133], v148
	ds_read_b128 v[134:137], v148 offset:1024
	ds_read_b128 v[138:141], v148 offset:2048
	ds_read_b128 v[164:167], v148 offset:3072
	v_add_u32_e32 v148, s76, v174
	ds_read_b128 v[168:171], v148
	ds_read_b128 v[180:183], v148 offset:1024
	ds_read_b128 v[184:187], v148 offset:2048
	ds_read_b128 v[188:191], v148 offset:3072
	s_add_u32 s52, s74, 0x80000
	s_addc_u32 s53, s75, 0
	s_mov_b32 m0, s89
	v_lshl_add_u64 v[230:231], s[52:53], 0, v[144:145]
	ds_read_b128 v[192:195], v178 offset:32768
	ds_read_b128 v[200:203], v178 offset:33792
	ds_read_b128 v[204:207], v178 offset:34816
	ds_read_b128 v[208:211], v178 offset:35840
	ds_read_b128 v[212:215], v178 offset:36864
	ds_read_b128 v[216:219], v178 offset:37888
	ds_read_b128 v[220:223], v178 offset:38912
	ds_read_b128 v[224:227], v178 offset:39936
	global_load_lds_dwordx4 v[230:231], off
	v_lshl_add_u64 v[230:231], s[52:53], 0, v[146:147]
	s_mov_b32 m0, s90
	s_nop 0
	global_load_lds_dwordx4 v[230:231], off
	s_waitcnt vmcnt(8)
	s_waitcnt lgkmcnt(0)
	s_barrier
	s_waitcnt lgkmcnt(0)
	v_mfma_f32_16x16x32_bf16 v[126:129], v[130:133], v[192:195], v[126:129]
	v_mfma_f32_16x16x32_bf16 v[122:125], v[138:141], v[192:195], v[122:125]
	v_mfma_f32_16x16x32_bf16 v[110:113], v[130:133], v[204:207], v[110:113]
	v_mfma_f32_16x16x32_bf16 v[106:109], v[138:141], v[204:207], v[106:109]
	v_mfma_f32_16x16x32_bf16 v[94:97], v[130:133], v[212:215], v[94:97]
	v_mfma_f32_16x16x32_bf16 v[90:93], v[138:141], v[212:215], v[90:93]
	v_mfma_f32_16x16x32_bf16 v[78:81], v[130:133], v[220:223], v[78:81]
	v_mfma_f32_16x16x32_bf16 v[74:77], v[138:141], v[220:223], v[74:77]
	v_mfma_f32_16x16x32_bf16 v[126:129], v[134:137], v[200:203], v[126:129]
	v_mfma_f32_16x16x32_bf16 v[122:125], v[164:167], v[200:203], v[122:125]
	v_mfma_f32_16x16x32_bf16 v[110:113], v[134:137], v[208:211], v[110:113]
	v_mfma_f32_16x16x32_bf16 v[106:109], v[164:167], v[208:211], v[106:109]
	v_mfma_f32_16x16x32_bf16 v[94:97], v[134:137], v[216:219], v[94:97]
	v_mfma_f32_16x16x32_bf16 v[90:93], v[164:167], v[216:219], v[90:93]
	v_mfma_f32_16x16x32_bf16 v[78:81], v[134:137], v[224:227], v[78:81]
	v_mfma_f32_16x16x32_bf16 v[74:77], v[164:167], v[224:227], v[74:77]
	v_mfma_f32_16x16x32_bf16 v[118:121], v[168:171], v[192:195], v[118:121]
	v_mfma_f32_16x16x32_bf16 v[114:117], v[184:187], v[192:195], v[114:117]
	v_mfma_f32_16x16x32_bf16 v[102:105], v[168:171], v[204:207], v[102:105]
	v_mfma_f32_16x16x32_bf16 v[98:101], v[184:187], v[204:207], v[98:101]
	v_mfma_f32_16x16x32_bf16 v[86:89], v[168:171], v[212:215], v[86:89]
	v_mfma_f32_16x16x32_bf16 v[82:85], v[184:187], v[212:215], v[82:85]
	v_mfma_f32_16x16x32_bf16 v[70:73], v[168:171], v[220:223], v[70:73]
	v_mfma_f32_16x16x32_bf16 v[66:69], v[184:187], v[220:223], v[66:69]
	v_mfma_f32_16x16x32_bf16 v[118:121], v[180:183], v[200:203], v[118:121]
	v_mfma_f32_16x16x32_bf16 v[114:117], v[188:191], v[200:203], v[114:117]
	v_mfma_f32_16x16x32_bf16 v[102:105], v[180:183], v[208:211], v[102:105]
	v_mfma_f32_16x16x32_bf16 v[98:101], v[188:191], v[208:211], v[98:101]
	v_mfma_f32_16x16x32_bf16 v[86:89], v[180:183], v[216:219], v[86:89]
	v_mfma_f32_16x16x32_bf16 v[82:85], v[188:191], v[216:219], v[82:85]
	v_mfma_f32_16x16x32_bf16 v[70:73], v[180:183], v[224:227], v[70:73]
	v_mfma_f32_16x16x32_bf16 v[66:69], v[188:191], v[224:227], v[66:69]
	s_barrier
; #define PG8_STAGE(bufoff, gbase, voff) do { _Pragma("unroll") for (int _i = 0; _i < 2; ++_i) \
;         __builtin_amdgcn_global_load_lds((const unsigned*)((const char*)(gbase) + (voff)[_i]), (PG8_LAS unsigned*)(lds + (bufoff) + ldsw + _i * 8192), 16, 0, 0); } while (0)
; #define PG8_LDA(dst, b, h) do { _Pragma("unroll") for (int m = 0; m < 4; ++m) _Pragma("unroll") for (int k = 0; k < 2; ++k) dst[m][k] = *(const PG8_LAS bf16x8*)(lds + PG8_SA(b, h) + aoff + m * 2048 + k * 1024); } while (0)
; #define PG8_WAIT_V(n) asm volatile("s_waitcnt vmcnt(" #n ")" ::: "memory")
; template <class Epi, class Sched, bool ALIGN_EPI = false, bool SP2 = false, bool MID = false>
; __device__ __forceinline__ void gemm_phase(PG8_LAS unsigned char* lds, const Gemm g, const Sched& S, const Epi& E) {
;     ...
;         for (int t = 0; t < nt; t += 2) {
;             const bool last = (t == nt - 2);
;             if constexpr (MID) { if (t == Epi::MID_T) { PG8_SCHED; E.mid(acc, cur, wr, wc, fr, fq); PG8_SCHED; } }
;             const char* a1 = cA + (size_t)(t + 1) * kstep;
;             const char* a2 = last ? nA : cA + (size_t)(t + 2) * kstep; const char* b2 = last ? nB : cB + (size_t)(t + 2) * kstep;
;             const char* a3 = a2 + kstep; const char* b3 = b2 + kstep;
;             if (last && has_next) S.a_ready(nxt);
;             if constexpr (SP2) {
;             PG8_LDB(B0, 0, 0); PG8_LDB(B1, 0, 1); PG8_SCHED; PG8_LDA(At, 0, 0); PG8_STAGE(PG8_SA(1, 1), a1 + hstep, voffA);
;             PG8_WAIT_V(8); PG8_WAIT_L(0); PG8_BAR; PG8_MMA(0, 0, At, B0); PG8_MMA(0, 1, At, B1); PG8_BAR; PG8_SCHED;
;             PG8_LDA(At, 0, 1); PG8_STAGE(PG8_SB(0, 0), b2, voffB); PG8_STAGE(PG8_SB(0, 1), b2 + hstep, voffB); PG8_STAGE(PG8_SA(0, 0), a2, voffA);
;             PG8_WAIT_V(8); PG8_WAIT_L(0); PG8_BAR; PG8_MMA(1, 0, At, B0); PG8_MMA(1, 1, At, B1); PG8_BAR; PG8_SCHED;
;             PG8_LDB(B0, 1, 0); PG8_LDB(B1, 1, 1); PG8_SCHED; PG8_LDA(At, 1, 0); PG8_STAGE(PG8_SA(0, 1), a2 + hstep, voffA);
;             PG8_WAIT_V(8); PG8_WAIT_L(0); PG8_BAR; PG8_MMA(0, 0, At, B0); PG8_MMA(0, 1, At, B1); PG8_BAR; PG8_SCHED;
;             PG8_LDA(At, 1, 1); PG8_STAGE(PG8_SB(1, 0), b3, voffB); PG8_STAGE(PG8_SB(1, 1), b3 + hstep, voffB); PG8_STAGE(PG8_SA(1, 0), a3, voffA);
;             PG8_WAIT_V(8); PG8_WAIT_L(0); PG8_BAR; PG8_MMA(1, 0, At, B0); PG8_MMA(1, 1, At, B1); PG8_BAR; PG8_SCHED;
	s_add_i32 s52, s55, s87
	v_lshl_add_u64 v[142:143], v[142:143], 0, s[22:23]
	s_mov_b32 m0, s52
	ds_read_b128 v[192:195], v178 offset:49152
	ds_read_b128 v[200:203], v178 offset:50176
	ds_read_b128 v[204:207], v178 offset:51200
	ds_read_b128 v[208:211], v178 offset:52224
	ds_read_b128 v[212:215], v178 offset:53248
	ds_read_b128 v[216:219], v178 offset:54272
	ds_read_b128 v[220:223], v178 offset:55296
	ds_read_b128 v[224:227], v178 offset:56320
	global_load_lds_dwordx4 v[142:143], off
	s_add_i32 m0, s52, 0x2000
	s_add_u32 s52, s72, 0x80080
	v_lshl_add_u64 v[142:143], v[172:173], 0, s[22:23]
	s_addc_u32 s53, s73, 0
	s_add_i32 s55, s76, s87
	global_load_lds_dwordx4 v[142:143], off
	v_lshl_add_u64 v[142:143], s[52:53], 0, v[144:145]
	s_mov_b32 m0, s55
	s_nop 0
	global_load_lds_dwordx4 v[142:143], off
	v_lshl_add_u64 v[142:143], s[52:53], 0, v[146:147]
	s_add_i32 m0, s55, 0x2000
	s_nop 0
	global_load_lds_dwordx4 v[142:143], off
	v_lshl_add_u64 v[142:143], v[196:197], 0, s[22:23]
	s_mov_b32 m0, s94
	s_nop 0
	global_load_lds_dwordx4 v[142:143], off
	v_lshl_add_u64 v[142:143], v[228:229], 0, s[22:23]
	s_mov_b32 m0, s95
	s_nop 0
	global_load_lds_dwordx4 v[142:143], off
	s_waitcnt vmcnt(8)
	s_waitcnt lgkmcnt(0)
	s_barrier
	s_waitcnt lgkmcnt(0)
	v_mfma_f32_16x16x32_bf16 v[62:65], v[130:133], v[192:195], v[62:65]
	v_mfma_f32_16x16x32_bf16 v[58:61], v[138:141], v[192:195], v[58:61]
	v_mfma_f32_16x16x32_bf16 v[46:49], v[130:133], v[204:207], v[46:49]
	v_mfma_f32_16x16x32_bf16 v[42:45], v[138:141], v[204:207], v[42:45]
	v_mfma_f32_16x16x32_bf16 v[30:33], v[130:133], v[212:215], v[30:33]
	v_mfma_f32_16x16x32_bf16 v[26:29], v[138:141], v[212:215], v[26:29]
	v_mfma_f32_16x16x32_bf16 v[14:17], v[130:133], v[220:223], v[14:17]
	v_mfma_f32_16x16x32_bf16 v[10:13], v[138:141], v[220:223], v[10:13]
	v_mfma_f32_16x16x32_bf16 v[62:65], v[134:137], v[200:203], v[62:65]
	v_mfma_f32_16x16x32_bf16 v[58:61], v[164:167], v[200:203], v[58:61]
	v_mfma_f32_16x16x32_bf16 v[46:49], v[134:137], v[208:211], v[46:49]
	v_mfma_f32_16x16x32_bf16 v[42:45], v[164:167], v[208:211], v[42:45]
	v_mfma_f32_16x16x32_bf16 v[30:33], v[134:137], v[216:219], v[30:33]
	v_mfma_f32_16x16x32_bf16 v[26:29], v[164:167], v[216:219], v[26:29]
	v_mfma_f32_16x16x32_bf16 v[14:17], v[134:137], v[224:227], v[14:17]
	v_mfma_f32_16x16x32_bf16 v[10:13], v[164:167], v[224:227], v[10:13]
	v_mfma_f32_16x16x32_bf16 v[54:57], v[168:171], v[192:195], v[54:57]
	v_mfma_f32_16x16x32_bf16 v[50:53], v[184:187], v[192:195], v[50:53]
	v_mfma_f32_16x16x32_bf16 v[38:41], v[168:171], v[204:207], v[38:41]
	v_mfma_f32_16x16x32_bf16 v[34:37], v[184:187], v[204:207], v[34:37]
	v_mfma_f32_16x16x32_bf16 v[22:25], v[168:171], v[212:215], v[22:25]
	v_mfma_f32_16x16x32_bf16 v[18:21], v[184:187], v[212:215], v[18:21]
	v_mfma_f32_16x16x32_bf16 v[6:9], v[168:171], v[220:223], v[6:9]
	v_mfma_f32_16x16x32_bf16 v[2:5], v[184:187], v[220:223], v[2:5]
	v_mfma_f32_16x16x32_bf16 v[54:57], v[180:183], v[200:203], v[54:57]
	v_mfma_f32_16x16x32_bf16 v[50:53], v[188:191], v[200:203], v[50:53]
	v_mfma_f32_16x16x32_bf16 v[38:41], v[180:183], v[208:211], v[38:41]
	v_mfma_f32_16x16x32_bf16 v[34:37], v[188:191], v[208:211], v[34:37]
	v_mfma_f32_16x16x32_bf16 v[22:25], v[180:183], v[216:219], v[22:25]
	v_mfma_f32_16x16x32_bf16 v[18:21], v[188:191], v[216:219], v[18:21]
	v_mfma_f32_16x16x32_bf16 v[6:9], v[180:183], v[224:227], v[6:9]
	v_mfma_f32_16x16x32_bf16 v[2:5], v[188:191], v[224:227], v[2:5]
	s_barrier
	s_add_i32 s51, s51, 2
	s_add_u32 s4, s4, 0x100
	s_addc_u32 s5, s5, 0
	s_add_u32 s26, s26, 0x100
	s_addc_u32 s27, s27, 0
	s_cmp_gt_u32 s51, 29
	s_cbranch_scc0 .LBB0_206
	s_and_b64 vcc, exec, s[42:43]
	s_cbranch_vccz .LBB0_210
	s_barrier
	v_lshl_add_u32 v130, s70, 8, v151
	s_cmp_gt_i32 s16, 23
	s_mov_b64 s[4:5], -1
	s_cbranch_scc1 .LBB0_211

; #define SBAR() __builtin_amdgcn_sched_barrier(0)
; #define VMW() asm volatile("s_waitcnt vmcnt(0)" ::: "memory")
; #define SLOAD_H(Kp, Vp, k0) do { S.st_v0 = load8<TIn>(ROW(Vp, k0, sr)); S.st_v1 = load8<TIn>(ROW(Vp, k0, 32 + sr));              \
;                          S.st_k0 = load8<TIn>(ROW(Kp, k0, sr)); S.st_k1 = load8<TIn>(ROW(Kp, k0, 32 + sr)); } while (0)
; #define SWRITE_HV(bf) do { *(bf16x8*)(V_lds + (bf) * SHM_V + vst0) = S.st_v0; *(bf16x8*)(V_lds + (bf) * SHM_V + vst1) = S.st_v1; } while (0)
; #define SWRITE_H(bf) do { SWRITE_HV(bf); SWRITE_HK(bf); } while (0)
; #define ACT(t) (KBASE(t) <= qlo + QBLK - 1 && KBASE(t) + KVBLK - 1 >= qlo - W + 1)
; __device__ __forceinline__ void partialSM(f32x16& p0, f32x16& p1, float& m_reg, float& mn, float& alpha) {
;     float pmax = p0[0]; for (int r = 1; r < 16; ++r) pmax = fmaxf(pmax, p0[r]); for (int r = 0; r < 16; ++r) pmax = fmaxf(pmax, p1[r]);
;     { auto rr = __builtin_amdgcn_permlane32_swap(__float_as_uint(pmax), __float_as_uint(pmax), false, false);
;       pmax = fmaxf(__uint_as_float(rr[0]), __uint_as_float(rr[1])); }
;     constexpr float C2 = 1.4426950408889634f * SCALE;
;     if (__builtin_expect(__all((pmax - m_reg) * SCALE <= THR), 1)) { mn = m_reg; alpha = 1.f; }
;     else { mn = fmaxf(m_reg, pmax); alpha = __builtin_amdgcn_exp2f((m_reg - mn) * C2); m_reg = mn; }
;     const float mnL = -mn * C2;
;     for (int r = 0; r < 16; ++r) p0[r] = fmaf(p0[r], C2, mnL); for (int r = 0; r < 16; ++r) p1[r] = fmaf(p1[r], C2, mnL);
;     for (int r = 0; r < 16; ++r) p0[r] = __builtin_amdgcn_exp2f(p0[r]);
; }
; template <class TIn, class TOut>
; __device__ __forceinline__ void causal_swa_block(const BlockRef<TIn, TOut>& cur, const BlockRef<TIn, TOut>& nxt, int skv, int W, char* lds, Seam<TIn>& S) {
;     ...
;     if constexpr (F32) { VMW(); SWRITE_VF(0); SBAR(); } else { SWRITE_HV(0); SBAR(); }
;     if (NT > 1) { if constexpr (F32) SLOAD_F((const float*)Kh, KBASE(1)); else SLOAD_H(Kh, Vh, KBASE(1)); }
;     SBAR(); qkt<0, SK>(pA0, pA1, K_lds, r32, hi, S.qr, ACT(0));
;     if constexpr (F32) { if (NT > 1) { VMW(); SWRITE_KF(1); SBAR(); SLOAD_F((const float*)Vh, KBASE(1)); } }
;     MASKT(pA0, pA1, 0); partialSM(pA0, pA1, m_reg, mnA, alA);
;     if (NT > 1) { VMW(); if constexpr (F32) { SWRITE_VF(1); SBAR(); if (NT > 2) SLOAD_F((const float*)Kh, KBASE(2)); } else SWRITE_H(1); }
;     __syncthreads();
.LBB0_1128:
	s_nop 8
	v_max_f32_e32 v50, v19, v19
	v_max_f32_e32 v51, v18, v18
	v_max_f32_e32 v50, v51, v50
	v_max3_f32 v50, v50, v20, v21
	v_max3_f32 v50, v50, v22, v23
	v_max3_f32 v50, v50, v24, v25
	v_max3_f32 v50, v50, v26, v27
	v_max3_f32 v50, v50, v28, v29
	v_max3_f32 v50, v50, v30, v31
	v_max3_f32 v50, v50, v32, v33
	v_max3_f32 v50, v50, v2, v3
	v_max3_f32 v50, v50, v4, v5
	v_max3_f32 v50, v50, v6, v7
	v_max3_f32 v50, v50, v8, v9
	v_max3_f32 v50, v50, v10, v11
	v_max3_f32 v50, v50, v12, v13
	v_max3_f32 v50, v50, v14, v15
	v_max3_f32 v50, v50, v16, v17
	v_mov_b32_e32 v51, v50
	s_nop 1
	v_permlane32_swap_b32_e32 v50, v51
	v_max_f32_e32 v51, v51, v51
	v_max_f32_e32 v50, v50, v50
	v_max_f32_e32 v50, v50, v51
	s_and_b32 s4, s4, 0x3fffffc0
	v_add_f32_e32 v51, 0x7149f2ca, v50
	s_lshl_b32 s4, s4, 2
	v_mul_f32_e32 v51, 0x3db504f3, v51
	v_max_f32_e32 v50, 0xf149f2ca, v50
	s_add_i32 s14, s80, 0xff
	s_add_i32 s4, s4, 0
	v_cmp_ge_f32_e32 vcc, s86, v51
	v_sub_f32_e32 v51, 0xf149f2ca, v50
	s_lshr_b32 s24, s14, 6
	s_add_i32 s4, s4, 0x10000
	s_add_i32 s15, s13, 0xffffc01f
	v_mul_f32_e32 v51, 0x3e0293ee, v51
	v_exp_f32_e32 v51, v51
	s_cmp_eq_u64 vcc, exec
	s_cselect_b64 vcc, -1, 0
	v_cndmask_b32_e32 v178, v50, v216, vcc
	v_mul_f32_e32 v50, 0xbe0293ee, v178
	v_cndmask_b32_e64 v197, v51, 1.0, vcc
	v_mov_b32_e32 v51, v50
	v_fmamk_f32 v18, v18, 0x3e0293ee, v50
	v_fmamk_f32 v19, v19, 0x3e0293ee, v50
	v_fmamk_f32 v20, v20, 0x3e0293ee, v50
	v_fmamk_f32 v21, v21, 0x3e0293ee, v50
	v_fmamk_f32 v22, v22, 0x3e0293ee, v50
	v_fmamk_f32 v23, v23, 0x3e0293ee, v50
	v_fmamk_f32 v24, v24, 0x3e0293ee, v50
	v_fmamk_f32 v25, v25, 0x3e0293ee, v50
	v_fmamk_f32 v26, v26, 0x3e0293ee, v50
	v_fmamk_f32 v27, v27, 0x3e0293ee, v50
	v_fmamk_f32 v28, v28, 0x3e0293ee, v50
	v_fmamk_f32 v29, v29, 0x3e0293ee, v50
	v_fmamk_f32 v30, v30, 0x3e0293ee, v50
	v_fmamk_f32 v31, v31, 0x3e0293ee, v50
	v_fmamk_f32 v32, v32, 0x3e0293ee, v50
	v_fmac_f32_e32 v51, 0x3e0293ee, v33
	v_exp_f32_e32 v170, v18
	v_exp_f32_e32 v171, v19
	v_exp_f32_e32 v172, v20
	v_exp_f32_e32 v173, v21
	v_exp_f32_e32 v174, v22
	v_exp_f32_e32 v176, v23
	v_exp_f32_e32 v175, v24
	v_exp_f32_e32 v177, v25
	v_exp_f32_e32 v162, v26
	v_exp_f32_e32 v163, v27
	v_exp_f32_e32 v164, v28
	v_exp_f32_e32 v166, v29
	v_exp_f32_e32 v165, v30
	v_exp_f32_e32 v167, v31
	v_exp_f32_e32 v168, v32
	v_exp_f32_e32 v169, v51
	s_waitcnt vmcnt(0)
	s_waitcnt vmcnt(3)
	ds_write_b128 v209, v[34:37] offset:16384
	s_waitcnt vmcnt(1)
	ds_write_b128 v210, v[46:49] offset:16384
	ds_write_b128 v217, v[38:41] offset:49152
	s_waitcnt vmcnt(0)
	ds_write_b128 v217, v[42:45] offset:57344
	v_mov_b32_e32 v34, v195
	v_mov_b32_e32 v35, v195
	v_mov_b32_e32 v48, v195
	v_mov_b32_e32 v49, v195
	v_pk_fma_f32 v[118:119], v[16:17], s[50:51], v[50:51] op_sel_hi:[1,0,0]
	v_pk_fma_f32 v[122:123], v[14:15], s[50:51], v[50:51] op_sel_hi:[1,0,0]
	v_pk_fma_f32 v[128:129], v[12:13], s[50:51], v[50:51] op_sel_hi:[1,0,0]
	v_pk_fma_f32 v[114:115], v[10:11], s[50:51], v[50:51] op_sel_hi:[1,0,0]
	v_pk_fma_f32 v[116:117], v[8:9], s[50:51], v[50:51] op_sel_hi:[1,0,0]
	v_pk_fma_f32 v[120:121], v[6:7], s[50:51], v[50:51] op_sel_hi:[1,0,0]
	v_pk_fma_f32 v[124:125], v[4:5], s[50:51], v[50:51] op_sel_hi:[1,0,0]
	v_pk_fma_f32 v[126:127], v[2:3], s[50:51], v[50:51] op_sel_hi:[1,0,0]
	v_mov_b32_e32 v36, v195
	v_mov_b32_e32 v37, v195
	v_mov_b32_e32 v38, v195
	v_mov_b32_e32 v39, v195
	v_mov_b32_e32 v40, v195
	v_mov_b32_e32 v41, v195
	v_mov_b32_e32 v42, v195
	v_mov_b32_e32 v43, v195
	v_mov_b32_e32 v44, v195
	v_mov_b32_e32 v45, v195
	v_mov_b32_e32 v46, v195
	v_mov_b32_e32 v47, v195
	v_mov_b64_e32 v[64:65], v[48:49]
	v_mov_b64_e32 v[18:19], v[34:35]
	v_mov_b64_e32 v[2:3], v[34:35]
	s_mov_b32 s25, 2
	v_lshl_add_u32 v219, v199, 2, s4
	v_lshl_add_u32 v218, v200, 2, s4
	v_add_u32_e32 v222, s12, v201
	v_mov_b32_e32 v221, 0
	s_movk_i32 s26, 0xbf
	v_mov_b32_e32 v194, v203
	v_mov_b64_e32 v[62:63], v[46:47]
	v_mov_b64_e32 v[60:61], v[44:45]
	v_mov_b64_e32 v[58:59], v[42:43]
	v_mov_b64_e32 v[56:57], v[40:41]
	v_mov_b64_e32 v[54:55], v[38:39]
	v_mov_b64_e32 v[52:53], v[36:37]
	v_mov_b64_e32 v[50:51], v[34:35]
	v_mov_b64_e32 v[20:21], v[36:37]
	v_mov_b64_e32 v[22:23], v[38:39]
	v_mov_b64_e32 v[24:25], v[40:41]
	v_mov_b64_e32 v[26:27], v[42:43]
	v_mov_b64_e32 v[28:29], v[44:45]
	v_mov_b64_e32 v[30:31], v[46:47]
	v_mov_b64_e32 v[32:33], v[48:49]
	v_mov_b64_e32 v[4:5], v[36:37]
	v_mov_b64_e32 v[6:7], v[38:39]
	v_mov_b64_e32 v[8:9], v[40:41]
	v_mov_b64_e32 v[10:11], v[42:43]
	v_mov_b64_e32 v[12:13], v[44:45]
	v_mov_b64_e32 v[14:15], v[46:47]
	v_mov_b64_e32 v[16:17], v[48:49]
	s_waitcnt lgkmcnt(0)
	s_barrier
	v_lshlrev_b32_e32 v255, 1, v194
	v_mov_b32_e32 v252, v178
	v_mul_f32_e32 v253, 0xbe0293ee, v178
; __device__ __forceinline__ void finishSM(f32x16& p0, f32x16& p1, float alpha, float& l_reg, bf16x8& pa0, bf16x8& pa1, bf16x8& pa2, bf16x8& pa3) {
;     for (int r = 0; r < 16; ++r) p1[r] = __builtin_amdgcn_exp2f(p1[r]);
;     float ps = 0; for (int r = 0; r < 16; ++r) ps += p0[r]; for (int r = 0; r < 16; ++r) ps += p1[r];
;     { auto rr = __builtin_amdgcn_permlane32_swap(__float_as_uint(ps), __float_as_uint(ps), false, false);
;       ps = __uint_as_float(rr[0]) + __uint_as_float(rr[1]); }
;     l_reg = l_reg * alpha + ps;
;     ...
;     PK4(p0, 0, pa0); PK4(p0, 8, pa1); PK4(p1, 0, pa2); PK4(p1, 8, pa3);
;     ...
; }
; template <int KB, bool SK>
; __device__ __forceinline__ void qkt(f32x16& p0, f32x16& p1, const char* K_lds, int r32, int hi, const bf16x8* qr, bool act) {
;     if (SK && !act) { const float NEG = -__builtin_inff();
; #pragma unroll
;         for (int r = 0; r < 16; ++r) { p0[r] = NEG; p1[r] = NEG; } return; }
;     p0 = f32x16{}; p1 = f32x16{};
;     const char* kb[4];
; #pragma unroll
;     for (int dd = 0; dd < 4; ++dd) kb[dd] = K_lds + KB * SHM_K + KSWZ(r32, (dd * 16 + hi * 8) * 2);
; #pragma unroll
;     for (int d0 = 0; d0 < 8; ++d0) { const char* a = kb[d0 & 3] + (d0 >> 2) * 128;
;         bf16x8 b0 = *reinterpret_cast<const bf16x8*>(a);
;         bf16x8 b1 = *reinterpret_cast<const bf16x8*>(a + 32 * 256);
;         const bf16x8 qf = qr[d0];
;         p0 = __builtin_amdgcn_mfma_f32_32x32x16_bf16(b0, qf, p0, 0, 0, 0);
;         p1 = __builtin_amdgcn_mfma_f32_32x32x16_bf16(b1, qf, p1, 0, 0, 0); }
; }
.LBB0_1129:
	ds_read_b128 v[180:183], v211 offset:49152
	ds_read_b128 v[184:187], v211 offset:57344
	ds_read_b128 v[188:191], v212 offset:49152
	ds_read_b128 v[228:231], v212 offset:57344
	ds_read_b128 v[232:235], v213 offset:49152
	ds_read_b128 v[236:239], v213 offset:57344
	ds_read_b128 v[240:243], v214 offset:49152
	ds_read_b128 v[244:247], v214 offset:57344
	v_exp_f32_e32 v126, v126
	v_exp_f32_e32 v127, v127
	v_exp_f32_e32 v124, v124
	v_exp_f32_e32 v125, v125
	v_exp_f32_e32 v120, v120
	v_exp_f32_e32 v121, v121
	s_add_i32 s4, s26, 0xffffff81
	s_sub_i32 s5, s26, 64
	s_waitcnt lgkmcnt(7)
	v_mfma_f32_32x32x16_bf16 v[86:101], v[180:183], v[158:161], 0
	ds_read_b128 v[180:183], v211 offset:49280
	v_exp_f32_e32 v116, v116
	v_exp_f32_e32 v117, v117
	v_exp_f32_e32 v114, v114
	v_exp_f32_e32 v115, v115
	v_exp_f32_e32 v128, v128
	s_waitcnt lgkmcnt(7)
	v_mfma_f32_32x32x16_bf16 v[70:85], v[184:187], v[158:161], 0
	ds_read_b128 v[184:187], v211 offset:57472
	v_exp_f32_e32 v129, v129
	v_exp_f32_e32 v122, v122
	v_exp_f32_e32 v123, v123
	v_exp_f32_e32 v118, v118
	v_exp_f32_e32 v119, v119
	s_waitcnt lgkmcnt(7)
	v_mfma_f32_32x32x16_bf16 v[86:101], v[188:191], v[154:157], v[86:101]
	ds_read_b128 v[188:191], v212 offset:49280
	v_add_f32_e32 v179, 0, v170
	v_add_f32_e32 v179, v171, v179
	v_add_f32_e32 v179, v172, v179
	v_add_f32_e32 v179, v173, v179
	v_add_f32_e32 v179, v174, v179
	s_waitcnt lgkmcnt(7)
	v_mfma_f32_32x32x16_bf16 v[70:85], v[228:231], v[154:157], v[70:85]
	ds_read_b128 v[228:231], v212 offset:57472
	v_add_f32_e32 v179, v176, v179
	v_add_f32_e32 v179, v175, v179
	v_add_f32_e32 v179, v177, v179
	v_add_f32_e32 v179, v162, v179
	v_add_f32_e32 v179, v163, v179
	s_waitcnt lgkmcnt(7)
	v_mfma_f32_32x32x16_bf16 v[86:101], v[232:235], v[150:153], v[86:101]
	ds_read_b128 v[232:235], v213 offset:49280
	v_add_f32_e32 v110, v164, v179
	v_add_f32_e32 v110, v166, v110
	v_add_f32_e32 v110, v165, v110
	v_add_f32_e32 v110, v167, v110
	s_waitcnt lgkmcnt(7)
	v_mfma_f32_32x32x16_bf16 v[70:85], v[236:239], v[150:153], v[70:85]
	ds_read_b128 v[236:239], v213 offset:57472
	v_add_f32_e32 v110, v168, v110
	v_add_f32_e32 v110, v169, v110
	v_add_f32_e32 v110, v126, v110
	v_add_f32_e32 v102, v127, v110
	s_waitcnt lgkmcnt(7)
	v_mfma_f32_32x32x16_bf16 v[86:101], v[240:243], v[134:137], v[86:101]
	ds_read_b128 v[240:243], v214 offset:49280
	v_add_f32_e32 v102, v124, v102
	v_add_f32_e32 v102, v125, v102
	v_add_f32_e32 v102, v120, v102
	v_add_f32_e32 v102, v121, v102
	s_waitcnt lgkmcnt(7)
	v_mfma_f32_32x32x16_bf16 v[70:85], v[244:247], v[134:137], v[70:85]
	ds_read_b128 v[244:247], v214 offset:57472
	v_add_f32_e32 v102, v116, v102
	v_add_f32_e32 v102, v117, v102
	v_add_f32_e32 v102, v114, v102
	v_add_f32_e32 v102, v115, v102
	s_waitcnt lgkmcnt(7)
	v_mfma_f32_32x32x16_bf16 v[86:101], v[180:183], v[138:141], v[86:101]
	v_add_f32_e32 v102, v128, v102
	v_add_f32_e32 v102, v129, v102
	v_add_f32_e32 v102, v122, v102
	v_add_f32_e32 v102, v123, v102
	s_waitcnt lgkmcnt(6)
	v_mfma_f32_32x32x16_bf16 v[70:85], v[184:187], v[138:141], v[70:85]
	v_add_f32_e32 v102, v118, v102
	v_add_f32_e32 v223, v119, v102
	v_mov_b32_e32 v224, v223
	s_nop 1
	v_permlane32_swap_b32_e32 v223, v224
	s_waitcnt lgkmcnt(5)
	v_mfma_f32_32x32x16_bf16 v[86:101], v[188:191], v[142:145], v[86:101]
	v_cvt_pk_bf16_f32 v102, v170, v171
	v_cvt_pk_bf16_f32 v103, v172, v173
	v_cvt_pk_bf16_f32 v104, v174, v176
	v_cvt_pk_bf16_f32 v105, v175, v177
	s_waitcnt lgkmcnt(4)
	v_mfma_f32_32x32x16_bf16 v[70:85], v[228:231], v[142:145], v[70:85]
	v_cvt_pk_bf16_f32 v66, v162, v163
	v_cvt_pk_bf16_f32 v67, v164, v166
	v_cvt_pk_bf16_f32 v68, v165, v167
	v_cvt_pk_bf16_f32 v69, v168, v169
	s_waitcnt lgkmcnt(3)
	v_mfma_f32_32x32x16_bf16 v[86:101], v[232:235], v[146:149], v[86:101]
	v_cvt_pk_bf16_f32 v106, v126, v127
	v_cvt_pk_bf16_f32 v107, v124, v125
	v_cvt_pk_bf16_f32 v108, v120, v121
	v_cvt_pk_bf16_f32 v109, v116, v117
	s_waitcnt lgkmcnt(2)
	v_mfma_f32_32x32x16_bf16 v[70:85], v[236:239], v[146:149], v[70:85]
	v_cvt_pk_bf16_f32 v110, v114, v115
	v_cvt_pk_bf16_f32 v111, v128, v129
	v_cvt_pk_bf16_f32 v112, v122, v123
	v_cvt_pk_bf16_f32 v113, v118, v119
	s_waitcnt lgkmcnt(1)
	v_mfma_f32_32x32x16_bf16 v[86:101], v[240:243], v[130:133], v[86:101]
	s_nop 1
	v_permlane32_swap_b32_e32 v102, v104
	v_permlane32_swap_b32_e32 v103, v105
	v_permlane32_swap_b32_e32 v66, v68
	v_permlane32_swap_b32_e32 v67, v69
	s_waitcnt lgkmcnt(0)
	v_mfma_f32_32x32x16_bf16 v[70:85], v[244:247], v[130:133], v[70:85]
	v_permlane32_swap_b32_e32 v106, v108
	v_permlane32_swap_b32_e32 v107, v109
	v_permlane32_swap_b32_e32 v110, v112
	v_permlane32_swap_b32_e32 v111, v113
	v_add_u32_e32 v114, 0x2000, v255
	global_load_dwordx4 v[162:165], v255, s[42:43]
	global_load_dwordx4 v[166:169], v114, s[42:43]
	global_load_dwordx4 v[170:173], v255, s[22:23]
	global_load_dwordx4 v[174:177], v114, s[22:23]
	s_cmp_le_i32 s5, s13
	s_cselect_b64 s[52:53], -1, 0
	s_cmp_gt_i32 s4, s15
	s_cselect_b64 s[4:5], -1, 0
	s_and_b64 s[4:5], s[52:53], s[4:5]
	s_and_b64 vcc, exec, s[4:5]
	ds_read_b64_tr_b16 v[114:115], v202 offset:0x0
	ds_read_b64_tr_b16 v[116:117], v202 offset:0x800
	ds_read_b64_tr_b16 v[118:119], v202 offset:0x1000
	ds_read_b64_tr_b16 v[120:121], v202 offset:0x1800
	ds_read_b64_tr_b16 v[122:123], v202 offset:0x2000
	ds_read_b64_tr_b16 v[124:125], v202 offset:0x2800
	ds_read_b64_tr_b16 v[126:127], v202 offset:0x3000
	ds_read_b64_tr_b16 v[128:129], v202 offset:0x3800
	ds_read_b64_tr_b16 v[182:183], v202 offset:0x200
	ds_read_b64_tr_b16 v[184:185], v202 offset:0xa00
	ds_read_b64_tr_b16 v[186:187], v202 offset:0x1200
	ds_read_b64_tr_b16 v[188:189], v202 offset:0x1a00
	ds_read_b64_tr_b16 v[190:191], v202 offset:0x2200
	ds_read_b64_tr_b16 v[192:193], v202 offset:0x2a00
	s_cbranch_vccnz .Lh1_nomask
; __device__ __forceinline__ void mask_tile(f32x16& p0, f32x16& p1, int dq, unsigned W) {
;     const float NEG = -__builtin_inff();
; #pragma unroll
;     for (int r = 0; r < 16; ++r) {
;         const int c = (r & 3) + 8 * (r >> 2);
;         if ((unsigned)(dq - c) >= W) p0[r] = NEG;
;         if ((unsigned)(dq - c - 32) >= W) p1[r] = NEG;
;     }
; }
	v_add_u32_e32 v226, s80, v222
	v_subrev_u32_e32 v240, 64, v226
	v_cmp_gt_u32_e32 vcc, s85, v240
	v_add_u32_e32 v240, 0xffffffa0, v226
	s_nop 0
	v_cndmask_b32_e32 v86, v215, v86, vcc
	v_cmp_gt_u32_e32 vcc, s85, v240
	v_add_u32_e32 v240, 0xffffffbf, v226
	s_nop 0
	v_cndmask_b32_e32 v70, v215, v70, vcc
	v_cmp_gt_u32_e32 vcc, s85, v240
	v_add_u32_e32 v240, 0xffffff9f, v226
	s_nop 0
	v_cndmask_b32_e32 v87, v215, v87, vcc
	v_cmp_gt_u32_e32 vcc, s85, v240
	v_add_u32_e32 v240, 0xffffffbe, v226
	s_nop 0
	v_cndmask_b32_e32 v71, v215, v71, vcc
	v_cmp_gt_u32_e32 vcc, s85, v240
	v_add_u32_e32 v240, 0xffffff9e, v226
	s_nop 0
	v_cndmask_b32_e32 v88, v215, v88, vcc
	v_cmp_gt_u32_e32 vcc, s85, v240
	v_add_u32_e32 v240, 0xffffffbd, v226
	s_nop 0
	v_cndmask_b32_e32 v72, v215, v72, vcc
	v_cmp_gt_u32_e32 vcc, s85, v240
	v_add_u32_e32 v240, 0xffffff9d, v226
	s_nop 0
	v_cndmask_b32_e32 v89, v215, v89, vcc
	v_cmp_gt_u32_e32 vcc, s85, v240
	v_add_u32_e32 v240, 0xffffffb8, v226
	s_nop 0
	v_cndmask_b32_e32 v73, v215, v73, vcc
	v_cmp_gt_u32_e32 vcc, s85, v240
	v_add_u32_e32 v240, 0xffffff98, v226
	s_nop 0
	v_cndmask_b32_e32 v90, v215, v90, vcc
	v_cmp_gt_u32_e32 vcc, s85, v240
	v_add_u32_e32 v240, 0xffffffb7, v226
	s_nop 0
	v_cndmask_b32_e32 v74, v215, v74, vcc
	v_cmp_gt_u32_e32 vcc, s85, v240
	v_add_u32_e32 v240, 0xffffff97, v226
	s_nop 0
	v_cndmask_b32_e32 v91, v215, v91, vcc
	v_cmp_gt_u32_e32 vcc, s85, v240
	v_add_u32_e32 v240, 0xffffffb6, v226
	s_nop 0
	v_cndmask_b32_e32 v75, v215, v75, vcc
	v_cmp_gt_u32_e32 vcc, s85, v240
	v_add_u32_e32 v240, 0xffffff96, v226
	s_nop 0
	v_cndmask_b32_e32 v92, v215, v92, vcc
	v_cmp_gt_u32_e32 vcc, s85, v240
	v_add_u32_e32 v240, 0xffffffb5, v226
	s_nop 0
	v_cndmask_b32_e32 v76, v215, v76, vcc
	v_cmp_gt_u32_e32 vcc, s85, v240
	v_add_u32_e32 v240, 0xffffff95, v226
	s_nop 0
	v_cndmask_b32_e32 v93, v215, v93, vcc
	v_cmp_gt_u32_e32 vcc, s85, v240
	v_add_u32_e32 v240, 0xffffffb0, v226
	s_nop 0
	v_cndmask_b32_e32 v77, v215, v77, vcc
	v_cmp_gt_u32_e32 vcc, s85, v240
	v_add_u32_e32 v240, 0xffffff90, v226
	s_nop 0
	v_cndmask_b32_e32 v94, v215, v94, vcc
	v_cmp_gt_u32_e32 vcc, s85, v240
	v_add_u32_e32 v240, 0xffffffaf, v226
	s_nop 0
	v_cndmask_b32_e32 v78, v215, v78, vcc
	v_cmp_gt_u32_e32 vcc, s85, v240
	v_add_u32_e32 v240, 0xffffff8f, v226
	s_nop 0
	v_cndmask_b32_e32 v95, v215, v95, vcc
	v_cmp_gt_u32_e32 vcc, s85, v240
	v_add_u32_e32 v240, 0xffffffae, v226
	s_nop 0
	v_cndmask_b32_e32 v79, v215, v79, vcc
	v_cmp_gt_u32_e32 vcc, s85, v240
	v_add_u32_e32 v240, 0xffffff8e, v226
	s_nop 0
	v_cndmask_b32_e32 v96, v215, v96, vcc
	v_cmp_gt_u32_e32 vcc, s85, v240
	v_add_u32_e32 v240, 0xffffffad, v226
	s_nop 0
	v_cndmask_b32_e32 v80, v215, v80, vcc
	v_cmp_gt_u32_e32 vcc, s85, v240
	v_add_u32_e32 v240, 0xffffff8d, v226
	s_nop 0
	v_cndmask_b32_e32 v97, v215, v97, vcc
	v_cmp_gt_u32_e32 vcc, s85, v240
	v_add_u32_e32 v240, 0xffffffa8, v226
	s_nop 0
	v_cndmask_b32_e32 v81, v215, v81, vcc
	v_cmp_gt_u32_e32 vcc, s85, v240
	v_add_u32_e32 v240, 0xffffff88, v226
	s_nop 0
	v_cndmask_b32_e32 v98, v215, v98, vcc
	v_cmp_gt_u32_e32 vcc, s85, v240
	v_add_u32_e32 v240, 0xffffffa7, v226
	s_nop 0
	v_cndmask_b32_e32 v82, v215, v82, vcc
	v_cmp_gt_u32_e32 vcc, s85, v240
	v_add_u32_e32 v240, 0xffffff87, v226
	s_nop 0
	v_cndmask_b32_e32 v99, v215, v99, vcc
	v_cmp_gt_u32_e32 vcc, s85, v240
	v_add_u32_e32 v240, 0xffffffa6, v226
	s_nop 0
	v_cndmask_b32_e32 v83, v215, v83, vcc
	v_cmp_gt_u32_e32 vcc, s85, v240
	v_add_u32_e32 v240, 0xffffff86, v226
	s_nop 0
	v_cndmask_b32_e32 v100, v215, v100, vcc
	v_cmp_gt_u32_e32 vcc, s85, v240
	v_add_u32_e32 v240, 0xffffffa5, v226
	s_nop 0
	v_cndmask_b32_e32 v84, v215, v84, vcc
	v_cmp_gt_u32_e32 vcc, s85, v240
	v_add_u32_e32 v240, 0xffffff85, v226
	s_nop 0
	v_cndmask_b32_e32 v101, v215, v101, vcc
	v_cmp_gt_u32_e32 vcc, s85, v240
	s_nop 1
	v_cndmask_b32_e32 v85, v215, v85, vcc

; #define PG8_STAGE(bufoff, gbase, voff) do { _Pragma("unroll") for (int _i = 0; _i < 2; ++_i) \
;         __builtin_amdgcn_global_load_lds((const unsigned*)((const char*)(gbase) + (voff)[_i]), (PG8_LAS unsigned*)(lds + (bufoff) + ldsw + _i * 8192), 16, 0, 0); } while (0)
; #define PG8_LDA(dst, b, h) do { _Pragma("unroll") for (int m = 0; m < 4; ++m) _Pragma("unroll") for (int k = 0; k < 2; ++k) dst[m][k] = *(const PG8_LAS bf16x8*)(lds + PG8_SA(b, h) + aoff + m * 2048 + k * 1024); } while (0)
; #define PG8_LDB(dst, b, h) do { _Pragma("unroll") for (int n = 0; n < 2; ++n) _Pragma("unroll") for (int k = 0; k < 2; ++k) dst[n][k] = *(const PG8_LAS bf16x8*)(lds + PG8_SB(b, h) + boff + n * 2048 + k * 1024); } while (0)
; #define PG8_MMA(ai, bj, At, Bt) do { __builtin_amdgcn_s_setprio(1); _Pragma("unroll") for (int m = 0; m < 4; ++m) _Pragma("unroll") for (int n = 0; n < 2; ++n) _Pragma("unroll") for (int k = 0; k < 2; ++k) \
;         acc[ai][bj][m][n] = __builtin_amdgcn_mfma_f32_16x16x32_bf16(Bt[n][k], At[m][k], acc[ai][bj][m][n], 0, 0, 0); __builtin_amdgcn_s_setprio(0); } while (0)
; #define PG8_BAR __builtin_amdgcn_s_barrier()
; template <class Epi, class Sched, bool ALIGN_EPI = false, bool SP2 = false, bool MID = false>
; __device__ __forceinline__ void gemm_phase(PG8_LAS unsigned char* lds, const Gemm g, const Sched& S, const Epi& E) {
;     ...
;             PG8_LDB(B0, 0, 0); PG8_LDB(B1, 0, 1); PG8_SCHED; PG8_LDA(At, 0, 0); PG8_STAGE(PG8_SA(1, 1), a1 + hstep, voffA);
;             PG8_WAIT_V(8); PG8_WAIT_L(0); PG8_BAR; PG8_MMA(0, 0, At, B0); PG8_MMA(0, 1, At, B1); PG8_BAR; PG8_SCHED;
;             PG8_LDA(At, 0, 1); PG8_STAGE(PG8_SB(0, 0), b2, voffB); PG8_STAGE(PG8_SB(0, 1), b2 + hstep, voffB); PG8_STAGE(PG8_SA(0, 0), a2, voffA);
;             PG8_WAIT_V(8); PG8_WAIT_L(0); PG8_BAR; PG8_MMA(1, 0, At, B0); PG8_MMA(1, 1, At, B1); PG8_BAR; PG8_SCHED;
;             PG8_LDB(B0, 1, 0); PG8_LDB(B1, 1, 1); PG8_SCHED; PG8_LDA(At, 1, 0); PG8_STAGE(PG8_SA(0, 1), a2 + hstep, voffA);
;             PG8_WAIT_V(8); PG8_WAIT_L(0); PG8_BAR; PG8_MMA(0, 0, At, B0); PG8_MMA(0, 1, At, B1); PG8_BAR; PG8_SCHED;
;             PG8_LDA(At, 1, 1); PG8_STAGE(PG8_SB(1, 0), b3, voffB); PG8_STAGE(PG8_SB(1, 1), b3 + hstep, voffB); PG8_STAGE(PG8_SA(1, 0), a3, voffA);
;             PG8_WAIT_V(8); PG8_WAIT_L(0); PG8_BAR; PG8_MMA(1, 0, At, B0); PG8_MMA(1, 1, At, B1); PG8_BAR; PG8_SCHED;
.LBB0_1439:
	v_add_u32_e32 v142, s15, v193
	v_add_u32_e32 v175, s81, v193
	s_add_u32 s4, s42, s46
	ds_read_b128 v[130:133], v142
	ds_read_b128 v[134:137], v142 offset:1024
	ds_read_b128 v[138:141], v142 offset:2048
	ds_read_b128 v[142:145], v142 offset:3072
	ds_read_b128 v[146:149], v175
	ds_read_b128 v[150:153], v175 offset:1024
	ds_read_b128 v[154:157], v175 offset:2048
	ds_read_b128 v[184:187], v175 offset:3072
	s_addc_u32 s5, s43, s47
	s_add_u32 s4, s4, 0x100
	s_addc_u32 s5, s5, 0
	s_add_u32 s92, s89, s46
	s_addc_u32 s93, s90, s47
	s_cmpk_eq_i32 s46, 0xf00
	s_cselect_b32 s49, s37, s5
	s_cselect_b32 s48, s87, s4
	s_cselect_b32 s5, s27, s93
	s_cselect_b32 s4, s88, s92
	v_lshl_add_u64 v[196:197], v[180:181], 0, s[46:47]
	s_add_i32 m0, s54, 0xc000
	ds_read_b128 v[188:191], v195
	ds_read_b128 v[200:203], v195 offset:1024
	ds_read_b128 v[204:207], v195 offset:2048
	ds_read_b128 v[208:211], v195 offset:3072
	ds_read_b128 v[212:215], v195 offset:4096
	ds_read_b128 v[216:219], v195 offset:5120
	ds_read_b128 v[220:223], v195 offset:6144
	ds_read_b128 v[224:227], v195 offset:7168
	global_load_lds_dwordx4 v[196:197], off
	v_lshl_add_u64 v[196:197], v[182:183], 0, s[46:47]
	s_add_i32 m0, s54, 0xe000
	s_nop 0
	global_load_lds_dwordx4 v[196:197], off
	s_waitcnt vmcnt(8)
	s_waitcnt lgkmcnt(0)
	s_barrier
	s_waitcnt lgkmcnt(0)
	v_mfma_f32_16x16x32_bf16 v[126:129], v[130:133], v[188:191], v[126:129]
	v_mfma_f32_16x16x32_bf16 v[122:125], v[138:141], v[188:191], v[122:125]
	v_mfma_f32_16x16x32_bf16 v[110:113], v[130:133], v[204:207], v[110:113]
	v_mfma_f32_16x16x32_bf16 v[106:109], v[138:141], v[204:207], v[106:109]
	v_mfma_f32_16x16x32_bf16 v[94:97], v[130:133], v[212:215], v[94:97]
	v_mfma_f32_16x16x32_bf16 v[90:93], v[138:141], v[212:215], v[90:93]
	v_mfma_f32_16x16x32_bf16 v[78:81], v[130:133], v[220:223], v[78:81]
	v_mfma_f32_16x16x32_bf16 v[74:77], v[138:141], v[220:223], v[74:77]
	v_mfma_f32_16x16x32_bf16 v[126:129], v[134:137], v[200:203], v[126:129]
	v_mfma_f32_16x16x32_bf16 v[122:125], v[142:145], v[200:203], v[122:125]
	v_mfma_f32_16x16x32_bf16 v[110:113], v[134:137], v[208:211], v[110:113]
	v_mfma_f32_16x16x32_bf16 v[106:109], v[142:145], v[208:211], v[106:109]
	v_mfma_f32_16x16x32_bf16 v[94:97], v[134:137], v[216:219], v[94:97]
	v_mfma_f32_16x16x32_bf16 v[90:93], v[142:145], v[216:219], v[90:93]
	v_mfma_f32_16x16x32_bf16 v[78:81], v[134:137], v[224:227], v[78:81]
	v_mfma_f32_16x16x32_bf16 v[74:77], v[142:145], v[224:227], v[74:77]
	v_mfma_f32_16x16x32_bf16 v[118:121], v[146:149], v[188:191], v[118:121]
	v_mfma_f32_16x16x32_bf16 v[114:117], v[154:157], v[188:191], v[114:117]
	v_mfma_f32_16x16x32_bf16 v[102:105], v[146:149], v[204:207], v[102:105]
	v_mfma_f32_16x16x32_bf16 v[98:101], v[154:157], v[204:207], v[98:101]
	v_mfma_f32_16x16x32_bf16 v[86:89], v[146:149], v[212:215], v[86:89]
	v_mfma_f32_16x16x32_bf16 v[82:85], v[154:157], v[212:215], v[82:85]
	v_mfma_f32_16x16x32_bf16 v[70:73], v[146:149], v[220:223], v[70:73]
	v_mfma_f32_16x16x32_bf16 v[66:69], v[154:157], v[220:223], v[66:69]
	v_mfma_f32_16x16x32_bf16 v[118:121], v[150:153], v[200:203], v[118:121]
	v_mfma_f32_16x16x32_bf16 v[114:117], v[184:187], v[200:203], v[114:117]
	v_mfma_f32_16x16x32_bf16 v[102:105], v[150:153], v[208:211], v[102:105]
	v_mfma_f32_16x16x32_bf16 v[98:101], v[184:187], v[208:211], v[98:101]
	v_mfma_f32_16x16x32_bf16 v[86:89], v[150:153], v[216:219], v[86:89]
	v_mfma_f32_16x16x32_bf16 v[82:85], v[184:187], v[216:219], v[82:85]
	v_mfma_f32_16x16x32_bf16 v[70:73], v[150:153], v[224:227], v[70:73]
	v_mfma_f32_16x16x32_bf16 v[66:69], v[184:187], v[224:227], v[66:69]
	s_barrier
	s_add_i32 s92, s15, s53
	v_lshl_add_u64 v[196:197], s[4:5], 0, v[160:161]
	s_mov_b32 m0, s92
	ds_read_b128 v[188:191], v195 offset:16384
	ds_read_b128 v[200:203], v195 offset:17408
	ds_read_b128 v[204:207], v195 offset:18432
	ds_read_b128 v[208:211], v195 offset:19456
	ds_read_b128 v[212:215], v195 offset:20480
	ds_read_b128 v[216:219], v195 offset:21504
	ds_read_b128 v[220:223], v195 offset:22528
	ds_read_b128 v[224:227], v195 offset:23552
	global_load_lds_dwordx4 v[196:197], off
	s_add_i32 m0, s92, 0x2000
	s_add_u32 s92, s4, 0x80000
	v_lshl_add_u64 v[228:229], s[4:5], 0, v[164:165]
	s_addc_u32 s93, s5, 0
	s_add_i32 s94, s81, s53
	global_load_lds_dwordx4 v[228:229], off
	v_lshl_add_u64 v[230:231], s[92:93], 0, v[160:161]
	s_mov_b32 m0, s94
	v_lshl_add_u64 v[232:233], s[48:49], 0, v[162:163]
	global_load_lds_dwordx4 v[230:231], off
	v_lshl_add_u64 v[230:231], s[92:93], 0, v[164:165]
	s_add_i32 m0, s94, 0x2000
	s_nop 0
	global_load_lds_dwordx4 v[230:231], off
	v_lshl_add_u64 v[230:231], s[48:49], 0, v[158:159]
	s_mov_b32 m0, s54
	s_nop 0
	global_load_lds_dwordx4 v[230:231], off
	s_mov_b32 m0, s55
	s_nop 0
	global_load_lds_dwordx4 v[232:233], off
	s_waitcnt vmcnt(8)
	s_waitcnt lgkmcnt(0)
	s_barrier
; #define PG8_STAGE(bufoff, gbase, voff) do { _Pragma("unroll") for (int _i = 0; _i < 2; ++_i) \
;         __builtin_amdgcn_global_load_lds((const unsigned*)((const char*)(gbase) + (voff)[_i]), (PG8_LAS unsigned*)(lds + (bufoff) + ldsw + _i * 8192), 16, 0, 0); } while (0)
; #define PG8_LDA(dst, b, h) do { _Pragma("unroll") for (int m = 0; m < 4; ++m) _Pragma("unroll") for (int k = 0; k < 2; ++k) dst[m][k] = *(const PG8_LAS bf16x8*)(lds + PG8_SA(b, h) + aoff + m * 2048 + k * 1024); } while (0)
; #define PG8_LDB(dst, b, h) do { _Pragma("unroll") for (int n = 0; n < 2; ++n) _Pragma("unroll") for (int k = 0; k < 2; ++k) dst[n][k] = *(const PG8_LAS bf16x8*)(lds + PG8_SB(b, h) + boff + n * 2048 + k * 1024); } while (0)
; #define PG8_MMA(ai, bj, At, Bt) do { __builtin_amdgcn_s_setprio(1); _Pragma("unroll") for (int m = 0; m < 4; ++m) _Pragma("unroll") for (int n = 0; n < 2; ++n) _Pragma("unroll") for (int k = 0; k < 2; ++k) \
;         acc[ai][bj][m][n] = __builtin_amdgcn_mfma_f32_16x16x32_bf16(Bt[n][k], At[m][k], acc[ai][bj][m][n], 0, 0, 0); __builtin_amdgcn_s_setprio(0); } while (0)
; #define PG8_BAR __builtin_amdgcn_s_barrier()
; template <class Epi, class Sched, bool ALIGN_EPI = false, bool SP2 = false, bool MID = false>
; __device__ __forceinline__ void gemm_phase(PG8_LAS unsigned char* lds, const Gemm g, const Sched& S, const Epi& E) {
;     ...
;             PG8_LDB(B0, 0, 0); PG8_LDB(B1, 0, 1); PG8_SCHED; PG8_LDA(At, 0, 0); PG8_STAGE(PG8_SA(1, 1), a1 + hstep, voffA);
;             PG8_WAIT_V(8); PG8_WAIT_L(0); PG8_BAR; PG8_MMA(0, 0, At, B0); PG8_MMA(0, 1, At, B1); PG8_BAR; PG8_SCHED;
;             PG8_LDA(At, 0, 1); PG8_STAGE(PG8_SB(0, 0), b2, voffB); PG8_STAGE(PG8_SB(0, 1), b2 + hstep, voffB); PG8_STAGE(PG8_SA(0, 0), a2, voffA);
;             PG8_WAIT_V(8); PG8_WAIT_L(0); PG8_BAR; PG8_MMA(1, 0, At, B0); PG8_MMA(1, 1, At, B1); PG8_BAR; PG8_SCHED;
;             PG8_LDB(B0, 1, 0); PG8_LDB(B1, 1, 1); PG8_SCHED; PG8_LDA(At, 1, 0); PG8_STAGE(PG8_SA(0, 1), a2 + hstep, voffA);
;             PG8_WAIT_V(8); PG8_WAIT_L(0); PG8_BAR; PG8_MMA(0, 0, At, B0); PG8_MMA(0, 1, At, B1); PG8_BAR; PG8_SCHED;
;             PG8_LDA(At, 1, 1); PG8_STAGE(PG8_SB(1, 0), b3, voffB); PG8_STAGE(PG8_SB(1, 1), b3 + hstep, voffB); PG8_STAGE(PG8_SA(1, 0), a3, voffA);
;             PG8_WAIT_V(8); PG8_WAIT_L(0); PG8_BAR; PG8_MMA(1, 0, At, B0); PG8_MMA(1, 1, At, B1); PG8_BAR; PG8_SCHED;
	s_waitcnt lgkmcnt(0)
	v_mfma_f32_16x16x32_bf16 v[62:65], v[130:133], v[188:191], v[62:65]
	v_mfma_f32_16x16x32_bf16 v[58:61], v[138:141], v[188:191], v[58:61]
	v_mfma_f32_16x16x32_bf16 v[46:49], v[130:133], v[204:207], v[46:49]
	v_mfma_f32_16x16x32_bf16 v[42:45], v[138:141], v[204:207], v[42:45]
	v_mfma_f32_16x16x32_bf16 v[30:33], v[130:133], v[212:215], v[30:33]
	v_mfma_f32_16x16x32_bf16 v[26:29], v[138:141], v[212:215], v[26:29]
	v_mfma_f32_16x16x32_bf16 v[14:17], v[130:133], v[220:223], v[14:17]
	v_mfma_f32_16x16x32_bf16 v[10:13], v[138:141], v[220:223], v[10:13]
	v_mfma_f32_16x16x32_bf16 v[62:65], v[134:137], v[200:203], v[62:65]
	v_mfma_f32_16x16x32_bf16 v[58:61], v[142:145], v[200:203], v[58:61]
	v_mfma_f32_16x16x32_bf16 v[46:49], v[134:137], v[208:211], v[46:49]
	v_mfma_f32_16x16x32_bf16 v[42:45], v[142:145], v[208:211], v[42:45]
	v_mfma_f32_16x16x32_bf16 v[30:33], v[134:137], v[216:219], v[30:33]
	v_mfma_f32_16x16x32_bf16 v[26:29], v[142:145], v[216:219], v[26:29]
	v_mfma_f32_16x16x32_bf16 v[14:17], v[134:137], v[224:227], v[14:17]
	v_mfma_f32_16x16x32_bf16 v[10:13], v[142:145], v[224:227], v[10:13]
	v_mfma_f32_16x16x32_bf16 v[54:57], v[146:149], v[188:191], v[54:57]
	v_mfma_f32_16x16x32_bf16 v[50:53], v[154:157], v[188:191], v[50:53]
	v_mfma_f32_16x16x32_bf16 v[38:41], v[146:149], v[204:207], v[38:41]
	v_mfma_f32_16x16x32_bf16 v[34:37], v[154:157], v[204:207], v[34:37]
	v_mfma_f32_16x16x32_bf16 v[22:25], v[146:149], v[212:215], v[22:25]
	v_mfma_f32_16x16x32_bf16 v[18:21], v[154:157], v[212:215], v[18:21]
	v_mfma_f32_16x16x32_bf16 v[6:9], v[146:149], v[220:223], v[6:9]
	v_mfma_f32_16x16x32_bf16 v[2:5], v[154:157], v[220:223], v[2:5]
	v_mfma_f32_16x16x32_bf16 v[54:57], v[150:153], v[200:203], v[54:57]
	v_mfma_f32_16x16x32_bf16 v[50:53], v[184:187], v[200:203], v[50:53]
	v_mfma_f32_16x16x32_bf16 v[38:41], v[150:153], v[208:211], v[38:41]
	v_mfma_f32_16x16x32_bf16 v[34:37], v[184:187], v[208:211], v[34:37]
	v_mfma_f32_16x16x32_bf16 v[22:25], v[150:153], v[216:219], v[22:25]
	v_mfma_f32_16x16x32_bf16 v[18:21], v[184:187], v[216:219], v[18:21]
	v_mfma_f32_16x16x32_bf16 v[6:9], v[150:153], v[224:227], v[6:9]
	v_mfma_f32_16x16x32_bf16 v[2:5], v[184:187], v[224:227], v[2:5]
	s_barrier
	s_add_i32 s92, 0, 0x18000
	s_add_i32 s93, 0, 0x1c000
	v_add_u32_e32 v142, s92, v193
	v_add_u32_e32 v175, s93, v193
	ds_read_b128 v[130:133], v142
	ds_read_b128 v[134:137], v142 offset:1024
	ds_read_b128 v[138:141], v142 offset:2048
	ds_read_b128 v[142:145], v142 offset:3072
	ds_read_b128 v[146:149], v175
	ds_read_b128 v[150:153], v175 offset:1024
	ds_read_b128 v[154:157], v175 offset:2048
	ds_read_b128 v[184:187], v175 offset:3072
	s_add_u32 s48, s48, 0x80000
	s_addc_u32 s49, s49, 0
	s_mov_b32 m0, s56
	v_lshl_add_u64 v[234:235], s[48:49], 0, v[158:159]
	ds_read_b128 v[188:191], v195 offset:32768
	ds_read_b128 v[200:203], v195 offset:33792
	ds_read_b128 v[204:207], v195 offset:34816
	ds_read_b128 v[208:211], v195 offset:35840
	ds_read_b128 v[212:215], v195 offset:36864
	ds_read_b128 v[216:219], v195 offset:37888
	ds_read_b128 v[220:223], v195 offset:38912
	ds_read_b128 v[224:227], v195 offset:39936
	global_load_lds_dwordx4 v[234:235], off
	v_lshl_add_u64 v[234:235], s[48:49], 0, v[162:163]
	s_mov_b32 m0, s57
	s_nop 0
	global_load_lds_dwordx4 v[234:235], off
	s_waitcnt vmcnt(8)
	s_waitcnt lgkmcnt(0)
	s_barrier
	s_waitcnt lgkmcnt(0)
	v_mfma_f32_16x16x32_bf16 v[126:129], v[130:133], v[188:191], v[126:129]
	v_mfma_f32_16x16x32_bf16 v[122:125], v[138:141], v[188:191], v[122:125]
	v_mfma_f32_16x16x32_bf16 v[110:113], v[130:133], v[204:207], v[110:113]
	v_mfma_f32_16x16x32_bf16 v[106:109], v[138:141], v[204:207], v[106:109]
	v_mfma_f32_16x16x32_bf16 v[94:97], v[130:133], v[212:215], v[94:97]
	v_mfma_f32_16x16x32_bf16 v[90:93], v[138:141], v[212:215], v[90:93]
	v_mfma_f32_16x16x32_bf16 v[78:81], v[130:133], v[220:223], v[78:81]
	v_mfma_f32_16x16x32_bf16 v[74:77], v[138:141], v[220:223], v[74:77]
	v_mfma_f32_16x16x32_bf16 v[126:129], v[134:137], v[200:203], v[126:129]
	v_mfma_f32_16x16x32_bf16 v[122:125], v[142:145], v[200:203], v[122:125]
	v_mfma_f32_16x16x32_bf16 v[110:113], v[134:137], v[208:211], v[110:113]
	v_mfma_f32_16x16x32_bf16 v[106:109], v[142:145], v[208:211], v[106:109]
	v_mfma_f32_16x16x32_bf16 v[94:97], v[134:137], v[216:219], v[94:97]
	v_mfma_f32_16x16x32_bf16 v[90:93], v[142:145], v[216:219], v[90:93]
	v_mfma_f32_16x16x32_bf16 v[78:81], v[134:137], v[224:227], v[78:81]
	v_mfma_f32_16x16x32_bf16 v[74:77], v[142:145], v[224:227], v[74:77]
	v_mfma_f32_16x16x32_bf16 v[118:121], v[146:149], v[188:191], v[118:121]
	v_mfma_f32_16x16x32_bf16 v[114:117], v[154:157], v[188:191], v[114:117]
	v_mfma_f32_16x16x32_bf16 v[102:105], v[146:149], v[204:207], v[102:105]
	v_mfma_f32_16x16x32_bf16 v[98:101], v[154:157], v[204:207], v[98:101]
	v_mfma_f32_16x16x32_bf16 v[86:89], v[146:149], v[212:215], v[86:89]
	v_mfma_f32_16x16x32_bf16 v[82:85], v[154:157], v[212:215], v[82:85]
	v_mfma_f32_16x16x32_bf16 v[70:73], v[146:149], v[220:223], v[70:73]
	v_mfma_f32_16x16x32_bf16 v[66:69], v[154:157], v[220:223], v[66:69]
	v_mfma_f32_16x16x32_bf16 v[118:121], v[150:153], v[200:203], v[118:121]
	v_mfma_f32_16x16x32_bf16 v[114:117], v[184:187], v[200:203], v[114:117]
	v_mfma_f32_16x16x32_bf16 v[102:105], v[150:153], v[208:211], v[102:105]
	v_mfma_f32_16x16x32_bf16 v[98:101], v[184:187], v[208:211], v[98:101]
	v_mfma_f32_16x16x32_bf16 v[86:89], v[150:153], v[216:219], v[86:89]
	v_mfma_f32_16x16x32_bf16 v[82:85], v[184:187], v[216:219], v[82:85]
	v_mfma_f32_16x16x32_bf16 v[70:73], v[150:153], v[224:227], v[70:73]
	v_mfma_f32_16x16x32_bf16 v[66:69], v[184:187], v[224:227], v[66:69]
	s_barrier
; #define PG8_STAGE(bufoff, gbase, voff) do { _Pragma("unroll") for (int _i = 0; _i < 2; ++_i) \
;         __builtin_amdgcn_global_load_lds((const unsigned*)((const char*)(gbase) + (voff)[_i]), (PG8_LAS unsigned*)(lds + (bufoff) + ldsw + _i * 8192), 16, 0, 0); } while (0)
; #define PG8_LDA(dst, b, h) do { _Pragma("unroll") for (int m = 0; m < 4; ++m) _Pragma("unroll") for (int k = 0; k < 2; ++k) dst[m][k] = *(const PG8_LAS bf16x8*)(lds + PG8_SA(b, h) + aoff + m * 2048 + k * 1024); } while (0)
; #define PG8_WAIT_V(n) asm volatile("s_waitcnt vmcnt(" #n ")" ::: "memory")
; template <class Epi, class Sched, bool ALIGN_EPI = false, bool SP2 = false, bool MID = false>
; __device__ __forceinline__ void gemm_phase(PG8_LAS unsigned char* lds, const Gemm g, const Sched& S, const Epi& E) {
;     ...
;         for (int t = 0; t < nt; t += 2) {
;             const bool last = (t == nt - 2);
;             if constexpr (MID) { if (t == Epi::MID_T) { PG8_SCHED; E.mid(acc, cur, wr, wc, fr, fq); PG8_SCHED; } }
;             const char* a1 = cA + (size_t)(t + 1) * kstep;
;             const char* a2 = last ? nA : cA + (size_t)(t + 2) * kstep; const char* b2 = last ? nB : cB + (size_t)(t + 2) * kstep;
;             const char* a3 = a2 + kstep; const char* b3 = b2 + kstep;
;             if (last && has_next) S.a_ready(nxt);
;             if constexpr (SP2) {
;             PG8_LDB(B0, 0, 0); PG8_LDB(B1, 0, 1); PG8_SCHED; PG8_LDA(At, 0, 0); PG8_STAGE(PG8_SA(1, 1), a1 + hstep, voffA);
;             PG8_WAIT_V(8); PG8_WAIT_L(0); PG8_BAR; PG8_MMA(0, 0, At, B0); PG8_MMA(0, 1, At, B1); PG8_BAR; PG8_SCHED;
;             PG8_LDA(At, 0, 1); PG8_STAGE(PG8_SB(0, 0), b2, voffB); PG8_STAGE(PG8_SB(0, 1), b2 + hstep, voffB); PG8_STAGE(PG8_SA(0, 0), a2, voffA);
;             PG8_WAIT_V(8); PG8_WAIT_L(0); PG8_BAR; PG8_MMA(1, 0, At, B0); PG8_MMA(1, 1, At, B1); PG8_BAR; PG8_SCHED;
;             PG8_LDB(B0, 1, 0); PG8_LDB(B1, 1, 1); PG8_SCHED; PG8_LDA(At, 1, 0); PG8_STAGE(PG8_SA(0, 1), a2 + hstep, voffA);
;             PG8_WAIT_V(8); PG8_WAIT_L(0); PG8_BAR; PG8_MMA(0, 0, At, B0); PG8_MMA(0, 1, At, B1); PG8_BAR; PG8_SCHED;
;             PG8_LDA(At, 1, 1); PG8_STAGE(PG8_SB(1, 0), b3, voffB); PG8_STAGE(PG8_SB(1, 1), b3 + hstep, voffB); PG8_STAGE(PG8_SA(1, 0), a3, voffA);
;             PG8_WAIT_V(8); PG8_WAIT_L(0); PG8_BAR; PG8_MMA(1, 0, At, B0); PG8_MMA(1, 1, At, B1); PG8_BAR; PG8_SCHED;
	s_add_i32 s48, s92, s53
	v_lshl_add_u64 v[196:197], v[196:197], 0, s[20:21]
	s_mov_b32 m0, s48
	ds_read_b128 v[188:191], v195 offset:49152
	ds_read_b128 v[200:203], v195 offset:50176
	ds_read_b128 v[204:207], v195 offset:51200
	ds_read_b128 v[208:211], v195 offset:52224
	ds_read_b128 v[212:215], v195 offset:53248
	ds_read_b128 v[216:219], v195 offset:54272
	ds_read_b128 v[220:223], v195 offset:55296
	ds_read_b128 v[224:227], v195 offset:56320
	global_load_lds_dwordx4 v[196:197], off
	s_add_i32 m0, s48, 0x2000
	s_add_u32 s4, s4, 0x80080
	v_lshl_add_u64 v[196:197], v[228:229], 0, s[20:21]
	s_addc_u32 s5, s5, 0
	s_add_i32 s48, s93, s53
	global_load_lds_dwordx4 v[196:197], off
	v_lshl_add_u64 v[196:197], s[4:5], 0, v[160:161]
	s_mov_b32 m0, s48
	s_nop 0
	global_load_lds_dwordx4 v[196:197], off
	v_lshl_add_u64 v[196:197], s[4:5], 0, v[164:165]
	s_add_i32 m0, s48, 0x2000
	s_nop 0
	global_load_lds_dwordx4 v[196:197], off
	v_lshl_add_u64 v[196:197], v[230:231], 0, s[20:21]
	s_mov_b32 m0, s59
	s_nop 0
	global_load_lds_dwordx4 v[196:197], off
	v_lshl_add_u64 v[196:197], v[232:233], 0, s[20:21]
	s_mov_b32 m0, s62
	s_nop 0
	global_load_lds_dwordx4 v[196:197], off
	s_waitcnt vmcnt(8)
	s_waitcnt lgkmcnt(0)
	s_barrier
	s_waitcnt lgkmcnt(0)
	v_mfma_f32_16x16x32_bf16 v[62:65], v[130:133], v[188:191], v[62:65]
	v_mfma_f32_16x16x32_bf16 v[58:61], v[138:141], v[188:191], v[58:61]
	v_mfma_f32_16x16x32_bf16 v[46:49], v[130:133], v[204:207], v[46:49]
	v_mfma_f32_16x16x32_bf16 v[42:45], v[138:141], v[204:207], v[42:45]
	v_mfma_f32_16x16x32_bf16 v[30:33], v[130:133], v[212:215], v[30:33]
	v_mfma_f32_16x16x32_bf16 v[26:29], v[138:141], v[212:215], v[26:29]
	v_mfma_f32_16x16x32_bf16 v[14:17], v[130:133], v[220:223], v[14:17]
	v_mfma_f32_16x16x32_bf16 v[10:13], v[138:141], v[220:223], v[10:13]
	v_mfma_f32_16x16x32_bf16 v[62:65], v[134:137], v[200:203], v[62:65]
	v_mfma_f32_16x16x32_bf16 v[58:61], v[142:145], v[200:203], v[58:61]
	v_mfma_f32_16x16x32_bf16 v[46:49], v[134:137], v[208:211], v[46:49]
	v_mfma_f32_16x16x32_bf16 v[42:45], v[142:145], v[208:211], v[42:45]
	v_mfma_f32_16x16x32_bf16 v[30:33], v[134:137], v[216:219], v[30:33]
	v_mfma_f32_16x16x32_bf16 v[26:29], v[142:145], v[216:219], v[26:29]
	v_mfma_f32_16x16x32_bf16 v[14:17], v[134:137], v[224:227], v[14:17]
	v_mfma_f32_16x16x32_bf16 v[10:13], v[142:145], v[224:227], v[10:13]
	v_mfma_f32_16x16x32_bf16 v[54:57], v[146:149], v[188:191], v[54:57]
	v_mfma_f32_16x16x32_bf16 v[50:53], v[154:157], v[188:191], v[50:53]
	v_mfma_f32_16x16x32_bf16 v[38:41], v[146:149], v[204:207], v[38:41]
	v_mfma_f32_16x16x32_bf16 v[34:37], v[154:157], v[204:207], v[34:37]
	v_mfma_f32_16x16x32_bf16 v[22:25], v[146:149], v[212:215], v[22:25]
	v_mfma_f32_16x16x32_bf16 v[18:21], v[154:157], v[212:215], v[18:21]
	v_mfma_f32_16x16x32_bf16 v[6:9], v[146:149], v[220:223], v[6:9]
	v_mfma_f32_16x16x32_bf16 v[2:5], v[154:157], v[220:223], v[2:5]
	v_mfma_f32_16x16x32_bf16 v[54:57], v[150:153], v[200:203], v[54:57]
	v_mfma_f32_16x16x32_bf16 v[50:53], v[184:187], v[200:203], v[50:53]
	v_mfma_f32_16x16x32_bf16 v[38:41], v[150:153], v[208:211], v[38:41]
	v_mfma_f32_16x16x32_bf16 v[34:37], v[184:187], v[208:211], v[34:37]
	v_mfma_f32_16x16x32_bf16 v[22:25], v[150:153], v[216:219], v[22:25]
	v_mfma_f32_16x16x32_bf16 v[18:21], v[184:187], v[216:219], v[18:21]
	v_mfma_f32_16x16x32_bf16 v[6:9], v[150:153], v[224:227], v[6:9]
	v_mfma_f32_16x16x32_bf16 v[2:5], v[184:187], v[224:227], v[2:5]
	s_barrier
	s_add_i32 s91, s91, 2
	s_add_u32 s46, s46, 0x100
	s_addc_u32 s47, s47, 0
	s_cmp_gt_u32 s91, 29
	s_cbranch_scc1 .LBB0_1442

; #define PG8_STAGE(bufoff, gbase, voff) do { _Pragma("unroll") for (int _i = 0; _i < 2; ++_i) \
;         __builtin_amdgcn_global_load_lds((const unsigned*)((const char*)(gbase) + (voff)[_i]), (PG8_LAS unsigned*)(lds + (bufoff) + ldsw + _i * 8192), 16, 0, 0); } while (0)
; #define PG8_LDA(dst, b, h) do { _Pragma("unroll") for (int m = 0; m < 4; ++m) _Pragma("unroll") for (int k = 0; k < 2; ++k) dst[m][k] = *(const PG8_LAS bf16x8*)(lds + PG8_SA(b, h) + aoff + m * 2048 + k * 1024); } while (0)
; #define PG8_LDB(dst, b, h) do { _Pragma("unroll") for (int n = 0; n < 2; ++n) _Pragma("unroll") for (int k = 0; k < 2; ++k) dst[n][k] = *(const PG8_LAS bf16x8*)(lds + PG8_SB(b, h) + boff + n * 2048 + k * 1024); } while (0)
; #define PG8_MMA(ai, bj, At, Bt) do { __builtin_amdgcn_s_setprio(1); _Pragma("unroll") for (int m = 0; m < 4; ++m) _Pragma("unroll") for (int n = 0; n < 2; ++n) _Pragma("unroll") for (int k = 0; k < 2; ++k) \
;         acc[ai][bj][m][n] = __builtin_amdgcn_mfma_f32_16x16x32_bf16(Bt[n][k], At[m][k], acc[ai][bj][m][n], 0, 0, 0); __builtin_amdgcn_s_setprio(0); } while (0)
; #define PG8_BAR __builtin_amdgcn_s_barrier()
; template <class Epi, class Sched, bool ALIGN_EPI = false, bool SP2 = false, bool MID = false>
; __device__ __forceinline__ void gemm_phase(PG8_LAS unsigned char* lds, const Gemm g, const Sched& S, const Epi& E) {
;     ...
;             PG8_LDB(B0, 0, 0); PG8_LDB(B1, 0, 1); PG8_SCHED; PG8_LDA(At, 0, 0); PG8_STAGE(PG8_SA(1, 1), a1 + hstep, voffA);
;             PG8_WAIT_V(8); PG8_WAIT_L(0); PG8_BAR; PG8_MMA(0, 0, At, B0); PG8_MMA(0, 1, At, B1); PG8_BAR; PG8_SCHED;
;             PG8_LDA(At, 0, 1); PG8_STAGE(PG8_SB(0, 0), b2, voffB); PG8_STAGE(PG8_SB(0, 1), b2 + hstep, voffB); PG8_STAGE(PG8_SA(0, 0), a2, voffA);
;             PG8_WAIT_V(8); PG8_WAIT_L(0); PG8_BAR; PG8_MMA(1, 0, At, B0); PG8_MMA(1, 1, At, B1); PG8_BAR; PG8_SCHED;
;             PG8_LDB(B0, 1, 0); PG8_LDB(B1, 1, 1); PG8_SCHED; PG8_LDA(At, 1, 0); PG8_STAGE(PG8_SA(0, 1), a2 + hstep, voffA);
;             PG8_WAIT_V(8); PG8_WAIT_L(0); PG8_BAR; PG8_MMA(0, 0, At, B0); PG8_MMA(0, 1, At, B1); PG8_BAR; PG8_SCHED;
;             PG8_LDA(At, 1, 1); PG8_STAGE(PG8_SB(1, 0), b3, voffB); PG8_STAGE(PG8_SB(1, 1), b3 + hstep, voffB); PG8_STAGE(PG8_SA(1, 0), a3, voffA);
;             PG8_WAIT_V(8); PG8_WAIT_L(0); PG8_BAR; PG8_MMA(1, 0, At, B0); PG8_MMA(1, 1, At, B1); PG8_BAR; PG8_SCHED;
.LBB0_1528:
	ds_read_b128 v[152:155], v149
	ds_read_b128 v[156:159], v149 offset:1024
	ds_read_b128 v[160:163], v149 offset:2048
	ds_read_b128 v[164:167], v149 offset:3072
	ds_read_b128 v[168:171], v150
	ds_read_b128 v[172:175], v150 offset:1024
	ds_read_b128 v[176:179], v150 offset:2048
	ds_read_b128 v[180:183], v150 offset:3072
	s_add_u32 s50, s48, 0xfff80080
	s_addc_u32 s51, s49, -1
	s_cmp_eq_u32 s81, 28
	s_cselect_b32 s55, s41, s51
	s_cselect_b32 s54, s77, s50
	s_cselect_b32 s51, s39, s80
	s_cselect_b32 s50, s78, s79
	v_lshl_add_u64 v[196:197], s[48:49], 0, v[138:139]
	s_add_i32 m0, s37, 0xc000
	ds_read_b128 v[184:187], v151
	ds_read_b128 v[188:191], v151 offset:1024
	ds_read_b128 v[192:195], v151 offset:2048
	ds_read_b128 v[200:203], v151 offset:3072
	ds_read_b128 v[204:207], v151 offset:4096
	ds_read_b128 v[208:211], v151 offset:5120
	ds_read_b128 v[212:215], v151 offset:6144
	ds_read_b128 v[216:219], v151 offset:7168
	global_load_lds_dwordx4 v[196:197], off
	v_lshl_add_u64 v[196:197], s[48:49], 0, v[140:141]
	s_add_i32 m0, s37, 0xe000
	s_nop 0
	global_load_lds_dwordx4 v[196:197], off
	s_waitcnt vmcnt(8)
	s_waitcnt lgkmcnt(0)
	s_barrier
	s_waitcnt lgkmcnt(0)
	v_mfma_f32_16x16x32_bf16 v[126:129], v[152:155], v[184:187], v[126:129]
	v_mfma_f32_16x16x32_bf16 v[122:125], v[160:163], v[184:187], v[122:125]
	v_mfma_f32_16x16x32_bf16 v[118:121], v[152:155], v[192:195], v[118:121]
	v_mfma_f32_16x16x32_bf16 v[114:117], v[160:163], v[192:195], v[114:117]
	v_mfma_f32_16x16x32_bf16 v[102:105], v[152:155], v[204:207], v[102:105]
	v_mfma_f32_16x16x32_bf16 v[98:101], v[160:163], v[204:207], v[98:101]
	v_mfma_f32_16x16x32_bf16 v[86:89], v[152:155], v[212:215], v[86:89]
	v_mfma_f32_16x16x32_bf16 v[82:85], v[160:163], v[212:215], v[82:85]
	v_mfma_f32_16x16x32_bf16 v[126:129], v[156:159], v[188:191], v[126:129]
	v_mfma_f32_16x16x32_bf16 v[122:125], v[164:167], v[188:191], v[122:125]
	v_mfma_f32_16x16x32_bf16 v[118:121], v[156:159], v[200:203], v[118:121]
	v_mfma_f32_16x16x32_bf16 v[114:117], v[164:167], v[200:203], v[114:117]
	v_mfma_f32_16x16x32_bf16 v[102:105], v[156:159], v[208:211], v[102:105]
	v_mfma_f32_16x16x32_bf16 v[98:101], v[164:167], v[208:211], v[98:101]
	v_mfma_f32_16x16x32_bf16 v[86:89], v[156:159], v[216:219], v[86:89]
	v_mfma_f32_16x16x32_bf16 v[82:85], v[164:167], v[216:219], v[82:85]
	v_mfma_f32_16x16x32_bf16 v[110:113], v[168:171], v[184:187], v[110:113]
	v_mfma_f32_16x16x32_bf16 v[106:109], v[176:179], v[184:187], v[106:109]
	v_mfma_f32_16x16x32_bf16 v[94:97], v[168:171], v[192:195], v[94:97]
	v_mfma_f32_16x16x32_bf16 v[90:93], v[176:179], v[192:195], v[90:93]
	v_mfma_f32_16x16x32_bf16 v[78:81], v[168:171], v[204:207], v[78:81]
	v_mfma_f32_16x16x32_bf16 v[74:77], v[176:179], v[204:207], v[74:77]
	v_mfma_f32_16x16x32_bf16 v[70:73], v[168:171], v[212:215], v[70:73]
	v_mfma_f32_16x16x32_bf16 v[66:69], v[176:179], v[212:215], v[66:69]
	v_mfma_f32_16x16x32_bf16 v[110:113], v[172:175], v[188:191], v[110:113]
	v_mfma_f32_16x16x32_bf16 v[106:109], v[180:183], v[188:191], v[106:109]
	v_mfma_f32_16x16x32_bf16 v[94:97], v[172:175], v[200:203], v[94:97]
	v_mfma_f32_16x16x32_bf16 v[90:93], v[180:183], v[200:203], v[90:93]
	v_mfma_f32_16x16x32_bf16 v[78:81], v[172:175], v[208:211], v[78:81]
	v_mfma_f32_16x16x32_bf16 v[74:77], v[180:183], v[208:211], v[74:77]
	v_mfma_f32_16x16x32_bf16 v[70:73], v[172:175], v[216:219], v[70:73]
	v_mfma_f32_16x16x32_bf16 v[66:69], v[180:183], v[216:219], v[66:69]
	s_barrier
	s_add_i32 s82, s70, s15
	v_lshl_add_u64 v[196:197], s[50:51], 0, v[132:133]
	s_mov_b32 m0, s82
	ds_read_b128 v[184:187], v151 offset:16384
	ds_read_b128 v[188:191], v151 offset:17408
	ds_read_b128 v[192:195], v151 offset:18432
	ds_read_b128 v[200:203], v151 offset:19456
	ds_read_b128 v[204:207], v151 offset:20480
	ds_read_b128 v[208:211], v151 offset:21504
	ds_read_b128 v[212:215], v151 offset:22528
	ds_read_b128 v[216:219], v151 offset:23552
	global_load_lds_dwordx4 v[196:197], off
	s_add_i32 m0, s82, 0x2000
	s_add_u32 s82, s50, 0x80000
	v_lshl_add_u64 v[220:221], s[50:51], 0, v[136:137]
	s_addc_u32 s83, s51, 0
	s_add_i32 s84, s71, s15
	global_load_lds_dwordx4 v[220:221], off
	v_lshl_add_u64 v[222:223], s[82:83], 0, v[132:133]
	s_mov_b32 m0, s84
	v_lshl_add_u64 v[224:225], s[54:55], 0, v[134:135]
	global_load_lds_dwordx4 v[222:223], off
	v_lshl_add_u64 v[222:223], s[82:83], 0, v[136:137]
	s_add_i32 m0, s84, 0x2000
	s_nop 0
	global_load_lds_dwordx4 v[222:223], off
	v_lshl_add_u64 v[222:223], s[54:55], 0, v[130:131]
	s_mov_b32 m0, s37
	s_nop 0
	global_load_lds_dwordx4 v[222:223], off
	s_mov_b32 m0, s52
	s_nop 0
	global_load_lds_dwordx4 v[224:225], off
	s_waitcnt vmcnt(8)
	s_waitcnt lgkmcnt(0)
	s_barrier
; #define PG8_STAGE(bufoff, gbase, voff) do { _Pragma("unroll") for (int _i = 0; _i < 2; ++_i) \
;         __builtin_amdgcn_global_load_lds((const unsigned*)((const char*)(gbase) + (voff)[_i]), (PG8_LAS unsigned*)(lds + (bufoff) + ldsw + _i * 8192), 16, 0, 0); } while (0)
; #define PG8_LDA(dst, b, h) do { _Pragma("unroll") for (int m = 0; m < 4; ++m) _Pragma("unroll") for (int k = 0; k < 2; ++k) dst[m][k] = *(const PG8_LAS bf16x8*)(lds + PG8_SA(b, h) + aoff + m * 2048 + k * 1024); } while (0)
; #define PG8_LDB(dst, b, h) do { _Pragma("unroll") for (int n = 0; n < 2; ++n) _Pragma("unroll") for (int k = 0; k < 2; ++k) dst[n][k] = *(const PG8_LAS bf16x8*)(lds + PG8_SB(b, h) + boff + n * 2048 + k * 1024); } while (0)
; #define PG8_MMA(ai, bj, At, Bt) do { __builtin_amdgcn_s_setprio(1); _Pragma("unroll") for (int m = 0; m < 4; ++m) _Pragma("unroll") for (int n = 0; n < 2; ++n) _Pragma("unroll") for (int k = 0; k < 2; ++k) \
;         acc[ai][bj][m][n] = __builtin_amdgcn_mfma_f32_16x16x32_bf16(Bt[n][k], At[m][k], acc[ai][bj][m][n], 0, 0, 0); __builtin_amdgcn_s_setprio(0); } while (0)
; #define PG8_BAR __builtin_amdgcn_s_barrier()
; template <class Epi, class Sched, bool ALIGN_EPI = false, bool SP2 = false, bool MID = false>
; __device__ __forceinline__ void gemm_phase(PG8_LAS unsigned char* lds, const Gemm g, const Sched& S, const Epi& E) {
;     ...
;             PG8_LDB(B0, 0, 0); PG8_LDB(B1, 0, 1); PG8_SCHED; PG8_LDA(At, 0, 0); PG8_STAGE(PG8_SA(1, 1), a1 + hstep, voffA);
;             PG8_WAIT_V(8); PG8_WAIT_L(0); PG8_BAR; PG8_MMA(0, 0, At, B0); PG8_MMA(0, 1, At, B1); PG8_BAR; PG8_SCHED;
;             PG8_LDA(At, 0, 1); PG8_STAGE(PG8_SB(0, 0), b2, voffB); PG8_STAGE(PG8_SB(0, 1), b2 + hstep, voffB); PG8_STAGE(PG8_SA(0, 0), a2, voffA);
;             PG8_WAIT_V(8); PG8_WAIT_L(0); PG8_BAR; PG8_MMA(1, 0, At, B0); PG8_MMA(1, 1, At, B1); PG8_BAR; PG8_SCHED;
;             PG8_LDB(B0, 1, 0); PG8_LDB(B1, 1, 1); PG8_SCHED; PG8_LDA(At, 1, 0); PG8_STAGE(PG8_SA(0, 1), a2 + hstep, voffA);
;             PG8_WAIT_V(8); PG8_WAIT_L(0); PG8_BAR; PG8_MMA(0, 0, At, B0); PG8_MMA(0, 1, At, B1); PG8_BAR; PG8_SCHED;
;             PG8_LDA(At, 1, 1); PG8_STAGE(PG8_SB(1, 0), b3, voffB); PG8_STAGE(PG8_SB(1, 1), b3 + hstep, voffB); PG8_STAGE(PG8_SA(1, 0), a3, voffA);
;             PG8_WAIT_V(8); PG8_WAIT_L(0); PG8_BAR; PG8_MMA(1, 0, At, B0); PG8_MMA(1, 1, At, B1); PG8_BAR; PG8_SCHED;
	s_waitcnt lgkmcnt(0)
	v_mfma_f32_16x16x32_bf16 v[62:65], v[152:155], v[184:187], v[62:65]
	v_mfma_f32_16x16x32_bf16 v[58:61], v[160:163], v[184:187], v[58:61]
	v_mfma_f32_16x16x32_bf16 v[54:57], v[152:155], v[192:195], v[54:57]
	v_mfma_f32_16x16x32_bf16 v[50:53], v[160:163], v[192:195], v[50:53]
	v_mfma_f32_16x16x32_bf16 v[38:41], v[152:155], v[204:207], v[38:41]
	v_mfma_f32_16x16x32_bf16 v[34:37], v[160:163], v[204:207], v[34:37]
	v_mfma_f32_16x16x32_bf16 v[22:25], v[152:155], v[212:215], v[22:25]
	v_mfma_f32_16x16x32_bf16 v[18:21], v[160:163], v[212:215], v[18:21]
	v_mfma_f32_16x16x32_bf16 v[62:65], v[156:159], v[188:191], v[62:65]
	v_mfma_f32_16x16x32_bf16 v[58:61], v[164:167], v[188:191], v[58:61]
	v_mfma_f32_16x16x32_bf16 v[54:57], v[156:159], v[200:203], v[54:57]
	v_mfma_f32_16x16x32_bf16 v[50:53], v[164:167], v[200:203], v[50:53]
	v_mfma_f32_16x16x32_bf16 v[38:41], v[156:159], v[208:211], v[38:41]
	v_mfma_f32_16x16x32_bf16 v[34:37], v[164:167], v[208:211], v[34:37]
	v_mfma_f32_16x16x32_bf16 v[22:25], v[156:159], v[216:219], v[22:25]
	v_mfma_f32_16x16x32_bf16 v[18:21], v[164:167], v[216:219], v[18:21]
	v_mfma_f32_16x16x32_bf16 v[46:49], v[168:171], v[184:187], v[46:49]
	v_mfma_f32_16x16x32_bf16 v[42:45], v[176:179], v[184:187], v[42:45]
	v_mfma_f32_16x16x32_bf16 v[30:33], v[168:171], v[192:195], v[30:33]
	v_mfma_f32_16x16x32_bf16 v[26:29], v[176:179], v[192:195], v[26:29]
	v_mfma_f32_16x16x32_bf16 v[14:17], v[168:171], v[204:207], v[14:17]
	v_mfma_f32_16x16x32_bf16 v[10:13], v[176:179], v[204:207], v[10:13]
	v_mfma_f32_16x16x32_bf16 v[6:9], v[168:171], v[212:215], v[6:9]
	v_mfma_f32_16x16x32_bf16 v[2:5], v[176:179], v[212:215], v[2:5]
	v_mfma_f32_16x16x32_bf16 v[46:49], v[172:175], v[188:191], v[46:49]
	v_mfma_f32_16x16x32_bf16 v[42:45], v[180:183], v[188:191], v[42:45]
	v_mfma_f32_16x16x32_bf16 v[30:33], v[172:175], v[200:203], v[30:33]
	v_mfma_f32_16x16x32_bf16 v[26:29], v[180:183], v[200:203], v[26:29]
	v_mfma_f32_16x16x32_bf16 v[14:17], v[172:175], v[208:211], v[14:17]
	v_mfma_f32_16x16x32_bf16 v[10:13], v[180:183], v[208:211], v[10:13]
	v_mfma_f32_16x16x32_bf16 v[6:9], v[172:175], v[216:219], v[6:9]
	v_mfma_f32_16x16x32_bf16 v[2:5], v[180:183], v[216:219], v[2:5]
	s_barrier
	s_add_i32 s82, 0, 0x18000
	s_add_i32 s83, 0, 0x1c000
	v_add_u32_e32 v164, s82, v147
	v_add_u32_e32 v180, s83, v147
	ds_read_b128 v[152:155], v164
	ds_read_b128 v[156:159], v164 offset:1024
	ds_read_b128 v[160:163], v164 offset:2048
	ds_read_b128 v[164:167], v164 offset:3072
	ds_read_b128 v[168:171], v180
	ds_read_b128 v[172:175], v180 offset:1024
	ds_read_b128 v[176:179], v180 offset:2048
	ds_read_b128 v[180:183], v180 offset:3072
	s_add_u32 s54, s54, 0x80000
	s_addc_u32 s55, s55, 0
	s_mov_b32 m0, s53
	v_lshl_add_u64 v[226:227], s[54:55], 0, v[130:131]
	ds_read_b128 v[184:187], v151 offset:32768
	ds_read_b128 v[188:191], v151 offset:33792
	ds_read_b128 v[192:195], v151 offset:34816
	ds_read_b128 v[200:203], v151 offset:35840
	ds_read_b128 v[204:207], v151 offset:36864
	ds_read_b128 v[208:211], v151 offset:37888
	ds_read_b128 v[212:215], v151 offset:38912
	ds_read_b128 v[216:219], v151 offset:39936
	global_load_lds_dwordx4 v[226:227], off
	v_lshl_add_u64 v[226:227], s[54:55], 0, v[134:135]
	s_mov_b32 m0, s56
	s_nop 0
	global_load_lds_dwordx4 v[226:227], off
	s_waitcnt vmcnt(8)
	s_waitcnt lgkmcnt(0)
	s_barrier
	s_waitcnt lgkmcnt(0)
	v_mfma_f32_16x16x32_bf16 v[126:129], v[152:155], v[184:187], v[126:129]
	v_mfma_f32_16x16x32_bf16 v[122:125], v[160:163], v[184:187], v[122:125]
	v_mfma_f32_16x16x32_bf16 v[118:121], v[152:155], v[192:195], v[118:121]
	v_mfma_f32_16x16x32_bf16 v[114:117], v[160:163], v[192:195], v[114:117]
	v_mfma_f32_16x16x32_bf16 v[102:105], v[152:155], v[204:207], v[102:105]
	v_mfma_f32_16x16x32_bf16 v[98:101], v[160:163], v[204:207], v[98:101]
	v_mfma_f32_16x16x32_bf16 v[86:89], v[152:155], v[212:215], v[86:89]
	v_mfma_f32_16x16x32_bf16 v[82:85], v[160:163], v[212:215], v[82:85]
	v_mfma_f32_16x16x32_bf16 v[126:129], v[156:159], v[188:191], v[126:129]
	v_mfma_f32_16x16x32_bf16 v[122:125], v[164:167], v[188:191], v[122:125]
	v_mfma_f32_16x16x32_bf16 v[118:121], v[156:159], v[200:203], v[118:121]
	v_mfma_f32_16x16x32_bf16 v[114:117], v[164:167], v[200:203], v[114:117]
	v_mfma_f32_16x16x32_bf16 v[102:105], v[156:159], v[208:211], v[102:105]
	v_mfma_f32_16x16x32_bf16 v[98:101], v[164:167], v[208:211], v[98:101]
	v_mfma_f32_16x16x32_bf16 v[86:89], v[156:159], v[216:219], v[86:89]
	v_mfma_f32_16x16x32_bf16 v[82:85], v[164:167], v[216:219], v[82:85]
	v_mfma_f32_16x16x32_bf16 v[110:113], v[168:171], v[184:187], v[110:113]
	v_mfma_f32_16x16x32_bf16 v[106:109], v[176:179], v[184:187], v[106:109]
	v_mfma_f32_16x16x32_bf16 v[94:97], v[168:171], v[192:195], v[94:97]
	v_mfma_f32_16x16x32_bf16 v[90:93], v[176:179], v[192:195], v[90:93]
	v_mfma_f32_16x16x32_bf16 v[78:81], v[168:171], v[204:207], v[78:81]
	v_mfma_f32_16x16x32_bf16 v[74:77], v[176:179], v[204:207], v[74:77]
	v_mfma_f32_16x16x32_bf16 v[70:73], v[168:171], v[212:215], v[70:73]
	v_mfma_f32_16x16x32_bf16 v[66:69], v[176:179], v[212:215], v[66:69]
	v_mfma_f32_16x16x32_bf16 v[110:113], v[172:175], v[188:191], v[110:113]
	v_mfma_f32_16x16x32_bf16 v[106:109], v[180:183], v[188:191], v[106:109]
	v_mfma_f32_16x16x32_bf16 v[94:97], v[172:175], v[200:203], v[94:97]
	v_mfma_f32_16x16x32_bf16 v[90:93], v[180:183], v[200:203], v[90:93]
	v_mfma_f32_16x16x32_bf16 v[78:81], v[172:175], v[208:211], v[78:81]
	v_mfma_f32_16x16x32_bf16 v[74:77], v[180:183], v[208:211], v[74:77]
	v_mfma_f32_16x16x32_bf16 v[70:73], v[172:175], v[216:219], v[70:73]
	v_mfma_f32_16x16x32_bf16 v[66:69], v[180:183], v[216:219], v[66:69]
	s_barrier
; #define PG8_STAGE(bufoff, gbase, voff) do { _Pragma("unroll") for (int _i = 0; _i < 2; ++_i) \
;         __builtin_amdgcn_global_load_lds((const unsigned*)((const char*)(gbase) + (voff)[_i]), (PG8_LAS unsigned*)(lds + (bufoff) + ldsw + _i * 8192), 16, 0, 0); } while (0)
; #define PG8_LDA(dst, b, h) do { _Pragma("unroll") for (int m = 0; m < 4; ++m) _Pragma("unroll") for (int k = 0; k < 2; ++k) dst[m][k] = *(const PG8_LAS bf16x8*)(lds + PG8_SA(b, h) + aoff + m * 2048 + k * 1024); } while (0)
; #define PG8_WAIT_V(n) asm volatile("s_waitcnt vmcnt(" #n ")" ::: "memory")
; template <class Epi, class Sched, bool ALIGN_EPI = false, bool SP2 = false, bool MID = false>
; __device__ __forceinline__ void gemm_phase(PG8_LAS unsigned char* lds, const Gemm g, const Sched& S, const Epi& E) {
;     ...
;         for (int t = 0; t < nt; t += 2) {
;             const bool last = (t == nt - 2);
;             if constexpr (MID) { if (t == Epi::MID_T) { PG8_SCHED; E.mid(acc, cur, wr, wc, fr, fq); PG8_SCHED; } }
;             const char* a1 = cA + (size_t)(t + 1) * kstep;
;             const char* a2 = last ? nA : cA + (size_t)(t + 2) * kstep; const char* b2 = last ? nB : cB + (size_t)(t + 2) * kstep;
;             const char* a3 = a2 + kstep; const char* b3 = b2 + kstep;
;             if (last && has_next) S.a_ready(nxt);
;             if constexpr (SP2) {
;             PG8_LDB(B0, 0, 0); PG8_LDB(B1, 0, 1); PG8_SCHED; PG8_LDA(At, 0, 0); PG8_STAGE(PG8_SA(1, 1), a1 + hstep, voffA);
;             PG8_WAIT_V(8); PG8_WAIT_L(0); PG8_BAR; PG8_MMA(0, 0, At, B0); PG8_MMA(0, 1, At, B1); PG8_BAR; PG8_SCHED;
;             PG8_LDA(At, 0, 1); PG8_STAGE(PG8_SB(0, 0), b2, voffB); PG8_STAGE(PG8_SB(0, 1), b2 + hstep, voffB); PG8_STAGE(PG8_SA(0, 0), a2, voffA);
;             PG8_WAIT_V(8); PG8_WAIT_L(0); PG8_BAR; PG8_MMA(1, 0, At, B0); PG8_MMA(1, 1, At, B1); PG8_BAR; PG8_SCHED;
;             PG8_LDB(B0, 1, 0); PG8_LDB(B1, 1, 1); PG8_SCHED; PG8_LDA(At, 1, 0); PG8_STAGE(PG8_SA(0, 1), a2 + hstep, voffA);
;             PG8_WAIT_V(8); PG8_WAIT_L(0); PG8_BAR; PG8_MMA(0, 0, At, B0); PG8_MMA(0, 1, At, B1); PG8_BAR; PG8_SCHED;
;             PG8_LDA(At, 1, 1); PG8_STAGE(PG8_SB(1, 0), b3, voffB); PG8_STAGE(PG8_SB(1, 1), b3 + hstep, voffB); PG8_STAGE(PG8_SA(1, 0), a3, voffA);
;             PG8_WAIT_V(8); PG8_WAIT_L(0); PG8_BAR; PG8_MMA(1, 0, At, B0); PG8_MMA(1, 1, At, B1); PG8_BAR; PG8_SCHED;
	s_add_i32 s54, s82, s15
	v_lshl_add_u64 v[196:197], v[196:197], 0, s[18:19]
	s_mov_b32 m0, s54
	ds_read_b128 v[184:187], v151 offset:49152
	ds_read_b128 v[188:191], v151 offset:50176
	ds_read_b128 v[192:195], v151 offset:51200
	ds_read_b128 v[200:203], v151 offset:52224
	ds_read_b128 v[204:207], v151 offset:53248
	ds_read_b128 v[208:211], v151 offset:54272
	ds_read_b128 v[212:215], v151 offset:55296
	ds_read_b128 v[216:219], v151 offset:56320
	global_load_lds_dwordx4 v[196:197], off
	s_add_i32 m0, s54, 0x2000
	s_add_u32 s50, s50, 0x80080
	v_lshl_add_u64 v[196:197], v[220:221], 0, s[18:19]
	s_addc_u32 s51, s51, 0
	s_add_i32 s54, s83, s15
	global_load_lds_dwordx4 v[196:197], off
	v_lshl_add_u64 v[196:197], s[50:51], 0, v[132:133]
	s_mov_b32 m0, s54
	s_nop 0
	global_load_lds_dwordx4 v[196:197], off
	v_lshl_add_u64 v[196:197], s[50:51], 0, v[136:137]
	s_add_i32 m0, s54, 0x2000
	s_nop 0
	global_load_lds_dwordx4 v[196:197], off
	v_lshl_add_u64 v[196:197], v[222:223], 0, s[18:19]
	s_mov_b32 m0, s58
	s_nop 0
	global_load_lds_dwordx4 v[196:197], off
	v_lshl_add_u64 v[196:197], v[224:225], 0, s[18:19]
	s_mov_b32 m0, s59
	s_nop 0
	global_load_lds_dwordx4 v[196:197], off
	s_waitcnt vmcnt(8)
	s_waitcnt lgkmcnt(0)
	s_barrier
	s_waitcnt lgkmcnt(0)
	v_mfma_f32_16x16x32_bf16 v[62:65], v[152:155], v[184:187], v[62:65]
	v_mfma_f32_16x16x32_bf16 v[58:61], v[160:163], v[184:187], v[58:61]
	v_mfma_f32_16x16x32_bf16 v[54:57], v[152:155], v[192:195], v[54:57]
	v_mfma_f32_16x16x32_bf16 v[50:53], v[160:163], v[192:195], v[50:53]
	v_mfma_f32_16x16x32_bf16 v[38:41], v[152:155], v[204:207], v[38:41]
	v_mfma_f32_16x16x32_bf16 v[34:37], v[160:163], v[204:207], v[34:37]
	v_mfma_f32_16x16x32_bf16 v[22:25], v[152:155], v[212:215], v[22:25]
	v_mfma_f32_16x16x32_bf16 v[18:21], v[160:163], v[212:215], v[18:21]
	v_mfma_f32_16x16x32_bf16 v[62:65], v[156:159], v[188:191], v[62:65]
	v_mfma_f32_16x16x32_bf16 v[58:61], v[164:167], v[188:191], v[58:61]
	v_mfma_f32_16x16x32_bf16 v[54:57], v[156:159], v[200:203], v[54:57]
	v_mfma_f32_16x16x32_bf16 v[50:53], v[164:167], v[200:203], v[50:53]
	v_mfma_f32_16x16x32_bf16 v[38:41], v[156:159], v[208:211], v[38:41]
	v_mfma_f32_16x16x32_bf16 v[34:37], v[164:167], v[208:211], v[34:37]
	v_mfma_f32_16x16x32_bf16 v[22:25], v[156:159], v[216:219], v[22:25]
	v_mfma_f32_16x16x32_bf16 v[18:21], v[164:167], v[216:219], v[18:21]
	v_mfma_f32_16x16x32_bf16 v[46:49], v[168:171], v[184:187], v[46:49]
	v_mfma_f32_16x16x32_bf16 v[42:45], v[176:179], v[184:187], v[42:45]
	v_mfma_f32_16x16x32_bf16 v[30:33], v[168:171], v[192:195], v[30:33]
	v_mfma_f32_16x16x32_bf16 v[26:29], v[176:179], v[192:195], v[26:29]
	v_mfma_f32_16x16x32_bf16 v[14:17], v[168:171], v[204:207], v[14:17]
	v_mfma_f32_16x16x32_bf16 v[10:13], v[176:179], v[204:207], v[10:13]
	v_mfma_f32_16x16x32_bf16 v[6:9], v[168:171], v[212:215], v[6:9]
	v_mfma_f32_16x16x32_bf16 v[2:5], v[176:179], v[212:215], v[2:5]
	v_mfma_f32_16x16x32_bf16 v[46:49], v[172:175], v[188:191], v[46:49]
	v_mfma_f32_16x16x32_bf16 v[42:45], v[180:183], v[188:191], v[42:45]
	v_mfma_f32_16x16x32_bf16 v[30:33], v[172:175], v[200:203], v[30:33]
	v_mfma_f32_16x16x32_bf16 v[26:29], v[180:183], v[200:203], v[26:29]
	v_mfma_f32_16x16x32_bf16 v[14:17], v[172:175], v[208:211], v[14:17]
	v_mfma_f32_16x16x32_bf16 v[10:13], v[180:183], v[208:211], v[10:13]
	v_mfma_f32_16x16x32_bf16 v[6:9], v[172:175], v[216:219], v[6:9]
	v_mfma_f32_16x16x32_bf16 v[2:5], v[180:183], v[216:219], v[2:5]
	s_barrier
	s_add_i32 s81, s81, 2
	s_add_u32 s48, s48, 0x100
	s_addc_u32 s49, s49, 0
	s_add_u32 s79, s79, 0x100
	s_addc_u32 s80, s80, 0
	s_cmp_gt_u32 s81, 29
	s_cbranch_scc0 .LBB0_1528
	s_and_b64 vcc, exec, s[20:21]
	s_cbranch_vccz .LBB0_1531
	s_barrier

; #define PG8_STAGE(bufoff, gbase, voff) do { _Pragma("unroll") for (int _i = 0; _i < 2; ++_i) \
;         __builtin_amdgcn_global_load_lds((const unsigned*)((const char*)(gbase) + (voff)[_i]), (PG8_LAS unsigned*)(lds + (bufoff) + ldsw + _i * 8192), 16, 0, 0); } while (0)
; #define PG8_LDA(dst, b, h) do { _Pragma("unroll") for (int m = 0; m < 4; ++m) _Pragma("unroll") for (int k = 0; k < 2; ++k) dst[m][k] = *(const PG8_LAS bf16x8*)(lds + PG8_SA(b, h) + aoff + m * 2048 + k * 1024); } while (0)
; #define PG8_LDB(dst, b, h) do { _Pragma("unroll") for (int n = 0; n < 2; ++n) _Pragma("unroll") for (int k = 0; k < 2; ++k) dst[n][k] = *(const PG8_LAS bf16x8*)(lds + PG8_SB(b, h) + boff + n * 2048 + k * 1024); } while (0)
; #define PG8_MMA(ai, bj, At, Bt) do { __builtin_amdgcn_s_setprio(1); _Pragma("unroll") for (int m = 0; m < 4; ++m) _Pragma("unroll") for (int n = 0; n < 2; ++n) _Pragma("unroll") for (int k = 0; k < 2; ++k) \
;         acc[ai][bj][m][n] = __builtin_amdgcn_mfma_f32_16x16x32_bf16(Bt[n][k], At[m][k], acc[ai][bj][m][n], 0, 0, 0); __builtin_amdgcn_s_setprio(0); } while (0)
; #define PG8_BAR __builtin_amdgcn_s_barrier()
; template <class Epi, class Sched, bool ALIGN_EPI = false, bool SP2 = false, bool MID = false>
; __device__ __forceinline__ void gemm_phase(PG8_LAS unsigned char* lds, const Gemm g, const Sched& S, const Epi& E) {
;     ...
;             PG8_LDB(B0, 0, 0); PG8_LDB(B1, 0, 1); PG8_SCHED; PG8_LDA(At, 0, 0); PG8_STAGE(PG8_SA(1, 1), a1 + hstep, voffA);
;             PG8_WAIT_V(8); PG8_WAIT_L(0); PG8_BAR; PG8_MMA(0, 0, At, B0); PG8_MMA(0, 1, At, B1); PG8_BAR; PG8_SCHED;
;             PG8_LDA(At, 0, 1); PG8_STAGE(PG8_SB(0, 0), b2, voffB); PG8_STAGE(PG8_SB(0, 1), b2 + hstep, voffB); PG8_STAGE(PG8_SA(0, 0), a2, voffA);
;             PG8_WAIT_V(8); PG8_WAIT_L(0); PG8_BAR; PG8_MMA(1, 0, At, B0); PG8_MMA(1, 1, At, B1); PG8_BAR; PG8_SCHED;
;             PG8_LDB(B0, 1, 0); PG8_LDB(B1, 1, 1); PG8_SCHED; PG8_LDA(At, 1, 0); PG8_STAGE(PG8_SA(0, 1), a2 + hstep, voffA);
;             PG8_WAIT_V(8); PG8_WAIT_L(0); PG8_BAR; PG8_MMA(0, 0, At, B0); PG8_MMA(0, 1, At, B1); PG8_BAR; PG8_SCHED;
;             PG8_LDA(At, 1, 1); PG8_STAGE(PG8_SB(1, 0), b3, voffB); PG8_STAGE(PG8_SB(1, 1), b3 + hstep, voffB); PG8_STAGE(PG8_SA(1, 0), a3, voffA);
;             PG8_WAIT_V(8); PG8_WAIT_L(0); PG8_BAR; PG8_MMA(1, 0, At, B0); PG8_MMA(1, 1, At, B1); PG8_BAR; PG8_SCHED;
.LBB0_1685:
	ds_read_b128 v[146:149], v157
	ds_read_b128 v[150:153], v157 offset:1024
	ds_read_b128 v[160:163], v157 offset:2048
	ds_read_b128 v[164:167], v157 offset:3072
	ds_read_b128 v[168:171], v158
	ds_read_b128 v[172:175], v158 offset:1024
	ds_read_b128 v[176:179], v158 offset:2048
	ds_read_b128 v[180:183], v158 offset:3072
	s_add_u32 s48, s46, 0xfff80080
	s_addc_u32 s49, s47, -1
	s_cmp_eq_u32 s79, 28
	s_cselect_b32 s51, s39, s49
	s_cselect_b32 s50, s75, s48
	s_cselect_b32 s49, s37, s78
	s_cselect_b32 s48, s76, s77
	v_lshl_add_u64 v[196:197], s[46:47], 0, v[138:139]
	s_add_i32 m0, s45, 0xc000
	ds_read_b128 v[184:187], v159
	ds_read_b128 v[188:191], v159 offset:1024
	ds_read_b128 v[192:195], v159 offset:2048
	ds_read_b128 v[200:203], v159 offset:3072
	ds_read_b128 v[204:207], v159 offset:4096
	ds_read_b128 v[208:211], v159 offset:5120
	ds_read_b128 v[212:215], v159 offset:6144
	ds_read_b128 v[216:219], v159 offset:7168
	global_load_lds_dwordx4 v[196:197], off
	v_lshl_add_u64 v[196:197], s[46:47], 0, v[140:141]
	s_add_i32 m0, s45, 0xe000
	s_nop 0
	global_load_lds_dwordx4 v[196:197], off
	s_waitcnt vmcnt(8)
	s_waitcnt lgkmcnt(0)
	s_barrier
	s_waitcnt lgkmcnt(0)
	v_mfma_f32_16x16x32_bf16 v[126:129], v[146:149], v[184:187], v[126:129]
	v_mfma_f32_16x16x32_bf16 v[122:125], v[160:163], v[184:187], v[122:125]
	v_mfma_f32_16x16x32_bf16 v[110:113], v[146:149], v[192:195], v[110:113]
	v_mfma_f32_16x16x32_bf16 v[106:109], v[160:163], v[192:195], v[106:109]
	v_mfma_f32_16x16x32_bf16 v[94:97], v[146:149], v[204:207], v[94:97]
	v_mfma_f32_16x16x32_bf16 v[90:93], v[160:163], v[204:207], v[90:93]
	v_mfma_f32_16x16x32_bf16 v[78:81], v[146:149], v[212:215], v[78:81]
	v_mfma_f32_16x16x32_bf16 v[74:77], v[160:163], v[212:215], v[74:77]
	v_mfma_f32_16x16x32_bf16 v[126:129], v[150:153], v[188:191], v[126:129]
	v_mfma_f32_16x16x32_bf16 v[122:125], v[164:167], v[188:191], v[122:125]
	v_mfma_f32_16x16x32_bf16 v[110:113], v[150:153], v[200:203], v[110:113]
	v_mfma_f32_16x16x32_bf16 v[106:109], v[164:167], v[200:203], v[106:109]
	v_mfma_f32_16x16x32_bf16 v[94:97], v[150:153], v[208:211], v[94:97]
	v_mfma_f32_16x16x32_bf16 v[90:93], v[164:167], v[208:211], v[90:93]
	v_mfma_f32_16x16x32_bf16 v[78:81], v[150:153], v[216:219], v[78:81]
	v_mfma_f32_16x16x32_bf16 v[74:77], v[164:167], v[216:219], v[74:77]
	v_mfma_f32_16x16x32_bf16 v[118:121], v[168:171], v[184:187], v[118:121]
	v_mfma_f32_16x16x32_bf16 v[114:117], v[176:179], v[184:187], v[114:117]
	v_mfma_f32_16x16x32_bf16 v[102:105], v[168:171], v[192:195], v[102:105]
	v_mfma_f32_16x16x32_bf16 v[98:101], v[176:179], v[192:195], v[98:101]
	v_mfma_f32_16x16x32_bf16 v[86:89], v[168:171], v[204:207], v[86:89]
	v_mfma_f32_16x16x32_bf16 v[82:85], v[176:179], v[204:207], v[82:85]
	v_mfma_f32_16x16x32_bf16 v[70:73], v[168:171], v[212:215], v[70:73]
	v_mfma_f32_16x16x32_bf16 v[66:69], v[176:179], v[212:215], v[66:69]
	v_mfma_f32_16x16x32_bf16 v[118:121], v[172:175], v[188:191], v[118:121]
	v_mfma_f32_16x16x32_bf16 v[114:117], v[180:183], v[188:191], v[114:117]
	v_mfma_f32_16x16x32_bf16 v[102:105], v[172:175], v[200:203], v[102:105]
	v_mfma_f32_16x16x32_bf16 v[98:101], v[180:183], v[200:203], v[98:101]
	v_mfma_f32_16x16x32_bf16 v[86:89], v[172:175], v[208:211], v[86:89]
	v_mfma_f32_16x16x32_bf16 v[82:85], v[180:183], v[208:211], v[82:85]
	v_mfma_f32_16x16x32_bf16 v[70:73], v[172:175], v[216:219], v[70:73]
	v_mfma_f32_16x16x32_bf16 v[66:69], v[180:183], v[216:219], v[66:69]
	s_barrier
	s_add_i32 s80, s59, s15
	v_lshl_add_u64 v[196:197], s[48:49], 0, v[132:133]
	s_mov_b32 m0, s80
	ds_read_b128 v[184:187], v159 offset:16384
	ds_read_b128 v[188:191], v159 offset:17408
	ds_read_b128 v[192:195], v159 offset:18432
	ds_read_b128 v[200:203], v159 offset:19456
	ds_read_b128 v[204:207], v159 offset:20480
	ds_read_b128 v[208:211], v159 offset:21504
	ds_read_b128 v[212:215], v159 offset:22528
	ds_read_b128 v[216:219], v159 offset:23552
	global_load_lds_dwordx4 v[196:197], off
	s_add_i32 m0, s80, 0x2000
	s_add_u32 s80, s48, 0x80000
	v_lshl_add_u64 v[220:221], s[48:49], 0, v[136:137]
	s_addc_u32 s81, s49, 0
	s_add_i32 s82, s62, s15
	global_load_lds_dwordx4 v[220:221], off
	v_lshl_add_u64 v[222:223], s[80:81], 0, v[132:133]
	s_mov_b32 m0, s82
	v_lshl_add_u64 v[224:225], s[50:51], 0, v[134:135]
	global_load_lds_dwordx4 v[222:223], off
	v_lshl_add_u64 v[222:223], s[80:81], 0, v[136:137]
	s_add_i32 m0, s82, 0x2000
	s_nop 0
	global_load_lds_dwordx4 v[222:223], off
	v_lshl_add_u64 v[222:223], s[50:51], 0, v[130:131]
	s_mov_b32 m0, s45
	s_nop 0
	global_load_lds_dwordx4 v[222:223], off
	s_mov_b32 m0, s52
	s_nop 0
	global_load_lds_dwordx4 v[224:225], off
	s_waitcnt vmcnt(8)
	s_waitcnt lgkmcnt(0)
	s_barrier
; #define PG8_STAGE(bufoff, gbase, voff) do { _Pragma("unroll") for (int _i = 0; _i < 2; ++_i) \
;         __builtin_amdgcn_global_load_lds((const unsigned*)((const char*)(gbase) + (voff)[_i]), (PG8_LAS unsigned*)(lds + (bufoff) + ldsw + _i * 8192), 16, 0, 0); } while (0)
; #define PG8_LDA(dst, b, h) do { _Pragma("unroll") for (int m = 0; m < 4; ++m) _Pragma("unroll") for (int k = 0; k < 2; ++k) dst[m][k] = *(const PG8_LAS bf16x8*)(lds + PG8_SA(b, h) + aoff + m * 2048 + k * 1024); } while (0)
; #define PG8_LDB(dst, b, h) do { _Pragma("unroll") for (int n = 0; n < 2; ++n) _Pragma("unroll") for (int k = 0; k < 2; ++k) dst[n][k] = *(const PG8_LAS bf16x8*)(lds + PG8_SB(b, h) + boff + n * 2048 + k * 1024); } while (0)
; #define PG8_MMA(ai, bj, At, Bt) do { __builtin_amdgcn_s_setprio(1); _Pragma("unroll") for (int m = 0; m < 4; ++m) _Pragma("unroll") for (int n = 0; n < 2; ++n) _Pragma("unroll") for (int k = 0; k < 2; ++k) \
;         acc[ai][bj][m][n] = __builtin_amdgcn_mfma_f32_16x16x32_bf16(Bt[n][k], At[m][k], acc[ai][bj][m][n], 0, 0, 0); __builtin_amdgcn_s_setprio(0); } while (0)
; #define PG8_BAR __builtin_amdgcn_s_barrier()
; template <class Epi, class Sched, bool ALIGN_EPI = false, bool SP2 = false, bool MID = false>
; __device__ __forceinline__ void gemm_phase(PG8_LAS unsigned char* lds, const Gemm g, const Sched& S, const Epi& E) {
;     ...
;             PG8_LDB(B0, 0, 0); PG8_LDB(B1, 0, 1); PG8_SCHED; PG8_LDA(At, 0, 0); PG8_STAGE(PG8_SA(1, 1), a1 + hstep, voffA);
;             PG8_WAIT_V(8); PG8_WAIT_L(0); PG8_BAR; PG8_MMA(0, 0, At, B0); PG8_MMA(0, 1, At, B1); PG8_BAR; PG8_SCHED;
;             PG8_LDA(At, 0, 1); PG8_STAGE(PG8_SB(0, 0), b2, voffB); PG8_STAGE(PG8_SB(0, 1), b2 + hstep, voffB); PG8_STAGE(PG8_SA(0, 0), a2, voffA);
;             PG8_WAIT_V(8); PG8_WAIT_L(0); PG8_BAR; PG8_MMA(1, 0, At, B0); PG8_MMA(1, 1, At, B1); PG8_BAR; PG8_SCHED;
;             PG8_LDB(B0, 1, 0); PG8_LDB(B1, 1, 1); PG8_SCHED; PG8_LDA(At, 1, 0); PG8_STAGE(PG8_SA(0, 1), a2 + hstep, voffA);
;             PG8_WAIT_V(8); PG8_WAIT_L(0); PG8_BAR; PG8_MMA(0, 0, At, B0); PG8_MMA(0, 1, At, B1); PG8_BAR; PG8_SCHED;
;             PG8_LDA(At, 1, 1); PG8_STAGE(PG8_SB(1, 0), b3, voffB); PG8_STAGE(PG8_SB(1, 1), b3 + hstep, voffB); PG8_STAGE(PG8_SA(1, 0), a3, voffA);
;             PG8_WAIT_V(8); PG8_WAIT_L(0); PG8_BAR; PG8_MMA(1, 0, At, B0); PG8_MMA(1, 1, At, B1); PG8_BAR; PG8_SCHED;
	s_waitcnt lgkmcnt(0)
	v_mfma_f32_16x16x32_bf16 v[62:65], v[146:149], v[184:187], v[62:65]
	v_mfma_f32_16x16x32_bf16 v[58:61], v[160:163], v[184:187], v[58:61]
	v_mfma_f32_16x16x32_bf16 v[46:49], v[146:149], v[192:195], v[46:49]
	v_mfma_f32_16x16x32_bf16 v[42:45], v[160:163], v[192:195], v[42:45]
	v_mfma_f32_16x16x32_bf16 v[30:33], v[146:149], v[204:207], v[30:33]
	v_mfma_f32_16x16x32_bf16 v[26:29], v[160:163], v[204:207], v[26:29]
	v_mfma_f32_16x16x32_bf16 v[14:17], v[146:149], v[212:215], v[14:17]
	v_mfma_f32_16x16x32_bf16 v[10:13], v[160:163], v[212:215], v[10:13]
	v_mfma_f32_16x16x32_bf16 v[62:65], v[150:153], v[188:191], v[62:65]
	v_mfma_f32_16x16x32_bf16 v[58:61], v[164:167], v[188:191], v[58:61]
	v_mfma_f32_16x16x32_bf16 v[46:49], v[150:153], v[200:203], v[46:49]
	v_mfma_f32_16x16x32_bf16 v[42:45], v[164:167], v[200:203], v[42:45]
	v_mfma_f32_16x16x32_bf16 v[30:33], v[150:153], v[208:211], v[30:33]
	v_mfma_f32_16x16x32_bf16 v[26:29], v[164:167], v[208:211], v[26:29]
	v_mfma_f32_16x16x32_bf16 v[14:17], v[150:153], v[216:219], v[14:17]
	v_mfma_f32_16x16x32_bf16 v[10:13], v[164:167], v[216:219], v[10:13]
	v_mfma_f32_16x16x32_bf16 v[54:57], v[168:171], v[184:187], v[54:57]
	v_mfma_f32_16x16x32_bf16 v[50:53], v[176:179], v[184:187], v[50:53]
	v_mfma_f32_16x16x32_bf16 v[38:41], v[168:171], v[192:195], v[38:41]
	v_mfma_f32_16x16x32_bf16 v[34:37], v[176:179], v[192:195], v[34:37]
	v_mfma_f32_16x16x32_bf16 v[22:25], v[168:171], v[204:207], v[22:25]
	v_mfma_f32_16x16x32_bf16 v[18:21], v[176:179], v[204:207], v[18:21]
	v_mfma_f32_16x16x32_bf16 v[6:9], v[168:171], v[212:215], v[6:9]
	v_mfma_f32_16x16x32_bf16 v[2:5], v[176:179], v[212:215], v[2:5]
	v_mfma_f32_16x16x32_bf16 v[54:57], v[172:175], v[188:191], v[54:57]
	v_mfma_f32_16x16x32_bf16 v[50:53], v[180:183], v[188:191], v[50:53]
	v_mfma_f32_16x16x32_bf16 v[38:41], v[172:175], v[200:203], v[38:41]
	v_mfma_f32_16x16x32_bf16 v[34:37], v[180:183], v[200:203], v[34:37]
	v_mfma_f32_16x16x32_bf16 v[22:25], v[172:175], v[208:211], v[22:25]
	v_mfma_f32_16x16x32_bf16 v[18:21], v[180:183], v[208:211], v[18:21]
	v_mfma_f32_16x16x32_bf16 v[6:9], v[172:175], v[216:219], v[6:9]
	v_mfma_f32_16x16x32_bf16 v[2:5], v[180:183], v[216:219], v[2:5]
	s_barrier
	s_add_i32 s80, 0, 0x18000
	s_add_i32 s81, 0, 0x1c000
	v_add_u32_e32 v164, s80, v155
	v_add_u32_e32 v180, s81, v155
	ds_read_b128 v[146:149], v164
	ds_read_b128 v[150:153], v164 offset:1024
	ds_read_b128 v[160:163], v164 offset:2048
	ds_read_b128 v[164:167], v164 offset:3072
	ds_read_b128 v[168:171], v180
	ds_read_b128 v[172:175], v180 offset:1024
	ds_read_b128 v[176:179], v180 offset:2048
	ds_read_b128 v[180:183], v180 offset:3072
	s_add_u32 s50, s50, 0x80000
	s_addc_u32 s51, s51, 0
	s_mov_b32 m0, s53
	v_lshl_add_u64 v[226:227], s[50:51], 0, v[130:131]
	ds_read_b128 v[184:187], v159 offset:32768
	ds_read_b128 v[188:191], v159 offset:33792
	ds_read_b128 v[192:195], v159 offset:34816
	ds_read_b128 v[200:203], v159 offset:35840
	ds_read_b128 v[204:207], v159 offset:36864
	ds_read_b128 v[208:211], v159 offset:37888
	ds_read_b128 v[212:215], v159 offset:38912
	ds_read_b128 v[216:219], v159 offset:39936
	global_load_lds_dwordx4 v[226:227], off
	v_lshl_add_u64 v[226:227], s[50:51], 0, v[134:135]
	s_mov_b32 m0, s54
	s_nop 0
	global_load_lds_dwordx4 v[226:227], off
	s_waitcnt vmcnt(8)
	s_waitcnt lgkmcnt(0)
	s_barrier
	s_waitcnt lgkmcnt(0)
	v_mfma_f32_16x16x32_bf16 v[126:129], v[146:149], v[184:187], v[126:129]
	v_mfma_f32_16x16x32_bf16 v[122:125], v[160:163], v[184:187], v[122:125]
	v_mfma_f32_16x16x32_bf16 v[110:113], v[146:149], v[192:195], v[110:113]
	v_mfma_f32_16x16x32_bf16 v[106:109], v[160:163], v[192:195], v[106:109]
	v_mfma_f32_16x16x32_bf16 v[94:97], v[146:149], v[204:207], v[94:97]
	v_mfma_f32_16x16x32_bf16 v[90:93], v[160:163], v[204:207], v[90:93]
	v_mfma_f32_16x16x32_bf16 v[78:81], v[146:149], v[212:215], v[78:81]
	v_mfma_f32_16x16x32_bf16 v[74:77], v[160:163], v[212:215], v[74:77]
	v_mfma_f32_16x16x32_bf16 v[126:129], v[150:153], v[188:191], v[126:129]
	v_mfma_f32_16x16x32_bf16 v[122:125], v[164:167], v[188:191], v[122:125]
	v_mfma_f32_16x16x32_bf16 v[110:113], v[150:153], v[200:203], v[110:113]
	v_mfma_f32_16x16x32_bf16 v[106:109], v[164:167], v[200:203], v[106:109]
	v_mfma_f32_16x16x32_bf16 v[94:97], v[150:153], v[208:211], v[94:97]
	v_mfma_f32_16x16x32_bf16 v[90:93], v[164:167], v[208:211], v[90:93]
	v_mfma_f32_16x16x32_bf16 v[78:81], v[150:153], v[216:219], v[78:81]
	v_mfma_f32_16x16x32_bf16 v[74:77], v[164:167], v[216:219], v[74:77]
	v_mfma_f32_16x16x32_bf16 v[118:121], v[168:171], v[184:187], v[118:121]
	v_mfma_f32_16x16x32_bf16 v[114:117], v[176:179], v[184:187], v[114:117]
	v_mfma_f32_16x16x32_bf16 v[102:105], v[168:171], v[192:195], v[102:105]
	v_mfma_f32_16x16x32_bf16 v[98:101], v[176:179], v[192:195], v[98:101]
	v_mfma_f32_16x16x32_bf16 v[86:89], v[168:171], v[204:207], v[86:89]
	v_mfma_f32_16x16x32_bf16 v[82:85], v[176:179], v[204:207], v[82:85]
	v_mfma_f32_16x16x32_bf16 v[70:73], v[168:171], v[212:215], v[70:73]
	v_mfma_f32_16x16x32_bf16 v[66:69], v[176:179], v[212:215], v[66:69]
	v_mfma_f32_16x16x32_bf16 v[118:121], v[172:175], v[188:191], v[118:121]
	v_mfma_f32_16x16x32_bf16 v[114:117], v[180:183], v[188:191], v[114:117]
	v_mfma_f32_16x16x32_bf16 v[102:105], v[172:175], v[200:203], v[102:105]
	v_mfma_f32_16x16x32_bf16 v[98:101], v[180:183], v[200:203], v[98:101]
	v_mfma_f32_16x16x32_bf16 v[86:89], v[172:175], v[208:211], v[86:89]
	v_mfma_f32_16x16x32_bf16 v[82:85], v[180:183], v[208:211], v[82:85]
	v_mfma_f32_16x16x32_bf16 v[70:73], v[172:175], v[216:219], v[70:73]
	v_mfma_f32_16x16x32_bf16 v[66:69], v[180:183], v[216:219], v[66:69]
	s_barrier
; #define PG8_STAGE(bufoff, gbase, voff) do { _Pragma("unroll") for (int _i = 0; _i < 2; ++_i) \
;         __builtin_amdgcn_global_load_lds((const unsigned*)((const char*)(gbase) + (voff)[_i]), (PG8_LAS unsigned*)(lds + (bufoff) + ldsw + _i * 8192), 16, 0, 0); } while (0)
; #define PG8_LDA(dst, b, h) do { _Pragma("unroll") for (int m = 0; m < 4; ++m) _Pragma("unroll") for (int k = 0; k < 2; ++k) dst[m][k] = *(const PG8_LAS bf16x8*)(lds + PG8_SA(b, h) + aoff + m * 2048 + k * 1024); } while (0)
; #define PG8_WAIT_V(n) asm volatile("s_waitcnt vmcnt(" #n ")" ::: "memory")
; template <class Epi, class Sched, bool ALIGN_EPI = false, bool SP2 = false, bool MID = false>
; __device__ __forceinline__ void gemm_phase(PG8_LAS unsigned char* lds, const Gemm g, const Sched& S, const Epi& E) {
;     ...
;         for (int t = 0; t < nt; t += 2) {
;             const bool last = (t == nt - 2);
;             if constexpr (MID) { if (t == Epi::MID_T) { PG8_SCHED; E.mid(acc, cur, wr, wc, fr, fq); PG8_SCHED; } }
;             const char* a1 = cA + (size_t)(t + 1) * kstep;
;             const char* a2 = last ? nA : cA + (size_t)(t + 2) * kstep; const char* b2 = last ? nB : cB + (size_t)(t + 2) * kstep;
;             const char* a3 = a2 + kstep; const char* b3 = b2 + kstep;
;             if (last && has_next) S.a_ready(nxt);
;             if constexpr (SP2) {
;             PG8_LDB(B0, 0, 0); PG8_LDB(B1, 0, 1); PG8_SCHED; PG8_LDA(At, 0, 0); PG8_STAGE(PG8_SA(1, 1), a1 + hstep, voffA);
;             PG8_WAIT_V(8); PG8_WAIT_L(0); PG8_BAR; PG8_MMA(0, 0, At, B0); PG8_MMA(0, 1, At, B1); PG8_BAR; PG8_SCHED;
;             PG8_LDA(At, 0, 1); PG8_STAGE(PG8_SB(0, 0), b2, voffB); PG8_STAGE(PG8_SB(0, 1), b2 + hstep, voffB); PG8_STAGE(PG8_SA(0, 0), a2, voffA);
;             PG8_WAIT_V(8); PG8_WAIT_L(0); PG8_BAR; PG8_MMA(1, 0, At, B0); PG8_MMA(1, 1, At, B1); PG8_BAR; PG8_SCHED;
;             PG8_LDB(B0, 1, 0); PG8_LDB(B1, 1, 1); PG8_SCHED; PG8_LDA(At, 1, 0); PG8_STAGE(PG8_SA(0, 1), a2 + hstep, voffA);
;             PG8_WAIT_V(8); PG8_WAIT_L(0); PG8_BAR; PG8_MMA(0, 0, At, B0); PG8_MMA(0, 1, At, B1); PG8_BAR; PG8_SCHED;
;             PG8_LDA(At, 1, 1); PG8_STAGE(PG8_SB(1, 0), b3, voffB); PG8_STAGE(PG8_SB(1, 1), b3 + hstep, voffB); PG8_STAGE(PG8_SA(1, 0), a3, voffA);
;             PG8_WAIT_V(8); PG8_WAIT_L(0); PG8_BAR; PG8_MMA(1, 0, At, B0); PG8_MMA(1, 1, At, B1); PG8_BAR; PG8_SCHED;
	s_add_i32 s50, s80, s15
	v_lshl_add_u64 v[196:197], v[196:197], 0, s[16:17]
	s_mov_b32 m0, s50
	ds_read_b128 v[184:187], v159 offset:49152
	ds_read_b128 v[188:191], v159 offset:50176
	ds_read_b128 v[192:195], v159 offset:51200
	ds_read_b128 v[200:203], v159 offset:52224
	ds_read_b128 v[204:207], v159 offset:53248
	ds_read_b128 v[208:211], v159 offset:54272
	ds_read_b128 v[212:215], v159 offset:55296
	ds_read_b128 v[216:219], v159 offset:56320
	global_load_lds_dwordx4 v[196:197], off
	s_add_i32 m0, s50, 0x2000
	s_add_u32 s48, s48, 0x80080
	v_lshl_add_u64 v[196:197], v[220:221], 0, s[16:17]
	s_addc_u32 s49, s49, 0
	s_add_i32 s50, s81, s15
	global_load_lds_dwordx4 v[196:197], off
	v_lshl_add_u64 v[196:197], s[48:49], 0, v[132:133]
	s_mov_b32 m0, s50
	s_nop 0
	global_load_lds_dwordx4 v[196:197], off
	v_lshl_add_u64 v[196:197], s[48:49], 0, v[136:137]
	s_add_i32 m0, s50, 0x2000
	s_nop 0
	global_load_lds_dwordx4 v[196:197], off
	v_lshl_add_u64 v[196:197], v[222:223], 0, s[16:17]
	s_mov_b32 m0, s56
	s_nop 0
	global_load_lds_dwordx4 v[196:197], off
	v_lshl_add_u64 v[196:197], v[224:225], 0, s[16:17]
	s_mov_b32 m0, s57
	s_nop 0
	global_load_lds_dwordx4 v[196:197], off
	s_waitcnt vmcnt(8)
	s_waitcnt lgkmcnt(0)
	s_barrier
	s_waitcnt lgkmcnt(0)
	v_mfma_f32_16x16x32_bf16 v[62:65], v[146:149], v[184:187], v[62:65]
	v_mfma_f32_16x16x32_bf16 v[58:61], v[160:163], v[184:187], v[58:61]
	v_mfma_f32_16x16x32_bf16 v[46:49], v[146:149], v[192:195], v[46:49]
	v_mfma_f32_16x16x32_bf16 v[42:45], v[160:163], v[192:195], v[42:45]
	v_mfma_f32_16x16x32_bf16 v[30:33], v[146:149], v[204:207], v[30:33]
	v_mfma_f32_16x16x32_bf16 v[26:29], v[160:163], v[204:207], v[26:29]
	v_mfma_f32_16x16x32_bf16 v[14:17], v[146:149], v[212:215], v[14:17]
	v_mfma_f32_16x16x32_bf16 v[10:13], v[160:163], v[212:215], v[10:13]
	v_mfma_f32_16x16x32_bf16 v[62:65], v[150:153], v[188:191], v[62:65]
	v_mfma_f32_16x16x32_bf16 v[58:61], v[164:167], v[188:191], v[58:61]
	v_mfma_f32_16x16x32_bf16 v[46:49], v[150:153], v[200:203], v[46:49]
	v_mfma_f32_16x16x32_bf16 v[42:45], v[164:167], v[200:203], v[42:45]
	v_mfma_f32_16x16x32_bf16 v[30:33], v[150:153], v[208:211], v[30:33]
	v_mfma_f32_16x16x32_bf16 v[26:29], v[164:167], v[208:211], v[26:29]
	v_mfma_f32_16x16x32_bf16 v[14:17], v[150:153], v[216:219], v[14:17]
	v_mfma_f32_16x16x32_bf16 v[10:13], v[164:167], v[216:219], v[10:13]
	v_mfma_f32_16x16x32_bf16 v[54:57], v[168:171], v[184:187], v[54:57]
	v_mfma_f32_16x16x32_bf16 v[50:53], v[176:179], v[184:187], v[50:53]
	v_mfma_f32_16x16x32_bf16 v[38:41], v[168:171], v[192:195], v[38:41]
	v_mfma_f32_16x16x32_bf16 v[34:37], v[176:179], v[192:195], v[34:37]
	v_mfma_f32_16x16x32_bf16 v[22:25], v[168:171], v[204:207], v[22:25]
	v_mfma_f32_16x16x32_bf16 v[18:21], v[176:179], v[204:207], v[18:21]
	v_mfma_f32_16x16x32_bf16 v[6:9], v[168:171], v[212:215], v[6:9]
	v_mfma_f32_16x16x32_bf16 v[2:5], v[176:179], v[212:215], v[2:5]
	v_mfma_f32_16x16x32_bf16 v[54:57], v[172:175], v[188:191], v[54:57]
	v_mfma_f32_16x16x32_bf16 v[50:53], v[180:183], v[188:191], v[50:53]
	v_mfma_f32_16x16x32_bf16 v[38:41], v[172:175], v[200:203], v[38:41]
	v_mfma_f32_16x16x32_bf16 v[34:37], v[180:183], v[200:203], v[34:37]
	v_mfma_f32_16x16x32_bf16 v[22:25], v[172:175], v[208:211], v[22:25]
	v_mfma_f32_16x16x32_bf16 v[18:21], v[180:183], v[208:211], v[18:21]
	v_mfma_f32_16x16x32_bf16 v[6:9], v[172:175], v[216:219], v[6:9]
	v_mfma_f32_16x16x32_bf16 v[2:5], v[180:183], v[216:219], v[2:5]
	s_barrier
	s_add_i32 s79, s79, 2
	s_add_u32 s46, s46, 0x100
	s_addc_u32 s47, s47, 0
	s_add_u32 s77, s77, 0x100
	s_addc_u32 s78, s78, 0
	s_cmp_gt_u32 s79, 29
	s_cbranch_scc0 .LBB0_1685
	s_and_b64 vcc, exec, s[18:19]
	s_cbranch_vccz .LBB0_1688
	s_barrier

; #define PG8_STAGE(bufoff, gbase, voff) do { _Pragma("unroll") for (int _i = 0; _i < 2; ++_i) \
;         __builtin_amdgcn_global_load_lds((const unsigned*)((const char*)(gbase) + (voff)[_i]), (PG8_LAS unsigned*)(lds + (bufoff) + ldsw + _i * 8192), 16, 0, 0); } while (0)
; #define PG8_LDA(dst, b, h) do { _Pragma("unroll") for (int m = 0; m < 4; ++m) _Pragma("unroll") for (int k = 0; k < 2; ++k) dst[m][k] = *(const PG8_LAS bf16x8*)(lds + PG8_SA(b, h) + aoff + m * 2048 + k * 1024); } while (0)
; #define PG8_LDB(dst, b, h) do { _Pragma("unroll") for (int n = 0; n < 2; ++n) _Pragma("unroll") for (int k = 0; k < 2; ++k) dst[n][k] = *(const PG8_LAS bf16x8*)(lds + PG8_SB(b, h) + boff + n * 2048 + k * 1024); } while (0)
; #define PG8_MMA(ai, bj, At, Bt) do { __builtin_amdgcn_s_setprio(1); _Pragma("unroll") for (int m = 0; m < 4; ++m) _Pragma("unroll") for (int n = 0; n < 2; ++n) _Pragma("unroll") for (int k = 0; k < 2; ++k) \
;         acc[ai][bj][m][n] = __builtin_amdgcn_mfma_f32_16x16x32_bf16(Bt[n][k], At[m][k], acc[ai][bj][m][n], 0, 0, 0); __builtin_amdgcn_s_setprio(0); } while (0)
; #define PG8_BAR __builtin_amdgcn_s_barrier()
; template <class Epi, class Sched, bool ALIGN_EPI = false, bool SP2 = false, bool MID = false>
; __device__ __forceinline__ void gemm_phase(PG8_LAS unsigned char* lds, const Gemm g, const Sched& S, const Epi& E) {
;     ...
;             PG8_LDB(B0, 0, 0); PG8_LDB(B1, 0, 1); PG8_SCHED; PG8_LDA(At, 0, 0); PG8_STAGE(PG8_SA(1, 1), a1 + hstep, voffA);
;             PG8_WAIT_V(8); PG8_WAIT_L(0); PG8_BAR; PG8_MMA(0, 0, At, B0); PG8_MMA(0, 1, At, B1); PG8_BAR; PG8_SCHED;
;             PG8_LDA(At, 0, 1); PG8_STAGE(PG8_SB(0, 0), b2, voffB); PG8_STAGE(PG8_SB(0, 1), b2 + hstep, voffB); PG8_STAGE(PG8_SA(0, 0), a2, voffA);
;             PG8_WAIT_V(8); PG8_WAIT_L(0); PG8_BAR; PG8_MMA(1, 0, At, B0); PG8_MMA(1, 1, At, B1); PG8_BAR; PG8_SCHED;
;             PG8_LDB(B0, 1, 0); PG8_LDB(B1, 1, 1); PG8_SCHED; PG8_LDA(At, 1, 0); PG8_STAGE(PG8_SA(0, 1), a2 + hstep, voffA);
;             PG8_WAIT_V(8); PG8_WAIT_L(0); PG8_BAR; PG8_MMA(0, 0, At, B0); PG8_MMA(0, 1, At, B1); PG8_BAR; PG8_SCHED;
;             PG8_LDA(At, 1, 1); PG8_STAGE(PG8_SB(1, 0), b3, voffB); PG8_STAGE(PG8_SB(1, 1), b3 + hstep, voffB); PG8_STAGE(PG8_SA(1, 0), a3, voffA);
;             PG8_WAIT_V(8); PG8_WAIT_L(0); PG8_BAR; PG8_MMA(1, 0, At, B0); PG8_MMA(1, 1, At, B1); PG8_BAR; PG8_SCHED;
.LBB0_1772:
	ds_read_b128 v[152:155], v149
	ds_read_b128 v[156:159], v149 offset:1024
	ds_read_b128 v[160:163], v149 offset:2048
	ds_read_b128 v[164:167], v149 offset:3072
	ds_read_b128 v[168:171], v150
	ds_read_b128 v[172:175], v150 offset:1024
	ds_read_b128 v[176:179], v150 offset:2048
	ds_read_b128 v[180:183], v150 offset:3072
	s_add_u32 s46, s44, 0xffe00080
	s_addc_u32 s47, s45, -1
	s_cmpk_eq_i32 s79, 0x7c
	s_cselect_b32 s49, s39, s47
	s_cselect_b32 s48, s75, s46
	s_cselect_b32 s47, s37, s78
	s_cselect_b32 s46, s76, s77
	v_lshl_add_u64 v[196:197], s[44:45], 0, v[138:139]
	s_add_i32 m0, s27, 0xc000
	ds_read_b128 v[184:187], v151
	ds_read_b128 v[188:191], v151 offset:1024
	ds_read_b128 v[192:195], v151 offset:2048
	ds_read_b128 v[200:203], v151 offset:3072
	ds_read_b128 v[204:207], v151 offset:4096
	ds_read_b128 v[208:211], v151 offset:5120
	ds_read_b128 v[212:215], v151 offset:6144
	ds_read_b128 v[216:219], v151 offset:7168
	global_load_lds_dwordx4 v[196:197], off
	v_lshl_add_u64 v[196:197], s[44:45], 0, v[140:141]
	s_add_i32 m0, s27, 0xe000
	s_nop 0
	global_load_lds_dwordx4 v[196:197], off
	s_waitcnt vmcnt(8)
	s_waitcnt lgkmcnt(0)
	s_barrier
	s_waitcnt lgkmcnt(0)
	v_mfma_f32_16x16x32_bf16 v[126:129], v[152:155], v[184:187], v[126:129]
	v_mfma_f32_16x16x32_bf16 v[122:125], v[160:163], v[184:187], v[122:125]
	v_mfma_f32_16x16x32_bf16 v[118:121], v[152:155], v[192:195], v[118:121]
	v_mfma_f32_16x16x32_bf16 v[114:117], v[160:163], v[192:195], v[114:117]
	v_mfma_f32_16x16x32_bf16 v[102:105], v[152:155], v[204:207], v[102:105]
	v_mfma_f32_16x16x32_bf16 v[98:101], v[160:163], v[204:207], v[98:101]
	v_mfma_f32_16x16x32_bf16 v[86:89], v[152:155], v[212:215], v[86:89]
	v_mfma_f32_16x16x32_bf16 v[82:85], v[160:163], v[212:215], v[82:85]
	v_mfma_f32_16x16x32_bf16 v[126:129], v[156:159], v[188:191], v[126:129]
	v_mfma_f32_16x16x32_bf16 v[122:125], v[164:167], v[188:191], v[122:125]
	v_mfma_f32_16x16x32_bf16 v[118:121], v[156:159], v[200:203], v[118:121]
	v_mfma_f32_16x16x32_bf16 v[114:117], v[164:167], v[200:203], v[114:117]
	v_mfma_f32_16x16x32_bf16 v[102:105], v[156:159], v[208:211], v[102:105]
	v_mfma_f32_16x16x32_bf16 v[98:101], v[164:167], v[208:211], v[98:101]
	v_mfma_f32_16x16x32_bf16 v[86:89], v[156:159], v[216:219], v[86:89]
	v_mfma_f32_16x16x32_bf16 v[82:85], v[164:167], v[216:219], v[82:85]
	v_mfma_f32_16x16x32_bf16 v[110:113], v[168:171], v[184:187], v[110:113]
	v_mfma_f32_16x16x32_bf16 v[106:109], v[176:179], v[184:187], v[106:109]
	v_mfma_f32_16x16x32_bf16 v[94:97], v[168:171], v[192:195], v[94:97]
	v_mfma_f32_16x16x32_bf16 v[90:93], v[176:179], v[192:195], v[90:93]
	v_mfma_f32_16x16x32_bf16 v[78:81], v[168:171], v[204:207], v[78:81]
	v_mfma_f32_16x16x32_bf16 v[74:77], v[176:179], v[204:207], v[74:77]
	v_mfma_f32_16x16x32_bf16 v[70:73], v[168:171], v[212:215], v[70:73]
	v_mfma_f32_16x16x32_bf16 v[66:69], v[176:179], v[212:215], v[66:69]
	v_mfma_f32_16x16x32_bf16 v[110:113], v[172:175], v[188:191], v[110:113]
	v_mfma_f32_16x16x32_bf16 v[106:109], v[180:183], v[188:191], v[106:109]
	v_mfma_f32_16x16x32_bf16 v[94:97], v[172:175], v[200:203], v[94:97]
	v_mfma_f32_16x16x32_bf16 v[90:93], v[180:183], v[200:203], v[90:93]
	v_mfma_f32_16x16x32_bf16 v[78:81], v[172:175], v[208:211], v[78:81]
	v_mfma_f32_16x16x32_bf16 v[74:77], v[180:183], v[208:211], v[74:77]
	v_mfma_f32_16x16x32_bf16 v[70:73], v[172:175], v[216:219], v[70:73]
	v_mfma_f32_16x16x32_bf16 v[66:69], v[180:183], v[216:219], v[66:69]
	s_barrier
	s_add_i32 s80, s59, s51
	v_lshl_add_u64 v[196:197], s[46:47], 0, v[132:133]
	s_mov_b32 m0, s80
	ds_read_b128 v[184:187], v151 offset:16384
	ds_read_b128 v[188:191], v151 offset:17408
	ds_read_b128 v[192:195], v151 offset:18432
	ds_read_b128 v[200:203], v151 offset:19456
	ds_read_b128 v[204:207], v151 offset:20480
	ds_read_b128 v[208:211], v151 offset:21504
	ds_read_b128 v[212:215], v151 offset:22528
	ds_read_b128 v[216:219], v151 offset:23552
	global_load_lds_dwordx4 v[196:197], off
	s_add_i32 m0, s80, 0x2000
	s_add_u32 s80, s46, 0x200000
	v_lshl_add_u64 v[220:221], s[46:47], 0, v[136:137]
	s_addc_u32 s81, s47, 0
	s_add_i32 s82, s62, s51
	global_load_lds_dwordx4 v[220:221], off
	v_lshl_add_u64 v[222:223], s[80:81], 0, v[132:133]
	s_mov_b32 m0, s82
	v_lshl_add_u64 v[224:225], s[48:49], 0, v[134:135]
	global_load_lds_dwordx4 v[222:223], off
	v_lshl_add_u64 v[222:223], s[80:81], 0, v[136:137]
	s_add_i32 m0, s82, 0x2000
	s_nop 0
	global_load_lds_dwordx4 v[222:223], off
	v_lshl_add_u64 v[222:223], s[48:49], 0, v[130:131]
	s_mov_b32 m0, s27
	s_nop 0
	global_load_lds_dwordx4 v[222:223], off
	s_mov_b32 m0, s52
	s_nop 0
	global_load_lds_dwordx4 v[224:225], off
	s_waitcnt vmcnt(8)
	s_waitcnt lgkmcnt(0)
	s_barrier
; #define PG8_STAGE(bufoff, gbase, voff) do { _Pragma("unroll") for (int _i = 0; _i < 2; ++_i) \
;         __builtin_amdgcn_global_load_lds((const unsigned*)((const char*)(gbase) + (voff)[_i]), (PG8_LAS unsigned*)(lds + (bufoff) + ldsw + _i * 8192), 16, 0, 0); } while (0)
; #define PG8_LDA(dst, b, h) do { _Pragma("unroll") for (int m = 0; m < 4; ++m) _Pragma("unroll") for (int k = 0; k < 2; ++k) dst[m][k] = *(const PG8_LAS bf16x8*)(lds + PG8_SA(b, h) + aoff + m * 2048 + k * 1024); } while (0)
; #define PG8_LDB(dst, b, h) do { _Pragma("unroll") for (int n = 0; n < 2; ++n) _Pragma("unroll") for (int k = 0; k < 2; ++k) dst[n][k] = *(const PG8_LAS bf16x8*)(lds + PG8_SB(b, h) + boff + n * 2048 + k * 1024); } while (0)
; #define PG8_MMA(ai, bj, At, Bt) do { __builtin_amdgcn_s_setprio(1); _Pragma("unroll") for (int m = 0; m < 4; ++m) _Pragma("unroll") for (int n = 0; n < 2; ++n) _Pragma("unroll") for (int k = 0; k < 2; ++k) \
;         acc[ai][bj][m][n] = __builtin_amdgcn_mfma_f32_16x16x32_bf16(Bt[n][k], At[m][k], acc[ai][bj][m][n], 0, 0, 0); __builtin_amdgcn_s_setprio(0); } while (0)
; #define PG8_BAR __builtin_amdgcn_s_barrier()
; template <class Epi, class Sched, bool ALIGN_EPI = false, bool SP2 = false, bool MID = false>
; __device__ __forceinline__ void gemm_phase(PG8_LAS unsigned char* lds, const Gemm g, const Sched& S, const Epi& E) {
;     ...
;             PG8_LDB(B0, 0, 0); PG8_LDB(B1, 0, 1); PG8_SCHED; PG8_LDA(At, 0, 0); PG8_STAGE(PG8_SA(1, 1), a1 + hstep, voffA);
;             PG8_WAIT_V(8); PG8_WAIT_L(0); PG8_BAR; PG8_MMA(0, 0, At, B0); PG8_MMA(0, 1, At, B1); PG8_BAR; PG8_SCHED;
;             PG8_LDA(At, 0, 1); PG8_STAGE(PG8_SB(0, 0), b2, voffB); PG8_STAGE(PG8_SB(0, 1), b2 + hstep, voffB); PG8_STAGE(PG8_SA(0, 0), a2, voffA);
;             PG8_WAIT_V(8); PG8_WAIT_L(0); PG8_BAR; PG8_MMA(1, 0, At, B0); PG8_MMA(1, 1, At, B1); PG8_BAR; PG8_SCHED;
;             PG8_LDB(B0, 1, 0); PG8_LDB(B1, 1, 1); PG8_SCHED; PG8_LDA(At, 1, 0); PG8_STAGE(PG8_SA(0, 1), a2 + hstep, voffA);
;             PG8_WAIT_V(8); PG8_WAIT_L(0); PG8_BAR; PG8_MMA(0, 0, At, B0); PG8_MMA(0, 1, At, B1); PG8_BAR; PG8_SCHED;
;             PG8_LDA(At, 1, 1); PG8_STAGE(PG8_SB(1, 0), b3, voffB); PG8_STAGE(PG8_SB(1, 1), b3 + hstep, voffB); PG8_STAGE(PG8_SA(1, 0), a3, voffA);
;             PG8_WAIT_V(8); PG8_WAIT_L(0); PG8_BAR; PG8_MMA(1, 0, At, B0); PG8_MMA(1, 1, At, B1); PG8_BAR; PG8_SCHED;
	s_waitcnt lgkmcnt(0)
	v_mfma_f32_16x16x32_bf16 v[62:65], v[152:155], v[184:187], v[62:65]
	v_mfma_f32_16x16x32_bf16 v[58:61], v[160:163], v[184:187], v[58:61]
	v_mfma_f32_16x16x32_bf16 v[54:57], v[152:155], v[192:195], v[54:57]
	v_mfma_f32_16x16x32_bf16 v[50:53], v[160:163], v[192:195], v[50:53]
	v_mfma_f32_16x16x32_bf16 v[38:41], v[152:155], v[204:207], v[38:41]
	v_mfma_f32_16x16x32_bf16 v[34:37], v[160:163], v[204:207], v[34:37]
	v_mfma_f32_16x16x32_bf16 v[22:25], v[152:155], v[212:215], v[22:25]
	v_mfma_f32_16x16x32_bf16 v[18:21], v[160:163], v[212:215], v[18:21]
	v_mfma_f32_16x16x32_bf16 v[62:65], v[156:159], v[188:191], v[62:65]
	v_mfma_f32_16x16x32_bf16 v[58:61], v[164:167], v[188:191], v[58:61]
	v_mfma_f32_16x16x32_bf16 v[54:57], v[156:159], v[200:203], v[54:57]
	v_mfma_f32_16x16x32_bf16 v[50:53], v[164:167], v[200:203], v[50:53]
	v_mfma_f32_16x16x32_bf16 v[38:41], v[156:159], v[208:211], v[38:41]
	v_mfma_f32_16x16x32_bf16 v[34:37], v[164:167], v[208:211], v[34:37]
	v_mfma_f32_16x16x32_bf16 v[22:25], v[156:159], v[216:219], v[22:25]
	v_mfma_f32_16x16x32_bf16 v[18:21], v[164:167], v[216:219], v[18:21]
	v_mfma_f32_16x16x32_bf16 v[46:49], v[168:171], v[184:187], v[46:49]
	v_mfma_f32_16x16x32_bf16 v[42:45], v[176:179], v[184:187], v[42:45]
	v_mfma_f32_16x16x32_bf16 v[30:33], v[168:171], v[192:195], v[30:33]
	v_mfma_f32_16x16x32_bf16 v[26:29], v[176:179], v[192:195], v[26:29]
	v_mfma_f32_16x16x32_bf16 v[14:17], v[168:171], v[204:207], v[14:17]
	v_mfma_f32_16x16x32_bf16 v[10:13], v[176:179], v[204:207], v[10:13]
	v_mfma_f32_16x16x32_bf16 v[6:9], v[168:171], v[212:215], v[6:9]
	v_mfma_f32_16x16x32_bf16 v[2:5], v[176:179], v[212:215], v[2:5]
	v_mfma_f32_16x16x32_bf16 v[46:49], v[172:175], v[188:191], v[46:49]
	v_mfma_f32_16x16x32_bf16 v[42:45], v[180:183], v[188:191], v[42:45]
	v_mfma_f32_16x16x32_bf16 v[30:33], v[172:175], v[200:203], v[30:33]
	v_mfma_f32_16x16x32_bf16 v[26:29], v[180:183], v[200:203], v[26:29]
	v_mfma_f32_16x16x32_bf16 v[14:17], v[172:175], v[208:211], v[14:17]
	v_mfma_f32_16x16x32_bf16 v[10:13], v[180:183], v[208:211], v[10:13]
	v_mfma_f32_16x16x32_bf16 v[6:9], v[172:175], v[216:219], v[6:9]
	v_mfma_f32_16x16x32_bf16 v[2:5], v[180:183], v[216:219], v[2:5]
	s_barrier
	s_add_i32 s80, 0, 0x18000
	s_add_i32 s81, 0, 0x1c000
	v_add_u32_e32 v164, s80, v147
	v_add_u32_e32 v180, s81, v147
	ds_read_b128 v[152:155], v164
	ds_read_b128 v[156:159], v164 offset:1024
	ds_read_b128 v[160:163], v164 offset:2048
	ds_read_b128 v[164:167], v164 offset:3072
	ds_read_b128 v[168:171], v180
	ds_read_b128 v[172:175], v180 offset:1024
	ds_read_b128 v[176:179], v180 offset:2048
	ds_read_b128 v[180:183], v180 offset:3072
	s_add_u32 s48, s48, 0x200000
	s_addc_u32 s49, s49, 0
	s_mov_b32 m0, s53
	v_lshl_add_u64 v[226:227], s[48:49], 0, v[130:131]
	ds_read_b128 v[184:187], v151 offset:32768
	ds_read_b128 v[188:191], v151 offset:33792
	ds_read_b128 v[192:195], v151 offset:34816
	ds_read_b128 v[200:203], v151 offset:35840
	ds_read_b128 v[204:207], v151 offset:36864
	ds_read_b128 v[208:211], v151 offset:37888
	ds_read_b128 v[212:215], v151 offset:38912
	ds_read_b128 v[216:219], v151 offset:39936
	global_load_lds_dwordx4 v[226:227], off
	v_lshl_add_u64 v[226:227], s[48:49], 0, v[134:135]
	s_mov_b32 m0, s54
	s_nop 0
	global_load_lds_dwordx4 v[226:227], off
	s_waitcnt vmcnt(8)
	s_waitcnt lgkmcnt(0)
	s_barrier
	s_waitcnt lgkmcnt(0)
	v_mfma_f32_16x16x32_bf16 v[126:129], v[152:155], v[184:187], v[126:129]
	v_mfma_f32_16x16x32_bf16 v[122:125], v[160:163], v[184:187], v[122:125]
	v_mfma_f32_16x16x32_bf16 v[118:121], v[152:155], v[192:195], v[118:121]
	v_mfma_f32_16x16x32_bf16 v[114:117], v[160:163], v[192:195], v[114:117]
	v_mfma_f32_16x16x32_bf16 v[102:105], v[152:155], v[204:207], v[102:105]
	v_mfma_f32_16x16x32_bf16 v[98:101], v[160:163], v[204:207], v[98:101]
	v_mfma_f32_16x16x32_bf16 v[86:89], v[152:155], v[212:215], v[86:89]
	v_mfma_f32_16x16x32_bf16 v[82:85], v[160:163], v[212:215], v[82:85]
	v_mfma_f32_16x16x32_bf16 v[126:129], v[156:159], v[188:191], v[126:129]
	v_mfma_f32_16x16x32_bf16 v[122:125], v[164:167], v[188:191], v[122:125]
	v_mfma_f32_16x16x32_bf16 v[118:121], v[156:159], v[200:203], v[118:121]
	v_mfma_f32_16x16x32_bf16 v[114:117], v[164:167], v[200:203], v[114:117]
	v_mfma_f32_16x16x32_bf16 v[102:105], v[156:159], v[208:211], v[102:105]
	v_mfma_f32_16x16x32_bf16 v[98:101], v[164:167], v[208:211], v[98:101]
	v_mfma_f32_16x16x32_bf16 v[86:89], v[156:159], v[216:219], v[86:89]
	v_mfma_f32_16x16x32_bf16 v[82:85], v[164:167], v[216:219], v[82:85]
	v_mfma_f32_16x16x32_bf16 v[110:113], v[168:171], v[184:187], v[110:113]
	v_mfma_f32_16x16x32_bf16 v[106:109], v[176:179], v[184:187], v[106:109]
	v_mfma_f32_16x16x32_bf16 v[94:97], v[168:171], v[192:195], v[94:97]
	v_mfma_f32_16x16x32_bf16 v[90:93], v[176:179], v[192:195], v[90:93]
	v_mfma_f32_16x16x32_bf16 v[78:81], v[168:171], v[204:207], v[78:81]
	v_mfma_f32_16x16x32_bf16 v[74:77], v[176:179], v[204:207], v[74:77]
	v_mfma_f32_16x16x32_bf16 v[70:73], v[168:171], v[212:215], v[70:73]
	v_mfma_f32_16x16x32_bf16 v[66:69], v[176:179], v[212:215], v[66:69]
	v_mfma_f32_16x16x32_bf16 v[110:113], v[172:175], v[188:191], v[110:113]
	v_mfma_f32_16x16x32_bf16 v[106:109], v[180:183], v[188:191], v[106:109]
	v_mfma_f32_16x16x32_bf16 v[94:97], v[172:175], v[200:203], v[94:97]
	v_mfma_f32_16x16x32_bf16 v[90:93], v[180:183], v[200:203], v[90:93]
	v_mfma_f32_16x16x32_bf16 v[78:81], v[172:175], v[208:211], v[78:81]
	v_mfma_f32_16x16x32_bf16 v[74:77], v[180:183], v[208:211], v[74:77]
	v_mfma_f32_16x16x32_bf16 v[70:73], v[172:175], v[216:219], v[70:73]
	v_mfma_f32_16x16x32_bf16 v[66:69], v[180:183], v[216:219], v[66:69]
	s_barrier
; #define PG8_STAGE(bufoff, gbase, voff) do { _Pragma("unroll") for (int _i = 0; _i < 2; ++_i) \
;         __builtin_amdgcn_global_load_lds((const unsigned*)((const char*)(gbase) + (voff)[_i]), (PG8_LAS unsigned*)(lds + (bufoff) + ldsw + _i * 8192), 16, 0, 0); } while (0)
; #define PG8_LDA(dst, b, h) do { _Pragma("unroll") for (int m = 0; m < 4; ++m) _Pragma("unroll") for (int k = 0; k < 2; ++k) dst[m][k] = *(const PG8_LAS bf16x8*)(lds + PG8_SA(b, h) + aoff + m * 2048 + k * 1024); } while (0)
; #define PG8_WAIT_V(n) asm volatile("s_waitcnt vmcnt(" #n ")" ::: "memory")
; template <class Epi, class Sched, bool ALIGN_EPI = false, bool SP2 = false, bool MID = false>
; __device__ __forceinline__ void gemm_phase(PG8_LAS unsigned char* lds, const Gemm g, const Sched& S, const Epi& E) {
;     ...
;         for (int t = 0; t < nt; t += 2) {
;             const bool last = (t == nt - 2);
;             if constexpr (MID) { if (t == Epi::MID_T) { PG8_SCHED; E.mid(acc, cur, wr, wc, fr, fq); PG8_SCHED; } }
;             const char* a1 = cA + (size_t)(t + 1) * kstep;
;             const char* a2 = last ? nA : cA + (size_t)(t + 2) * kstep; const char* b2 = last ? nB : cB + (size_t)(t + 2) * kstep;
;             const char* a3 = a2 + kstep; const char* b3 = b2 + kstep;
;             if (last && has_next) S.a_ready(nxt);
;             if constexpr (SP2) {
;             PG8_LDB(B0, 0, 0); PG8_LDB(B1, 0, 1); PG8_SCHED; PG8_LDA(At, 0, 0); PG8_STAGE(PG8_SA(1, 1), a1 + hstep, voffA);
;             PG8_WAIT_V(8); PG8_WAIT_L(0); PG8_BAR; PG8_MMA(0, 0, At, B0); PG8_MMA(0, 1, At, B1); PG8_BAR; PG8_SCHED;
;             PG8_LDA(At, 0, 1); PG8_STAGE(PG8_SB(0, 0), b2, voffB); PG8_STAGE(PG8_SB(0, 1), b2 + hstep, voffB); PG8_STAGE(PG8_SA(0, 0), a2, voffA);
;             PG8_WAIT_V(8); PG8_WAIT_L(0); PG8_BAR; PG8_MMA(1, 0, At, B0); PG8_MMA(1, 1, At, B1); PG8_BAR; PG8_SCHED;
;             PG8_LDB(B0, 1, 0); PG8_LDB(B1, 1, 1); PG8_SCHED; PG8_LDA(At, 1, 0); PG8_STAGE(PG8_SA(0, 1), a2 + hstep, voffA);
;             PG8_WAIT_V(8); PG8_WAIT_L(0); PG8_BAR; PG8_MMA(0, 0, At, B0); PG8_MMA(0, 1, At, B1); PG8_BAR; PG8_SCHED;
;             PG8_LDA(At, 1, 1); PG8_STAGE(PG8_SB(1, 0), b3, voffB); PG8_STAGE(PG8_SB(1, 1), b3 + hstep, voffB); PG8_STAGE(PG8_SA(1, 0), a3, voffA);
;             PG8_WAIT_V(8); PG8_WAIT_L(0); PG8_BAR; PG8_MMA(1, 0, At, B0); PG8_MMA(1, 1, At, B1); PG8_BAR; PG8_SCHED;
	s_add_i32 s48, s80, s51
	v_lshl_add_u64 v[196:197], v[196:197], 0, s[12:13]
	s_mov_b32 m0, s48
	ds_read_b128 v[184:187], v151 offset:49152
	ds_read_b128 v[188:191], v151 offset:50176
	ds_read_b128 v[192:195], v151 offset:51200
	ds_read_b128 v[200:203], v151 offset:52224
	ds_read_b128 v[204:207], v151 offset:53248
	ds_read_b128 v[208:211], v151 offset:54272
	ds_read_b128 v[212:215], v151 offset:55296
	ds_read_b128 v[216:219], v151 offset:56320
	global_load_lds_dwordx4 v[196:197], off
	s_add_i32 m0, s48, 0x2000
	s_add_u32 s46, s46, 0x200080
	v_lshl_add_u64 v[196:197], v[220:221], 0, s[12:13]
	s_addc_u32 s47, s47, 0
	s_add_i32 s48, s81, s51
	global_load_lds_dwordx4 v[196:197], off
	v_lshl_add_u64 v[196:197], s[46:47], 0, v[132:133]
	s_mov_b32 m0, s48
	s_nop 0
	global_load_lds_dwordx4 v[196:197], off
	v_lshl_add_u64 v[196:197], s[46:47], 0, v[136:137]
	s_add_i32 m0, s48, 0x2000
	s_nop 0
	global_load_lds_dwordx4 v[196:197], off
	v_lshl_add_u64 v[196:197], v[222:223], 0, s[12:13]
	s_mov_b32 m0, s56
	s_nop 0
	global_load_lds_dwordx4 v[196:197], off
	v_lshl_add_u64 v[196:197], v[224:225], 0, s[12:13]
	s_mov_b32 m0, s57
	s_nop 0
	global_load_lds_dwordx4 v[196:197], off
	s_waitcnt vmcnt(8)
	s_waitcnt lgkmcnt(0)
	s_barrier
	s_waitcnt lgkmcnt(0)
	v_mfma_f32_16x16x32_bf16 v[62:65], v[152:155], v[184:187], v[62:65]
	v_mfma_f32_16x16x32_bf16 v[58:61], v[160:163], v[184:187], v[58:61]
	v_mfma_f32_16x16x32_bf16 v[54:57], v[152:155], v[192:195], v[54:57]
	v_mfma_f32_16x16x32_bf16 v[50:53], v[160:163], v[192:195], v[50:53]
	v_mfma_f32_16x16x32_bf16 v[38:41], v[152:155], v[204:207], v[38:41]
	v_mfma_f32_16x16x32_bf16 v[34:37], v[160:163], v[204:207], v[34:37]
	v_mfma_f32_16x16x32_bf16 v[22:25], v[152:155], v[212:215], v[22:25]
	v_mfma_f32_16x16x32_bf16 v[18:21], v[160:163], v[212:215], v[18:21]
	v_mfma_f32_16x16x32_bf16 v[62:65], v[156:159], v[188:191], v[62:65]
	v_mfma_f32_16x16x32_bf16 v[58:61], v[164:167], v[188:191], v[58:61]
	v_mfma_f32_16x16x32_bf16 v[54:57], v[156:159], v[200:203], v[54:57]
	v_mfma_f32_16x16x32_bf16 v[50:53], v[164:167], v[200:203], v[50:53]
	v_mfma_f32_16x16x32_bf16 v[38:41], v[156:159], v[208:211], v[38:41]
	v_mfma_f32_16x16x32_bf16 v[34:37], v[164:167], v[208:211], v[34:37]
	v_mfma_f32_16x16x32_bf16 v[22:25], v[156:159], v[216:219], v[22:25]
	v_mfma_f32_16x16x32_bf16 v[18:21], v[164:167], v[216:219], v[18:21]
	v_mfma_f32_16x16x32_bf16 v[46:49], v[168:171], v[184:187], v[46:49]
	v_mfma_f32_16x16x32_bf16 v[42:45], v[176:179], v[184:187], v[42:45]
	v_mfma_f32_16x16x32_bf16 v[30:33], v[168:171], v[192:195], v[30:33]
	v_mfma_f32_16x16x32_bf16 v[26:29], v[176:179], v[192:195], v[26:29]
	v_mfma_f32_16x16x32_bf16 v[14:17], v[168:171], v[204:207], v[14:17]
	v_mfma_f32_16x16x32_bf16 v[10:13], v[176:179], v[204:207], v[10:13]
	v_mfma_f32_16x16x32_bf16 v[6:9], v[168:171], v[212:215], v[6:9]
	v_mfma_f32_16x16x32_bf16 v[2:5], v[176:179], v[212:215], v[2:5]
	v_mfma_f32_16x16x32_bf16 v[46:49], v[172:175], v[188:191], v[46:49]
	v_mfma_f32_16x16x32_bf16 v[42:45], v[180:183], v[188:191], v[42:45]
	v_mfma_f32_16x16x32_bf16 v[30:33], v[172:175], v[200:203], v[30:33]
	v_mfma_f32_16x16x32_bf16 v[26:29], v[180:183], v[200:203], v[26:29]
	v_mfma_f32_16x16x32_bf16 v[14:17], v[172:175], v[208:211], v[14:17]
	v_mfma_f32_16x16x32_bf16 v[10:13], v[180:183], v[208:211], v[10:13]
	v_mfma_f32_16x16x32_bf16 v[6:9], v[172:175], v[216:219], v[6:9]
	v_mfma_f32_16x16x32_bf16 v[2:5], v[180:183], v[216:219], v[2:5]
	s_barrier
	s_add_i32 s79, s79, 2
	s_add_u32 s44, s44, 0x100
	s_addc_u32 s45, s45, 0
	s_add_u32 s77, s77, 0x100
	s_addc_u32 s78, s78, 0
	s_cmpk_gt_u32 s79, 0x7d
	s_cbranch_scc0 .LBB0_1772
	s_and_b64 vcc, exec, s[16:17]
	s_cbranch_vccz .LBB0_1775
	s_barrier

; #define PG8_STAGE(bufoff, gbase, voff) do { _Pragma("unroll") for (int _i = 0; _i < 2; ++_i) \
;         __builtin_amdgcn_global_load_lds((const unsigned*)((const char*)(gbase) + (voff)[_i]), (PG8_LAS unsigned*)(lds + (bufoff) + ldsw + _i * 8192), 16, 0, 0); } while (0)
; #define PG8_LDA(dst, b, h) do { _Pragma("unroll") for (int m = 0; m < 4; ++m) _Pragma("unroll") for (int k = 0; k < 2; ++k) dst[m][k] = *(const PG8_LAS bf16x8*)(lds + PG8_SA(b, h) + aoff + m * 2048 + k * 1024); } while (0)
; #define PG8_WAIT_V(n) asm volatile("s_waitcnt vmcnt(" #n ")" ::: "memory")
; template <class Epi, class Sched, bool ALIGN_EPI = false, bool SP2 = false, bool MID = false>
; __device__ __forceinline__ void gemm_phase(PG8_LAS unsigned char* lds, const Gemm g, const Sched& S, const Epi& E) {
;     ...
;         for (int t = 0; t < nt; t += 2) {
;             const bool last = (t == nt - 2);
;             if constexpr (MID) { if (t == Epi::MID_T) { PG8_SCHED; E.mid(acc, cur, wr, wc, fr, fq); PG8_SCHED; } }
;             const char* a1 = cA + (size_t)(t + 1) * kstep;
;             const char* a2 = last ? nA : cA + (size_t)(t + 2) * kstep; const char* b2 = last ? nB : cB + (size_t)(t + 2) * kstep;
;             const char* a3 = a2 + kstep; const char* b3 = b2 + kstep;
;             if (last && has_next) S.a_ready(nxt);
;             if constexpr (SP2) {
;             PG8_LDB(B0, 0, 0); PG8_LDB(B1, 0, 1); PG8_SCHED; PG8_LDA(At, 0, 0); PG8_STAGE(PG8_SA(1, 1), a1 + hstep, voffA);
;             PG8_WAIT_V(8); PG8_WAIT_L(0); PG8_BAR; PG8_MMA(0, 0, At, B0); PG8_MMA(0, 1, At, B1); PG8_BAR; PG8_SCHED;
;             PG8_LDA(At, 0, 1); PG8_STAGE(PG8_SB(0, 0), b2, voffB); PG8_STAGE(PG8_SB(0, 1), b2 + hstep, voffB); PG8_STAGE(PG8_SA(0, 0), a2, voffA);
;             PG8_WAIT_V(8); PG8_WAIT_L(0); PG8_BAR; PG8_MMA(1, 0, At, B0); PG8_MMA(1, 1, At, B1); PG8_BAR; PG8_SCHED;
;             PG8_LDB(B0, 1, 0); PG8_LDB(B1, 1, 1); PG8_SCHED; PG8_LDA(At, 1, 0); PG8_STAGE(PG8_SA(0, 1), a2 + hstep, voffA);
;             PG8_WAIT_V(8); PG8_WAIT_L(0); PG8_BAR; PG8_MMA(0, 0, At, B0); PG8_MMA(0, 1, At, B1); PG8_BAR; PG8_SCHED;
;             PG8_LDA(At, 1, 1); PG8_STAGE(PG8_SB(1, 0), b3, voffB); PG8_STAGE(PG8_SB(1, 1), b3 + hstep, voffB); PG8_STAGE(PG8_SA(1, 0), a3, voffA);
;             PG8_WAIT_V(8); PG8_WAIT_L(0); PG8_BAR; PG8_MMA(1, 0, At, B0); PG8_MMA(1, 1, At, B1); PG8_BAR; PG8_SCHED;
.LBB0_1937:
	s_add_u32 s26, s22, s24
	s_addc_u32 s27, s23, s25
	s_add_u32 s26, s26, 0x100
	s_addc_u32 s27, s27, 0
	s_add_u32 s73, s62, s24
	s_addc_u32 s74, s70, s25
	s_add_i32 s72, 0, 0x10000
	v_add_u32_e32 v133, s72, v161
	ds_read_b128 v[156:159], v133
	ds_read_b128 v[164:167], v133 offset:1024
	ds_read_b128 v[168:171], v133 offset:2048
	ds_read_b128 v[172:175], v133 offset:3072
	v_add_u32_e32 v133, s57, v161
	ds_read_b128 v[176:179], v133
	ds_read_b128 v[180:183], v133 offset:1024
	ds_read_b128 v[184:187], v133 offset:2048
	ds_read_b128 v[188:191], v133 offset:3072
	s_cmpk_eq_i32 s24, 0x1100
	s_cselect_b32 s37, s5, s27
	s_cselect_b32 s36, s4, s26
	s_cselect_b32 s27, s21, s74
	s_cselect_b32 s26, s20, s73
	v_lshl_add_u64 v[196:197], v[152:153], 0, s[24:25]
	s_add_i32 m0, s42, 0xc000
	ds_read_b128 v[192:195], v163
	ds_read_b128 v[200:203], v163 offset:1024
	ds_read_b128 v[204:207], v163 offset:2048
	ds_read_b128 v[208:211], v163 offset:3072
	ds_read_b128 v[212:215], v163 offset:4096
	ds_read_b128 v[216:219], v163 offset:5120
	ds_read_b128 v[220:223], v163 offset:6144
	ds_read_b128 v[224:227], v163 offset:7168
	global_load_lds_dwordx4 v[196:197], off
	v_lshl_add_u64 v[196:197], v[154:155], 0, s[24:25]
	s_add_i32 m0, s42, 0xe000
	s_nop 0
	global_load_lds_dwordx4 v[196:197], off
	s_waitcnt vmcnt(8)
	s_waitcnt lgkmcnt(0)
	s_barrier
	s_waitcnt lgkmcnt(0)
	v_mfma_f32_16x16x32_bf16 v[126:129], v[156:159], v[192:195], v[126:129]
	v_mfma_f32_16x16x32_bf16 v[122:125], v[168:171], v[192:195], v[122:125]
	v_mfma_f32_16x16x32_bf16 v[110:113], v[156:159], v[204:207], v[110:113]
	v_mfma_f32_16x16x32_bf16 v[106:109], v[168:171], v[204:207], v[106:109]
	v_mfma_f32_16x16x32_bf16 v[94:97], v[156:159], v[212:215], v[94:97]
	v_mfma_f32_16x16x32_bf16 v[90:93], v[168:171], v[212:215], v[90:93]
	v_mfma_f32_16x16x32_bf16 v[78:81], v[156:159], v[220:223], v[78:81]
	v_mfma_f32_16x16x32_bf16 v[74:77], v[168:171], v[220:223], v[74:77]
	v_mfma_f32_16x16x32_bf16 v[126:129], v[164:167], v[200:203], v[126:129]
	v_mfma_f32_16x16x32_bf16 v[122:125], v[172:175], v[200:203], v[122:125]
	v_mfma_f32_16x16x32_bf16 v[110:113], v[164:167], v[208:211], v[110:113]
	v_mfma_f32_16x16x32_bf16 v[106:109], v[172:175], v[208:211], v[106:109]
	v_mfma_f32_16x16x32_bf16 v[94:97], v[164:167], v[216:219], v[94:97]
	v_mfma_f32_16x16x32_bf16 v[90:93], v[172:175], v[216:219], v[90:93]
	v_mfma_f32_16x16x32_bf16 v[78:81], v[164:167], v[224:227], v[78:81]
	v_mfma_f32_16x16x32_bf16 v[74:77], v[172:175], v[224:227], v[74:77]
	v_mfma_f32_16x16x32_bf16 v[118:121], v[176:179], v[192:195], v[118:121]
	v_mfma_f32_16x16x32_bf16 v[114:117], v[184:187], v[192:195], v[114:117]
	v_mfma_f32_16x16x32_bf16 v[102:105], v[176:179], v[204:207], v[102:105]
	v_mfma_f32_16x16x32_bf16 v[98:101], v[184:187], v[204:207], v[98:101]
	v_mfma_f32_16x16x32_bf16 v[86:89], v[176:179], v[212:215], v[86:89]
	v_mfma_f32_16x16x32_bf16 v[82:85], v[184:187], v[212:215], v[82:85]
	v_mfma_f32_16x16x32_bf16 v[70:73], v[176:179], v[220:223], v[70:73]
	v_mfma_f32_16x16x32_bf16 v[66:69], v[184:187], v[220:223], v[66:69]
	v_mfma_f32_16x16x32_bf16 v[118:121], v[180:183], v[200:203], v[118:121]
	v_mfma_f32_16x16x32_bf16 v[114:117], v[188:191], v[200:203], v[114:117]
	v_mfma_f32_16x16x32_bf16 v[102:105], v[180:183], v[208:211], v[102:105]
	v_mfma_f32_16x16x32_bf16 v[98:101], v[188:191], v[208:211], v[98:101]
	v_mfma_f32_16x16x32_bf16 v[86:89], v[180:183], v[216:219], v[86:89]
	v_mfma_f32_16x16x32_bf16 v[82:85], v[188:191], v[216:219], v[82:85]
	v_mfma_f32_16x16x32_bf16 v[70:73], v[180:183], v[224:227], v[70:73]
	v_mfma_f32_16x16x32_bf16 v[66:69], v[188:191], v[224:227], v[66:69]
	s_barrier
	s_add_i32 s72, s72, s41
	v_lshl_add_u64 v[196:197], s[26:27], 0, v[136:137]
	s_mov_b32 m0, s72
	ds_read_b128 v[192:195], v163 offset:16384
	ds_read_b128 v[200:203], v163 offset:17408
	ds_read_b128 v[204:207], v163 offset:18432
	ds_read_b128 v[208:211], v163 offset:19456
	ds_read_b128 v[212:215], v163 offset:20480
	ds_read_b128 v[216:219], v163 offset:21504
	ds_read_b128 v[220:223], v163 offset:22528
	ds_read_b128 v[224:227], v163 offset:23552
	global_load_lds_dwordx4 v[196:197], off
	s_add_i32 m0, s72, 0x2000
	s_add_u32 s72, s26, 0x90000
	v_lshl_add_u64 v[228:229], s[26:27], 0, v[140:141]
	s_addc_u32 s73, s27, 0
	s_add_i32 s74, s57, s41
	global_load_lds_dwordx4 v[228:229], off
	v_lshl_add_u64 v[230:231], s[72:73], 0, v[136:137]
	s_mov_b32 m0, s74
	v_lshl_add_u64 v[232:233], s[36:37], 0, v[138:139]
	global_load_lds_dwordx4 v[230:231], off
	v_lshl_add_u64 v[230:231], s[72:73], 0, v[140:141]
	s_add_i32 m0, s74, 0x2000
	s_nop 0
	global_load_lds_dwordx4 v[230:231], off
	v_lshl_add_u64 v[230:231], s[36:37], 0, v[134:135]
	s_mov_b32 m0, s42
	s_nop 0
	global_load_lds_dwordx4 v[230:231], off
	s_mov_b32 m0, s43
	s_nop 0
	global_load_lds_dwordx4 v[232:233], off
	s_waitcnt vmcnt(8)
	s_waitcnt lgkmcnt(0)
	s_barrier
; #define PG8_STAGE(bufoff, gbase, voff) do { _Pragma("unroll") for (int _i = 0; _i < 2; ++_i) \
;         __builtin_amdgcn_global_load_lds((const unsigned*)((const char*)(gbase) + (voff)[_i]), (PG8_LAS unsigned*)(lds + (bufoff) + ldsw + _i * 8192), 16, 0, 0); } while (0)
; #define PG8_LDA(dst, b, h) do { _Pragma("unroll") for (int m = 0; m < 4; ++m) _Pragma("unroll") for (int k = 0; k < 2; ++k) dst[m][k] = *(const PG8_LAS bf16x8*)(lds + PG8_SA(b, h) + aoff + m * 2048 + k * 1024); } while (0)
; #define PG8_LDB(dst, b, h) do { _Pragma("unroll") for (int n = 0; n < 2; ++n) _Pragma("unroll") for (int k = 0; k < 2; ++k) dst[n][k] = *(const PG8_LAS bf16x8*)(lds + PG8_SB(b, h) + boff + n * 2048 + k * 1024); } while (0)
; #define PG8_MMA(ai, bj, At, Bt) do { __builtin_amdgcn_s_setprio(1); _Pragma("unroll") for (int m = 0; m < 4; ++m) _Pragma("unroll") for (int n = 0; n < 2; ++n) _Pragma("unroll") for (int k = 0; k < 2; ++k) \
;         acc[ai][bj][m][n] = __builtin_amdgcn_mfma_f32_16x16x32_bf16(Bt[n][k], At[m][k], acc[ai][bj][m][n], 0, 0, 0); __builtin_amdgcn_s_setprio(0); } while (0)
; #define PG8_BAR __builtin_amdgcn_s_barrier()
; template <class Epi, class Sched, bool ALIGN_EPI = false, bool SP2 = false, bool MID = false>
; __device__ __forceinline__ void gemm_phase(PG8_LAS unsigned char* lds, const Gemm g, const Sched& S, const Epi& E) {
;     ...
;             PG8_LDB(B0, 0, 0); PG8_LDB(B1, 0, 1); PG8_SCHED; PG8_LDA(At, 0, 0); PG8_STAGE(PG8_SA(1, 1), a1 + hstep, voffA);
;             PG8_WAIT_V(8); PG8_WAIT_L(0); PG8_BAR; PG8_MMA(0, 0, At, B0); PG8_MMA(0, 1, At, B1); PG8_BAR; PG8_SCHED;
;             PG8_LDA(At, 0, 1); PG8_STAGE(PG8_SB(0, 0), b2, voffB); PG8_STAGE(PG8_SB(0, 1), b2 + hstep, voffB); PG8_STAGE(PG8_SA(0, 0), a2, voffA);
;             PG8_WAIT_V(8); PG8_WAIT_L(0); PG8_BAR; PG8_MMA(1, 0, At, B0); PG8_MMA(1, 1, At, B1); PG8_BAR; PG8_SCHED;
;             PG8_LDB(B0, 1, 0); PG8_LDB(B1, 1, 1); PG8_SCHED; PG8_LDA(At, 1, 0); PG8_STAGE(PG8_SA(0, 1), a2 + hstep, voffA);
;             PG8_WAIT_V(8); PG8_WAIT_L(0); PG8_BAR; PG8_MMA(0, 0, At, B0); PG8_MMA(0, 1, At, B1); PG8_BAR; PG8_SCHED;
;             PG8_LDA(At, 1, 1); PG8_STAGE(PG8_SB(1, 0), b3, voffB); PG8_STAGE(PG8_SB(1, 1), b3 + hstep, voffB); PG8_STAGE(PG8_SA(1, 0), a3, voffA);
;             PG8_WAIT_V(8); PG8_WAIT_L(0); PG8_BAR; PG8_MMA(1, 0, At, B0); PG8_MMA(1, 1, At, B1); PG8_BAR; PG8_SCHED;
	s_waitcnt lgkmcnt(0)
	v_mfma_f32_16x16x32_bf16 v[62:65], v[156:159], v[192:195], v[62:65]
	v_mfma_f32_16x16x32_bf16 v[58:61], v[168:171], v[192:195], v[58:61]
	v_mfma_f32_16x16x32_bf16 v[46:49], v[156:159], v[204:207], v[46:49]
	v_mfma_f32_16x16x32_bf16 v[42:45], v[168:171], v[204:207], v[42:45]
	v_mfma_f32_16x16x32_bf16 v[30:33], v[156:159], v[212:215], v[30:33]
	v_mfma_f32_16x16x32_bf16 v[26:29], v[168:171], v[212:215], v[26:29]
	v_mfma_f32_16x16x32_bf16 v[14:17], v[156:159], v[220:223], v[14:17]
	v_mfma_f32_16x16x32_bf16 v[10:13], v[168:171], v[220:223], v[10:13]
	v_mfma_f32_16x16x32_bf16 v[62:65], v[164:167], v[200:203], v[62:65]
	v_mfma_f32_16x16x32_bf16 v[58:61], v[172:175], v[200:203], v[58:61]
	v_mfma_f32_16x16x32_bf16 v[46:49], v[164:167], v[208:211], v[46:49]
	v_mfma_f32_16x16x32_bf16 v[42:45], v[172:175], v[208:211], v[42:45]
	v_mfma_f32_16x16x32_bf16 v[30:33], v[164:167], v[216:219], v[30:33]
	v_mfma_f32_16x16x32_bf16 v[26:29], v[172:175], v[216:219], v[26:29]
	v_mfma_f32_16x16x32_bf16 v[14:17], v[164:167], v[224:227], v[14:17]
	v_mfma_f32_16x16x32_bf16 v[10:13], v[172:175], v[224:227], v[10:13]
	v_mfma_f32_16x16x32_bf16 v[54:57], v[176:179], v[192:195], v[54:57]
	v_mfma_f32_16x16x32_bf16 v[50:53], v[184:187], v[192:195], v[50:53]
	v_mfma_f32_16x16x32_bf16 v[38:41], v[176:179], v[204:207], v[38:41]
	v_mfma_f32_16x16x32_bf16 v[34:37], v[184:187], v[204:207], v[34:37]
	v_mfma_f32_16x16x32_bf16 v[22:25], v[176:179], v[212:215], v[22:25]
	v_mfma_f32_16x16x32_bf16 v[18:21], v[184:187], v[212:215], v[18:21]
	v_mfma_f32_16x16x32_bf16 v[6:9], v[176:179], v[220:223], v[6:9]
	v_mfma_f32_16x16x32_bf16 v[2:5], v[184:187], v[220:223], v[2:5]
	v_mfma_f32_16x16x32_bf16 v[54:57], v[180:183], v[200:203], v[54:57]
	v_mfma_f32_16x16x32_bf16 v[50:53], v[188:191], v[200:203], v[50:53]
	v_mfma_f32_16x16x32_bf16 v[38:41], v[180:183], v[208:211], v[38:41]
	v_mfma_f32_16x16x32_bf16 v[34:37], v[188:191], v[208:211], v[34:37]
	v_mfma_f32_16x16x32_bf16 v[22:25], v[180:183], v[216:219], v[22:25]
	v_mfma_f32_16x16x32_bf16 v[18:21], v[188:191], v[216:219], v[18:21]
	v_mfma_f32_16x16x32_bf16 v[6:9], v[180:183], v[224:227], v[6:9]
	v_mfma_f32_16x16x32_bf16 v[2:5], v[188:191], v[224:227], v[2:5]
	s_barrier
	s_add_i32 s72, 0, 0x18000
	v_add_u32_e32 v133, s72, v161
	s_add_i32 s73, 0, 0x1c000
	ds_read_b128 v[156:159], v133
	ds_read_b128 v[164:167], v133 offset:1024
	ds_read_b128 v[168:171], v133 offset:2048
	ds_read_b128 v[172:175], v133 offset:3072
	v_add_u32_e32 v133, s73, v161
	ds_read_b128 v[176:179], v133
	ds_read_b128 v[180:183], v133 offset:1024
	ds_read_b128 v[184:187], v133 offset:2048
	ds_read_b128 v[188:191], v133 offset:3072
	s_add_u32 s36, s36, 0x90000
	s_addc_u32 s37, s37, 0
	s_mov_b32 m0, s44
	v_lshl_add_u64 v[234:235], s[36:37], 0, v[134:135]
	ds_read_b128 v[192:195], v163 offset:32768
	ds_read_b128 v[200:203], v163 offset:33792
	ds_read_b128 v[204:207], v163 offset:34816
	ds_read_b128 v[208:211], v163 offset:35840
	ds_read_b128 v[212:215], v163 offset:36864
	ds_read_b128 v[216:219], v163 offset:37888
	ds_read_b128 v[220:223], v163 offset:38912
	ds_read_b128 v[224:227], v163 offset:39936
	global_load_lds_dwordx4 v[234:235], off
	v_lshl_add_u64 v[234:235], s[36:37], 0, v[138:139]
	s_mov_b32 m0, s45
	s_nop 0
	global_load_lds_dwordx4 v[234:235], off
	s_waitcnt vmcnt(8)
	s_waitcnt lgkmcnt(0)
	s_barrier
	s_waitcnt lgkmcnt(0)
	v_mfma_f32_16x16x32_bf16 v[126:129], v[156:159], v[192:195], v[126:129]
	v_mfma_f32_16x16x32_bf16 v[122:125], v[168:171], v[192:195], v[122:125]
	v_mfma_f32_16x16x32_bf16 v[110:113], v[156:159], v[204:207], v[110:113]
	v_mfma_f32_16x16x32_bf16 v[106:109], v[168:171], v[204:207], v[106:109]
	v_mfma_f32_16x16x32_bf16 v[94:97], v[156:159], v[212:215], v[94:97]
	v_mfma_f32_16x16x32_bf16 v[90:93], v[168:171], v[212:215], v[90:93]
	v_mfma_f32_16x16x32_bf16 v[78:81], v[156:159], v[220:223], v[78:81]
	v_mfma_f32_16x16x32_bf16 v[74:77], v[168:171], v[220:223], v[74:77]
	v_mfma_f32_16x16x32_bf16 v[126:129], v[164:167], v[200:203], v[126:129]
	v_mfma_f32_16x16x32_bf16 v[122:125], v[172:175], v[200:203], v[122:125]
	v_mfma_f32_16x16x32_bf16 v[110:113], v[164:167], v[208:211], v[110:113]
	v_mfma_f32_16x16x32_bf16 v[106:109], v[172:175], v[208:211], v[106:109]
	v_mfma_f32_16x16x32_bf16 v[94:97], v[164:167], v[216:219], v[94:97]
	v_mfma_f32_16x16x32_bf16 v[90:93], v[172:175], v[216:219], v[90:93]
	v_mfma_f32_16x16x32_bf16 v[78:81], v[164:167], v[224:227], v[78:81]
	v_mfma_f32_16x16x32_bf16 v[74:77], v[172:175], v[224:227], v[74:77]
	v_mfma_f32_16x16x32_bf16 v[118:121], v[176:179], v[192:195], v[118:121]
	v_mfma_f32_16x16x32_bf16 v[114:117], v[184:187], v[192:195], v[114:117]
	v_mfma_f32_16x16x32_bf16 v[102:105], v[176:179], v[204:207], v[102:105]
	v_mfma_f32_16x16x32_bf16 v[98:101], v[184:187], v[204:207], v[98:101]
	v_mfma_f32_16x16x32_bf16 v[86:89], v[176:179], v[212:215], v[86:89]
	v_mfma_f32_16x16x32_bf16 v[82:85], v[184:187], v[212:215], v[82:85]
	v_mfma_f32_16x16x32_bf16 v[70:73], v[176:179], v[220:223], v[70:73]
	v_mfma_f32_16x16x32_bf16 v[66:69], v[184:187], v[220:223], v[66:69]
	v_mfma_f32_16x16x32_bf16 v[118:121], v[180:183], v[200:203], v[118:121]
	v_mfma_f32_16x16x32_bf16 v[114:117], v[188:191], v[200:203], v[114:117]
	v_mfma_f32_16x16x32_bf16 v[102:105], v[180:183], v[208:211], v[102:105]
	v_mfma_f32_16x16x32_bf16 v[98:101], v[188:191], v[208:211], v[98:101]
	v_mfma_f32_16x16x32_bf16 v[86:89], v[180:183], v[216:219], v[86:89]
	v_mfma_f32_16x16x32_bf16 v[82:85], v[188:191], v[216:219], v[82:85]
	v_mfma_f32_16x16x32_bf16 v[70:73], v[180:183], v[224:227], v[70:73]
	v_mfma_f32_16x16x32_bf16 v[66:69], v[188:191], v[224:227], v[66:69]
	s_barrier
; #define PG8_STAGE(bufoff, gbase, voff) do { _Pragma("unroll") for (int _i = 0; _i < 2; ++_i) \
;         __builtin_amdgcn_global_load_lds((const unsigned*)((const char*)(gbase) + (voff)[_i]), (PG8_LAS unsigned*)(lds + (bufoff) + ldsw + _i * 8192), 16, 0, 0); } while (0)
; #define PG8_LDA(dst, b, h) do { _Pragma("unroll") for (int m = 0; m < 4; ++m) _Pragma("unroll") for (int k = 0; k < 2; ++k) dst[m][k] = *(const PG8_LAS bf16x8*)(lds + PG8_SA(b, h) + aoff + m * 2048 + k * 1024); } while (0)
; #define PG8_WAIT_V(n) asm volatile("s_waitcnt vmcnt(" #n ")" ::: "memory")
; template <class Epi, class Sched, bool ALIGN_EPI = false, bool SP2 = false, bool MID = false>
; __device__ __forceinline__ void gemm_phase(PG8_LAS unsigned char* lds, const Gemm g, const Sched& S, const Epi& E) {
;     ...
;         for (int t = 0; t < nt; t += 2) {
;             const bool last = (t == nt - 2);
;             if constexpr (MID) { if (t == Epi::MID_T) { PG8_SCHED; E.mid(acc, cur, wr, wc, fr, fq); PG8_SCHED; } }
;             const char* a1 = cA + (size_t)(t + 1) * kstep;
;             const char* a2 = last ? nA : cA + (size_t)(t + 2) * kstep; const char* b2 = last ? nB : cB + (size_t)(t + 2) * kstep;
;             const char* a3 = a2 + kstep; const char* b3 = b2 + kstep;
;             if (last && has_next) S.a_ready(nxt);
;             if constexpr (SP2) {
;             PG8_LDB(B0, 0, 0); PG8_LDB(B1, 0, 1); PG8_SCHED; PG8_LDA(At, 0, 0); PG8_STAGE(PG8_SA(1, 1), a1 + hstep, voffA);
;             PG8_WAIT_V(8); PG8_WAIT_L(0); PG8_BAR; PG8_MMA(0, 0, At, B0); PG8_MMA(0, 1, At, B1); PG8_BAR; PG8_SCHED;
;             PG8_LDA(At, 0, 1); PG8_STAGE(PG8_SB(0, 0), b2, voffB); PG8_STAGE(PG8_SB(0, 1), b2 + hstep, voffB); PG8_STAGE(PG8_SA(0, 0), a2, voffA);
;             PG8_WAIT_V(8); PG8_WAIT_L(0); PG8_BAR; PG8_MMA(1, 0, At, B0); PG8_MMA(1, 1, At, B1); PG8_BAR; PG8_SCHED;
;             PG8_LDB(B0, 1, 0); PG8_LDB(B1, 1, 1); PG8_SCHED; PG8_LDA(At, 1, 0); PG8_STAGE(PG8_SA(0, 1), a2 + hstep, voffA);
;             PG8_WAIT_V(8); PG8_WAIT_L(0); PG8_BAR; PG8_MMA(0, 0, At, B0); PG8_MMA(0, 1, At, B1); PG8_BAR; PG8_SCHED;
;             PG8_LDA(At, 1, 1); PG8_STAGE(PG8_SB(1, 0), b3, voffB); PG8_STAGE(PG8_SB(1, 1), b3 + hstep, voffB); PG8_STAGE(PG8_SA(1, 0), a3, voffA);
;             PG8_WAIT_V(8); PG8_WAIT_L(0); PG8_BAR; PG8_MMA(1, 0, At, B0); PG8_MMA(1, 1, At, B1); PG8_BAR; PG8_SCHED;
	s_add_i32 s36, s72, s41
	v_lshl_add_u64 v[196:197], v[196:197], 0, s[16:17]
	s_mov_b32 m0, s36
	ds_read_b128 v[192:195], v163 offset:49152
	ds_read_b128 v[200:203], v163 offset:50176
	ds_read_b128 v[204:207], v163 offset:51200
	ds_read_b128 v[208:211], v163 offset:52224
	ds_read_b128 v[212:215], v163 offset:53248
	ds_read_b128 v[216:219], v163 offset:54272
	ds_read_b128 v[220:223], v163 offset:55296
	ds_read_b128 v[224:227], v163 offset:56320
	global_load_lds_dwordx4 v[196:197], off
	s_add_i32 m0, s36, 0x2000
	s_add_u32 s26, s26, 0x90080
	v_lshl_add_u64 v[196:197], v[228:229], 0, s[16:17]
	s_addc_u32 s27, s27, 0
	s_add_i32 s36, s73, s41
	global_load_lds_dwordx4 v[196:197], off
	v_lshl_add_u64 v[196:197], s[26:27], 0, v[136:137]
	s_mov_b32 m0, s36
	s_nop 0
	global_load_lds_dwordx4 v[196:197], off
	v_lshl_add_u64 v[196:197], s[26:27], 0, v[140:141]
	s_add_i32 m0, s36, 0x2000
	s_nop 0
	global_load_lds_dwordx4 v[196:197], off
	v_lshl_add_u64 v[196:197], v[230:231], 0, s[16:17]
	s_mov_b32 m0, s48
	s_nop 0
	global_load_lds_dwordx4 v[196:197], off
	v_lshl_add_u64 v[196:197], v[232:233], 0, s[16:17]
	s_mov_b32 m0, s49
	s_nop 0
	global_load_lds_dwordx4 v[196:197], off
	s_waitcnt vmcnt(8)
	s_waitcnt lgkmcnt(0)
	s_barrier
	s_waitcnt lgkmcnt(0)
	v_mfma_f32_16x16x32_bf16 v[62:65], v[156:159], v[192:195], v[62:65]
	v_mfma_f32_16x16x32_bf16 v[58:61], v[168:171], v[192:195], v[58:61]
	v_mfma_f32_16x16x32_bf16 v[46:49], v[156:159], v[204:207], v[46:49]
	v_mfma_f32_16x16x32_bf16 v[42:45], v[168:171], v[204:207], v[42:45]
	v_mfma_f32_16x16x32_bf16 v[30:33], v[156:159], v[212:215], v[30:33]
	v_mfma_f32_16x16x32_bf16 v[26:29], v[168:171], v[212:215], v[26:29]
	v_mfma_f32_16x16x32_bf16 v[14:17], v[156:159], v[220:223], v[14:17]
	v_mfma_f32_16x16x32_bf16 v[10:13], v[168:171], v[220:223], v[10:13]
	v_mfma_f32_16x16x32_bf16 v[62:65], v[164:167], v[200:203], v[62:65]
	v_mfma_f32_16x16x32_bf16 v[58:61], v[172:175], v[200:203], v[58:61]
	v_mfma_f32_16x16x32_bf16 v[46:49], v[164:167], v[208:211], v[46:49]
	v_mfma_f32_16x16x32_bf16 v[42:45], v[172:175], v[208:211], v[42:45]
	v_mfma_f32_16x16x32_bf16 v[30:33], v[164:167], v[216:219], v[30:33]
	v_mfma_f32_16x16x32_bf16 v[26:29], v[172:175], v[216:219], v[26:29]
	v_mfma_f32_16x16x32_bf16 v[14:17], v[164:167], v[224:227], v[14:17]
	v_mfma_f32_16x16x32_bf16 v[10:13], v[172:175], v[224:227], v[10:13]
	v_mfma_f32_16x16x32_bf16 v[54:57], v[176:179], v[192:195], v[54:57]
	v_mfma_f32_16x16x32_bf16 v[50:53], v[184:187], v[192:195], v[50:53]
	v_mfma_f32_16x16x32_bf16 v[38:41], v[176:179], v[204:207], v[38:41]
	v_mfma_f32_16x16x32_bf16 v[34:37], v[184:187], v[204:207], v[34:37]
	v_mfma_f32_16x16x32_bf16 v[22:25], v[176:179], v[212:215], v[22:25]
	v_mfma_f32_16x16x32_bf16 v[18:21], v[184:187], v[212:215], v[18:21]
	v_mfma_f32_16x16x32_bf16 v[6:9], v[176:179], v[220:223], v[6:9]
	v_mfma_f32_16x16x32_bf16 v[2:5], v[184:187], v[220:223], v[2:5]
	v_mfma_f32_16x16x32_bf16 v[54:57], v[180:183], v[200:203], v[54:57]
	v_mfma_f32_16x16x32_bf16 v[50:53], v[188:191], v[200:203], v[50:53]
	v_mfma_f32_16x16x32_bf16 v[38:41], v[180:183], v[208:211], v[38:41]
	v_mfma_f32_16x16x32_bf16 v[34:37], v[188:191], v[208:211], v[34:37]
	v_mfma_f32_16x16x32_bf16 v[22:25], v[180:183], v[216:219], v[22:25]
	v_mfma_f32_16x16x32_bf16 v[18:21], v[188:191], v[216:219], v[18:21]
	v_mfma_f32_16x16x32_bf16 v[6:9], v[180:183], v[224:227], v[6:9]
	v_mfma_f32_16x16x32_bf16 v[2:5], v[188:191], v[224:227], v[2:5]
	s_barrier
	s_add_i32 s71, s71, 2
	s_add_u32 s24, s24, 0x100
	s_addc_u32 s25, s25, 0
	s_cmp_gt_u32 s71, 33
	s_cbranch_scc1 .LBB0_1940
